# sc1 write-through on dwordx4 epilogue stores (all GEMM epilogues except gates/final, conv, weight conversion)
# speedup vs baseline: 1.0041x; 1.0041x over previous
; #define LAS __attribute__((address_space(3)))
; __device__ __forceinline__ unsigned pk_bf16(float lo, float hi) { f32x2 v = {lo, hi}; return __builtin_bit_cast(unsigned, __builtin_convertvector(v, bf16v2)); }
; __device__ __forceinline__ void transpose_item(const float* W, int K, int N, bf16_t* WT, int mode, int rowoff, const float* g, LAS float* scr, int item, int lane) {
;     ...
;     for (int i = 0; i < 32; ++i) scr[(2 * i + (lane >> 5)) * 33 + (lane & 31)] = tv[i];
;     asm volatile("s_waitcnt lgkmcnt(0)" ::: "memory");
;     const int c = lane & 7;
; #pragma unroll
;     for (int j = 0; j < 4; ++j) { const int n = (lane >> 3) + 8 * j; const LAS float* s = scr + (8 * c) * 33 + n;
;         u32x4 o; o.x = pk_bf16(s[0 * 33], s[1 * 33]); o.y = pk_bf16(s[2 * 33], s[3 * 33]); o.z = pk_bf16(s[4 * 33], s[5 * 33]); o.w = pk_bf16(s[6 * 33], s[7 * 33]);
;         *(u32x4*)(WT + (size_t)(drow0 + n) * K + k0 + 8 * c) = o; }
.LBB0_11:
	s_waitcnt vmcnt(30)
	ds_write2_b32 v48, v14, v15 offset1:66
	s_waitcnt vmcnt(28)
	ds_write2_b32 v48, v18, v19 offset0:132 offset1:198
	v_add_u32_e32 v14, 0x400, v48
	s_waitcnt vmcnt(26)
	ds_write2_b32 v14, v16, v17 offset0:8 offset1:74
	s_waitcnt vmcnt(24)
	ds_write2_b32 v14, v20, v21 offset0:140 offset1:206
	v_add_u32_e32 v14, 0x800, v48
	s_waitcnt vmcnt(22)
	ds_write2_b32 v14, v22, v23 offset0:16 offset1:82
	s_waitcnt vmcnt(20)
	ds_write2_b32 v14, v26, v27 offset0:148 offset1:214
	v_add_u32_e32 v14, 0xc00, v48
	s_waitcnt vmcnt(18)
	ds_write2_b32 v14, v24, v25 offset0:24 offset1:90
	s_waitcnt vmcnt(16)
	ds_write2_b32 v14, v28, v29 offset0:156 offset1:222
	v_add_u32_e32 v14, 0x1000, v48
	s_waitcnt vmcnt(14)
	ds_write2_b32 v14, v30, v31 offset0:32 offset1:98
	s_waitcnt vmcnt(12)
	ds_write2_b32 v14, v34, v35 offset0:164 offset1:230
	v_add_u32_e32 v14, 0x1400, v48
	s_waitcnt vmcnt(10)
	ds_write2_b32 v14, v32, v33 offset0:40 offset1:106
	s_waitcnt vmcnt(8)
	ds_write2_b32 v14, v36, v37 offset0:172 offset1:238
	v_add_u32_e32 v14, 0x1800, v48
	s_waitcnt vmcnt(6)
	ds_write2_b32 v14, v38, v39 offset0:48 offset1:114
	s_waitcnt vmcnt(4)
	ds_write2_b32 v14, v44, v45 offset0:180 offset1:246
	v_add_u32_e32 v14, 0x1c00, v48
	s_waitcnt vmcnt(2)
	ds_write2_b32 v14, v42, v43 offset0:56 offset1:122
	s_waitcnt vmcnt(0)
	ds_write2_b32 v14, v40, v41 offset0:188 offset1:254
	s_waitcnt lgkmcnt(0)
	s_sub_i32 s6, 0, s6
	ds_read2_b32 v[18:19], v50 offset0:33 offset1:41
	ds_read2_b32 v[20:21], v50 offset1:8
	ds_read2_b32 v[22:23], v50 offset0:66 offset1:74
	ds_read2_b32 v[24:25], v50 offset0:99 offset1:107
	ds_read2_b32 v[26:27], v50 offset0:132 offset1:140
	ds_read2_b32 v[28:29], v50 offset0:165 offset1:173
	ds_read2_b32 v[30:31], v50 offset0:198 offset1:206
	ds_read2_b32 v[32:33], v50 offset0:231 offset1:239
	s_add_i32 s6, s6, s34
	v_add_u32_e32 v36, s6, v49
	s_ashr_i32 s11, s10, 31
	v_ashrrev_i32_e32 v37, 31, v36
	v_lshl_add_u64 v[34:35], s[10:11], 1, v[12:13]
	v_lshlrev_b64 v[38:39], 11, v[36:37]
	s_waitcnt lgkmcnt(6)
	v_cvt_pk_bf16_f32 v14, v20, v18
	s_waitcnt lgkmcnt(4)
	v_cvt_pk_bf16_f32 v15, v22, v24
	s_waitcnt lgkmcnt(2)
	v_cvt_pk_bf16_f32 v16, v26, v28
	s_waitcnt lgkmcnt(0)
	v_cvt_pk_bf16_f32 v17, v30, v32
	v_lshl_add_u64 v[38:39], v[34:35], 0, v[38:39]
	v_add_u32_e32 v18, 8, v36
	global_store_dwordx4 v[38:39], v[14:17], off sc1
	s_nop 1
	v_cvt_pk_bf16_f32 v14, v21, v19
	v_ashrrev_i32_e32 v19, 31, v18
	v_cvt_pk_bf16_f32 v15, v23, v25
	v_cvt_pk_bf16_f32 v16, v27, v29
	v_cvt_pk_bf16_f32 v17, v31, v33
	v_lshlrev_b64 v[18:19], 11, v[18:19]
	ds_read2_b32 v[20:21], v50 offset0:49 offset1:57
	ds_read2_b32 v[22:23], v50 offset0:16 offset1:24
	ds_read2_b32 v[24:25], v50 offset0:82 offset1:90
	ds_read2_b32 v[26:27], v50 offset0:115 offset1:123
	ds_read2_b32 v[28:29], v50 offset0:148 offset1:156
	ds_read2_b32 v[30:31], v50 offset0:181 offset1:189
	ds_read2_b32 v[32:33], v50 offset0:214 offset1:222
	ds_read2_b32 v[38:39], v50 offset0:247 offset1:255
	v_lshl_add_u64 v[18:19], v[34:35], 0, v[18:19]
	global_store_dwordx4 v[18:19], v[14:17], off sc1
	v_add_u32_e32 v18, 16, v36
	v_ashrrev_i32_e32 v19, 31, v18
	v_lshlrev_b64 v[18:19], 11, v[18:19]
	s_waitcnt lgkmcnt(6)
	v_cvt_pk_bf16_f32 v14, v22, v20
	s_waitcnt lgkmcnt(4)
	v_cvt_pk_bf16_f32 v15, v24, v26
	s_waitcnt lgkmcnt(2)
	v_cvt_pk_bf16_f32 v16, v28, v30
	s_waitcnt lgkmcnt(0)
	v_cvt_pk_bf16_f32 v17, v32, v38
	v_lshl_add_u64 v[18:19], v[34:35], 0, v[18:19]
	global_store_dwordx4 v[18:19], v[14:17], off sc1
	v_add_u32_e32 v18, 24, v36
	v_ashrrev_i32_e32 v19, 31, v18
	v_lshlrev_b64 v[18:19], 11, v[18:19]
	v_cvt_pk_bf16_f32 v14, v23, v21
	v_cvt_pk_bf16_f32 v15, v25, v27
	v_cvt_pk_bf16_f32 v16, v29, v31
	v_cvt_pk_bf16_f32 v17, v33, v39
	v_lshl_add_u64 v[18:19], v[34:35], 0, v[18:19]
	global_store_dwordx4 v[18:19], v[14:17], off sc1
	s_waitcnt lgkmcnt(0)

; #define LAS __attribute__((address_space(3)))
; __device__ __forceinline__ unsigned pk_bf16(float lo, float hi) { f32x2 v = {lo, hi}; return __builtin_bit_cast(unsigned, __builtin_convertvector(v, bf16v2)); }
; __device__ __forceinline__ void transpose_item(const float* W, int K, int N, bf16_t* WT, int mode, int rowoff, const float* g, LAS float* scr, int item, int lane) {
;     ...
;     const float* wp = W + (size_t)(k0 + (lane >> 5)) * N + n0 + (lane & 31);
; #pragma unroll
;     for (int i = 0; i < 32; ++i) tv[i] = __builtin_nontemporal_load(wp + (size_t)(2 * i) * N);
;     ...
;     for (int i = 0; i < 32; ++i) scr[(2 * i + (lane >> 5)) * 33 + (lane & 31)] = tv[i];
;     asm volatile("s_waitcnt lgkmcnt(0)" ::: "memory");
;     const int c = lane & 7;
; #pragma unroll
;     for (int j = 0; j < 4; ++j) { const int n = (lane >> 3) + 8 * j; const LAS float* s = scr + (8 * c) * 33 + n;
;         u32x4 o; o.x = pk_bf16(s[0 * 33], s[1 * 33]); o.y = pk_bf16(s[2 * 33], s[3 * 33]); o.z = pk_bf16(s[4 * 33], s[5 * 33]); o.w = pk_bf16(s[6 * 33], s[7 * 33]);
;         *(u32x4*)(WT + (size_t)(drow0 + n) * K + k0 + 8 * c) = o; }
.LBB0_18:
	s_waitcnt vmcnt(30)
	ds_write2_b32 v48, v14, v15 offset1:66
	s_waitcnt vmcnt(28)
	ds_write2_b32 v48, v18, v19 offset0:132 offset1:198
	v_add_u32_e32 v14, 0x400, v48
	s_waitcnt vmcnt(26)
	ds_write2_b32 v14, v16, v17 offset0:8 offset1:74
	s_waitcnt vmcnt(24)
	ds_write2_b32 v14, v20, v21 offset0:140 offset1:206
	v_add_u32_e32 v14, 0x800, v48
	s_waitcnt vmcnt(22)
	ds_write2_b32 v14, v22, v23 offset0:16 offset1:82
	s_waitcnt vmcnt(20)
	ds_write2_b32 v14, v26, v27 offset0:148 offset1:214
	v_add_u32_e32 v14, 0xc00, v48
	s_waitcnt vmcnt(18)
	ds_write2_b32 v14, v24, v25 offset0:24 offset1:90
	s_waitcnt vmcnt(16)
	ds_write2_b32 v14, v28, v29 offset0:156 offset1:222
	v_add_u32_e32 v14, 0x1000, v48
	s_waitcnt vmcnt(14)
	ds_write2_b32 v14, v30, v31 offset0:32 offset1:98
	s_waitcnt vmcnt(12)
	ds_write2_b32 v14, v34, v35 offset0:164 offset1:230
	v_add_u32_e32 v14, 0x1400, v48
	s_waitcnt vmcnt(10)
	ds_write2_b32 v14, v32, v33 offset0:40 offset1:106
	s_waitcnt vmcnt(8)
	ds_write2_b32 v14, v36, v37 offset0:172 offset1:238
	v_add_u32_e32 v14, 0x1800, v48
	s_waitcnt vmcnt(6)
	ds_write2_b32 v14, v38, v39 offset0:48 offset1:114
	s_waitcnt vmcnt(4)
	ds_write2_b32 v14, v44, v45 offset0:180 offset1:246
	v_add_u32_e32 v14, 0x1c00, v48
	s_cmpk_gt_u32 s6, 0x57f
	s_waitcnt vmcnt(2)
	ds_write2_b32 v14, v42, v43 offset0:56 offset1:122
	s_waitcnt vmcnt(0)
	ds_write2_b32 v14, v40, v41 offset0:188 offset1:254
	s_cselect_b32 s6, 0x80, 0
	s_lshl_b32 s11, s11, 6
	s_and_b32 s30, s30, 0x60
	s_waitcnt lgkmcnt(0)
	s_and_b32 s11, s11, 0xffffff00
	s_or_b32 s6, s30, s6
	ds_read2_b32 v[18:19], v50 offset0:33 offset1:41
	ds_read2_b32 v[20:21], v50 offset1:8
	ds_read2_b32 v[22:23], v50 offset0:66 offset1:74
	ds_read2_b32 v[24:25], v50 offset0:99 offset1:107
	ds_read2_b32 v[26:27], v50 offset0:132 offset1:140
	ds_read2_b32 v[28:29], v50 offset0:165 offset1:173
	ds_read2_b32 v[30:31], v50 offset0:198 offset1:206
	ds_read2_b32 v[32:33], v50 offset0:231 offset1:239
	s_or_b32 s6, s6, s11
	v_add_u32_e32 v36, s6, v49
	s_ashr_i32 s11, s10, 31
	v_ashrrev_i32_e32 v37, 31, v36
	v_lshl_add_u64 v[34:35], s[10:11], 1, v[6:7]
	v_lshlrev_b64 v[36:37], 11, v[36:37]
	s_waitcnt lgkmcnt(6)
	v_cvt_pk_bf16_f32 v14, v20, v18
	s_waitcnt lgkmcnt(4)
	v_cvt_pk_bf16_f32 v15, v22, v24
	s_waitcnt lgkmcnt(2)
	v_cvt_pk_bf16_f32 v16, v26, v28
	s_waitcnt lgkmcnt(0)
	v_cvt_pk_bf16_f32 v17, v30, v32
	v_lshl_add_u64 v[36:37], v[34:35], 0, v[36:37]
	v_add_u32_e32 v18, s6, v51
	global_store_dwordx4 v[36:37], v[14:17], off sc1
	s_mov_b64 s[10:11], 0
	s_nop 0
	v_cvt_pk_bf16_f32 v14, v21, v19
	v_ashrrev_i32_e32 v19, 31, v18
	v_cvt_pk_bf16_f32 v15, v23, v25
	v_cvt_pk_bf16_f32 v16, v27, v29
	v_cvt_pk_bf16_f32 v17, v31, v33
	v_lshlrev_b64 v[18:19], 11, v[18:19]
	ds_read2_b32 v[20:21], v50 offset0:49 offset1:57
	ds_read2_b32 v[22:23], v50 offset0:16 offset1:24
	ds_read2_b32 v[24:25], v50 offset0:82 offset1:90
	ds_read2_b32 v[26:27], v50 offset0:115 offset1:123
	ds_read2_b32 v[28:29], v50 offset0:148 offset1:156
	ds_read2_b32 v[30:31], v50 offset0:181 offset1:189
	ds_read2_b32 v[32:33], v50 offset0:214 offset1:222
	ds_read2_b32 v[36:37], v50 offset0:247 offset1:255
	v_lshl_add_u64 v[18:19], v[34:35], 0, v[18:19]
	global_store_dwordx4 v[18:19], v[14:17], off sc1
	v_add_u32_e32 v18, s6, v52
	v_ashrrev_i32_e32 v19, 31, v18
	v_lshlrev_b64 v[18:19], 11, v[18:19]
	s_waitcnt lgkmcnt(6)
	v_cvt_pk_bf16_f32 v14, v22, v20
	s_waitcnt lgkmcnt(4)
	v_cvt_pk_bf16_f32 v15, v24, v26
	s_waitcnt lgkmcnt(2)
	v_cvt_pk_bf16_f32 v16, v28, v30
	s_waitcnt lgkmcnt(0)
	v_cvt_pk_bf16_f32 v17, v32, v36
	v_lshl_add_u64 v[18:19], v[34:35], 0, v[18:19]
	global_store_dwordx4 v[18:19], v[14:17], off sc1
	v_add_u32_e32 v18, s6, v53
	v_ashrrev_i32_e32 v19, 31, v18
	v_lshlrev_b64 v[18:19], 11, v[18:19]
	v_cvt_pk_bf16_f32 v14, v23, v21
	v_cvt_pk_bf16_f32 v15, v25, v27
	v_cvt_pk_bf16_f32 v16, v29, v31
	v_cvt_pk_bf16_f32 v17, v33, v37
	v_lshl_add_u64 v[18:19], v[34:35], 0, v[18:19]
	global_store_dwordx4 v[18:19], v[14:17], off sc1
	s_waitcnt lgkmcnt(0)
.LBB0_19:
	s_and_b64 vcc, exec, s[10:11]
	s_cbranch_vccz .LBB0_21
	s_and_b32 s11, s36, 0x1ffc0
	v_add_u32_e32 v14, s11, v3
	v_ashrrev_i32_e32 v15, 31, v14
	v_readlane_b32 s60, v250, 2
	s_and_b32 s10, s34, 0x3e0
	v_lshlrev_b64 v[14:15], 12, v[14:15]
	v_readlane_b32 s66, v250, 8
	v_readlane_b32 s67, v250, 9
	s_lshl_b32 s6, s10, 2
	v_readlane_b32 s61, v250, 3
	v_lshl_add_u64 v[14:15], s[66:67], 0, v[14:15]
	v_lshl_add_u64 v[14:15], v[14:15], 0, s[6:7]
	v_lshl_add_u64 v[14:15], v[14:15], 0, v[4:5]
	v_add_co_u32_e32 v16, vcc, 0x2000, v14
	s_lshl_b32 s6, s11, 1
	s_nop 0
	v_addc_co_u32_e32 v17, vcc, 0, v15, vcc
	v_add_co_u32_e32 v18, vcc, 0x4000, v14
	v_readlane_b32 s62, v250, 4
	s_nop 0
	v_addc_co_u32_e32 v19, vcc, 0, v15, vcc
	v_add_co_u32_e32 v20, vcc, 0x6000, v14
	v_readlane_b32 s63, v250, 5
	s_nop 0
	v_addc_co_u32_e32 v21, vcc, 0, v15, vcc
	v_add_co_u32_e32 v22, vcc, 0x8000, v14
	v_readlane_b32 s64, v250, 6
	s_nop 0
	v_addc_co_u32_e32 v23, vcc, 0, v15, vcc
	v_add_co_u32_e32 v24, vcc, 0xa000, v14
	v_readlane_b32 s65, v250, 7
	s_nop 0
	v_addc_co_u32_e32 v25, vcc, 0, v15, vcc
	v_add_co_u32_e32 v26, vcc, 0xc000, v14
	v_readlane_b32 s68, v250, 10
	s_nop 0
	v_addc_co_u32_e32 v27, vcc, 0, v15, vcc
	v_add_co_u32_e32 v28, vcc, 0xe000, v14
	v_readlane_b32 s69, v250, 11
	s_nop 0
	v_addc_co_u32_e32 v29, vcc, 0, v15, vcc
	global_load_dword v32, v[14:15], off nt
	global_load_dword v33, v[16:17], off nt
	global_load_dword v34, v[18:19], off nt
	global_load_dword v35, v[20:21], off nt
	global_load_dword v36, v[22:23], off nt
	global_load_dword v37, v[24:25], off nt
	global_load_dword v38, v[26:27], off nt
; __device__ __forceinline__ void transpose_item(const float* W, int K, int N, bf16_t* WT, int mode, int rowoff, const float* g, LAS float* scr, int item, int lane) {
;     ...
;     const float* wp = W + (size_t)(k0 + (lane >> 5)) * N + n0 + (lane & 31);
; #pragma unroll
;     for (int i = 0; i < 32; ++i) tv[i] = __builtin_nontemporal_load(wp + (size_t)(2 * i) * N);
;     if (g) {
; #pragma unroll
;         for (int i = 0; i < 32; ++i) tv[i] *= g[k0 + 2 * i + (lane >> 5)]; }
; #pragma unroll
;     for (int i = 0; i < 32; ++i) scr[(2 * i + (lane >> 5)) * 33 + (lane & 31)] = tv[i];
	global_load_dword v39, v[28:29], off nt
	v_add_co_u32_e32 v16, vcc, s46, v14
	v_readlane_b32 s70, v250, 12
	s_nop 0
	v_addc_co_u32_e32 v17, vcc, 0, v15, vcc
	v_add_co_u32_e32 v18, vcc, 0x12000, v14
	v_readlane_b32 s71, v250, 13
	s_nop 0
	v_addc_co_u32_e32 v19, vcc, 0, v15, vcc
	v_add_co_u32_e32 v20, vcc, 0x14000, v14
	v_readlane_b32 s72, v250, 14
	s_nop 0
	v_addc_co_u32_e32 v21, vcc, 0, v15, vcc
	v_add_co_u32_e32 v22, vcc, s47, v14
	v_readlane_b32 s73, v250, 15
	s_nop 0
	v_addc_co_u32_e32 v23, vcc, 0, v15, vcc
	v_add_co_u32_e32 v24, vcc, 0x18000, v14
	v_readlane_b32 s74, v250, 16
	s_nop 0
	v_addc_co_u32_e32 v25, vcc, 0, v15, vcc
	v_add_co_u32_e32 v26, vcc, 0x1a000, v14
	v_readlane_b32 s75, v250, 17
	s_nop 0
	v_addc_co_u32_e32 v27, vcc, 0, v15, vcc
	v_add_co_u32_e32 v28, vcc, 0x1c000, v14
	s_nop 1
	v_addc_co_u32_e32 v29, vcc, 0, v15, vcc
	v_add_co_u32_e32 v30, vcc, 0x1e000, v14
	s_nop 1
	v_addc_co_u32_e32 v31, vcc, 0, v15, vcc
	global_load_dword v40, v[16:17], off nt
	global_load_dword v41, v[18:19], off nt
	global_load_dword v42, v[20:21], off nt
	global_load_dword v43, v[22:23], off nt
	global_load_dword v44, v[24:25], off nt
	global_load_dword v45, v[26:27], off nt
	global_load_dword v46, v[28:29], off nt
	global_load_dword v47, v[30:31], off nt
	v_add_co_u32_e32 v16, vcc, 0x20000, v14
	s_nop 1
	v_addc_co_u32_e32 v17, vcc, 0, v15, vcc
	v_add_co_u32_e32 v18, vcc, 0x22000, v14
	s_nop 1
	v_addc_co_u32_e32 v19, vcc, 0, v15, vcc
	v_add_co_u32_e32 v20, vcc, 0x24000, v14
	s_nop 1
	v_addc_co_u32_e32 v21, vcc, 0, v15, vcc
	v_add_co_u32_e32 v22, vcc, s48, v14
	s_nop 1
	v_addc_co_u32_e32 v23, vcc, 0, v15, vcc
	v_add_co_u32_e32 v24, vcc, 0x28000, v14
	s_nop 1
	v_addc_co_u32_e32 v25, vcc, 0, v15, vcc
	v_add_co_u32_e32 v26, vcc, 0x2a000, v14
	s_nop 1
	v_addc_co_u32_e32 v27, vcc, 0, v15, vcc
	v_add_co_u32_e32 v28, vcc, s49, v14
	s_nop 1
	v_addc_co_u32_e32 v29, vcc, 0, v15, vcc
	v_add_co_u32_e32 v30, vcc, 0x2e000, v14
	s_nop 1
	v_addc_co_u32_e32 v31, vcc, 0, v15, vcc
	global_load_dword v54, v[16:17], off nt
	global_load_dword v55, v[18:19], off nt
	global_load_dword v56, v[20:21], off nt
	global_load_dword v57, v[22:23], off nt
	global_load_dword v58, v[24:25], off nt
	global_load_dword v59, v[26:27], off nt
	global_load_dword v60, v[28:29], off nt
	s_nop 0
	global_load_dword v30, v[30:31], off nt
	v_add_co_u32_e32 v16, vcc, 0x30000, v14
	s_nop 1
	v_addc_co_u32_e32 v17, vcc, 0, v15, vcc
	v_add_co_u32_e32 v18, vcc, 0x32000, v14
	s_nop 1
	v_addc_co_u32_e32 v19, vcc, 0, v15, vcc
	v_add_co_u32_e32 v20, vcc, 0x34000, v14
	s_nop 1
	v_addc_co_u32_e32 v21, vcc, 0, v15, vcc
	v_add_co_u32_e32 v22, vcc, 0x36000, v14
	s_nop 1
	v_addc_co_u32_e32 v23, vcc, 0, v15, vcc
	v_add_co_u32_e32 v24, vcc, 0x38000, v14
	s_nop 1
	v_addc_co_u32_e32 v25, vcc, 0, v15, vcc
	v_add_co_u32_e32 v26, vcc, 0x3a000, v14
	s_nop 1
	v_addc_co_u32_e32 v27, vcc, 0, v15, vcc
	v_add_co_u32_e32 v28, vcc, s54, v14
	s_nop 1
	v_addc_co_u32_e32 v29, vcc, 0, v15, vcc
	v_add_co_u32_e32 v14, vcc, 0x3e000, v14
	s_nop 1
	v_addc_co_u32_e32 v15, vcc, 0, v15, vcc
	global_load_dword v16, v[16:17], off nt
	s_nop 0
	global_load_dword v17, v[18:19], off nt
	s_nop 0
	global_load_dword v18, v[20:21], off nt
	global_load_dword v19, v[22:23], off nt
	s_nop 0
	global_load_dword v20, v[24:25], off nt
	global_load_dword v21, v[26:27], off nt
	global_load_dword v22, v[28:29], off nt
	s_nop 0
	global_load_dword v14, v[14:15], off nt
	v_add_u32_e32 v15, 0x400, v48
	s_waitcnt vmcnt(30)
	ds_write2_b32 v48, v32, v33 offset1:66
	s_waitcnt vmcnt(28)
	ds_write2_b32 v48, v34, v35 offset0:132 offset1:198
	s_waitcnt vmcnt(26)
; #define LAS __attribute__((address_space(3)))
; __device__ __forceinline__ unsigned pk_bf16(float lo, float hi) { f32x2 v = {lo, hi}; return __builtin_bit_cast(unsigned, __builtin_convertvector(v, bf16v2)); }
; __device__ __forceinline__ void transpose_item(const float* W, int K, int N, bf16_t* WT, int mode, int rowoff, const float* g, LAS float* scr, int item, int lane) {
;     ...
;     for (int i = 0; i < 32; ++i) scr[(2 * i + (lane >> 5)) * 33 + (lane & 31)] = tv[i];
;     asm volatile("s_waitcnt lgkmcnt(0)" ::: "memory");
;     const int c = lane & 7;
; #pragma unroll
;     for (int j = 0; j < 4; ++j) { const int n = (lane >> 3) + 8 * j; const LAS float* s = scr + (8 * c) * 33 + n;
;         u32x4 o; o.x = pk_bf16(s[0 * 33], s[1 * 33]); o.y = pk_bf16(s[2 * 33], s[3 * 33]); o.z = pk_bf16(s[4 * 33], s[5 * 33]); o.w = pk_bf16(s[6 * 33], s[7 * 33]);
;         *(u32x4*)(WT + (size_t)(drow0 + n) * K + k0 + 8 * c) = o; }
	ds_write2_b32 v15, v36, v37 offset0:8 offset1:74
	s_waitcnt vmcnt(24)
	ds_write2_b32 v15, v38, v39 offset0:140 offset1:206
	v_add_u32_e32 v15, 0x800, v48
	s_waitcnt vmcnt(22)
	ds_write2_b32 v15, v40, v41 offset0:16 offset1:82
	s_waitcnt vmcnt(20)
	ds_write2_b32 v15, v42, v43 offset0:148 offset1:214
	v_add_u32_e32 v15, 0xc00, v48
	s_waitcnt vmcnt(18)
	ds_write2_b32 v15, v44, v45 offset0:24 offset1:90
	s_waitcnt vmcnt(16)
	ds_write2_b32 v15, v46, v47 offset0:156 offset1:222
	v_add_u32_e32 v15, 0x1000, v48
	s_waitcnt vmcnt(14)
	ds_write2_b32 v15, v54, v55 offset0:32 offset1:98
	s_waitcnt vmcnt(12)
	ds_write2_b32 v15, v56, v57 offset0:164 offset1:230
	v_add_u32_e32 v15, 0x1400, v48
	s_waitcnt vmcnt(10)
	ds_write2_b32 v15, v58, v59 offset0:40 offset1:106
	s_waitcnt vmcnt(8)
	ds_write2_b32 v15, v60, v30 offset0:172 offset1:238
	v_add_u32_e32 v15, 0x1800, v48
	s_waitcnt vmcnt(6)
	ds_write2_b32 v15, v16, v17 offset0:48 offset1:114
	s_waitcnt vmcnt(4)
	ds_write2_b32 v15, v18, v19 offset0:180 offset1:246
	v_add_u32_e32 v15, 0x1c00, v48
	s_waitcnt vmcnt(2)
	ds_write2_b32 v15, v20, v21 offset0:56 offset1:122
	s_waitcnt vmcnt(0)
	ds_write2_b32 v15, v22, v14 offset0:188 offset1:254
	s_waitcnt lgkmcnt(0)
	ds_read2_b32 v[18:19], v50 offset0:33 offset1:41
	ds_read2_b32 v[20:21], v50 offset1:8
	ds_read2_b32 v[22:23], v50 offset0:66 offset1:74
	ds_read2_b32 v[24:25], v50 offset0:99 offset1:107
	ds_read2_b32 v[26:27], v50 offset0:132 offset1:140
	ds_read2_b32 v[28:29], v50 offset0:165 offset1:173
	ds_read2_b32 v[30:31], v50 offset0:198 offset1:206
	ds_read2_b32 v[32:33], v50 offset0:231 offset1:239
	v_add_u32_e32 v36, s10, v49
	v_ashrrev_i32_e32 v37, 31, v36
	v_lshl_add_u64 v[34:35], v[8:9], 0, s[6:7]
	v_lshlrev_b64 v[36:37], 11, v[36:37]
	s_waitcnt lgkmcnt(6)
	v_cvt_pk_bf16_f32 v14, v20, v18
	s_waitcnt lgkmcnt(4)
	v_cvt_pk_bf16_f32 v15, v22, v24
	s_waitcnt lgkmcnt(2)
	v_cvt_pk_bf16_f32 v16, v26, v28
	s_waitcnt lgkmcnt(0)
	v_cvt_pk_bf16_f32 v17, v30, v32
	v_lshl_add_u64 v[36:37], v[34:35], 0, v[36:37]
	v_add_u32_e32 v18, s10, v51
	global_store_dwordx4 v[36:37], v[14:17], off sc1
	s_nop 1
	v_cvt_pk_bf16_f32 v14, v21, v19
	v_ashrrev_i32_e32 v19, 31, v18
	v_cvt_pk_bf16_f32 v15, v23, v25
	v_cvt_pk_bf16_f32 v16, v27, v29
	v_cvt_pk_bf16_f32 v17, v31, v33
	v_lshlrev_b64 v[18:19], 11, v[18:19]
	ds_read2_b32 v[20:21], v50 offset0:49 offset1:57
	ds_read2_b32 v[22:23], v50 offset0:16 offset1:24
	ds_read2_b32 v[24:25], v50 offset0:82 offset1:90
	ds_read2_b32 v[26:27], v50 offset0:115 offset1:123
	ds_read2_b32 v[28:29], v50 offset0:148 offset1:156
	ds_read2_b32 v[30:31], v50 offset0:181 offset1:189
	ds_read2_b32 v[32:33], v50 offset0:214 offset1:222
	ds_read2_b32 v[36:37], v50 offset0:247 offset1:255
	v_lshl_add_u64 v[18:19], v[34:35], 0, v[18:19]
	global_store_dwordx4 v[18:19], v[14:17], off sc1
	v_add_u32_e32 v18, s10, v52
	v_ashrrev_i32_e32 v19, 31, v18
	v_lshlrev_b64 v[18:19], 11, v[18:19]
	s_waitcnt lgkmcnt(6)
	v_cvt_pk_bf16_f32 v14, v22, v20
	s_waitcnt lgkmcnt(4)
	v_cvt_pk_bf16_f32 v15, v24, v26
	s_waitcnt lgkmcnt(2)
	v_cvt_pk_bf16_f32 v16, v28, v30
	s_waitcnt lgkmcnt(0)
	v_cvt_pk_bf16_f32 v17, v32, v36
	v_lshl_add_u64 v[18:19], v[34:35], 0, v[18:19]
	global_store_dwordx4 v[18:19], v[14:17], off sc1
	v_add_u32_e32 v18, s10, v53
	v_ashrrev_i32_e32 v19, 31, v18
	v_lshlrev_b64 v[18:19], 11, v[18:19]
	v_cvt_pk_bf16_f32 v14, v23, v21
	v_cvt_pk_bf16_f32 v15, v25, v27
	v_cvt_pk_bf16_f32 v16, v29, v31
	v_cvt_pk_bf16_f32 v17, v33, v37
	v_lshl_add_u64 v[18:19], v[34:35], 0, v[18:19]
	global_store_dwordx4 v[18:19], v[14:17], off sc1
	s_waitcnt lgkmcnt(0)

; __device__ __forceinline__ void transpose_item(const float* W, int K, int N, bf16_t* WT, int mode, int rowoff, const float* g, LAS float* scr, int item, int lane) {
;     const int nblk = N / 32, kb = item / nblk, nb = item % nblk, k0 = 64 * kb, n0 = 32 * nb;
;     const int drow0 = rowoff + (mode ? 256 * (n0 >> 7) + (n0 & 127) : n0);
;     float tv[32];
;     const float* wp = W + (size_t)(k0 + (lane >> 5)) * N + n0 + (lane & 31);
; #pragma unroll
;     for (int i = 0; i < 32; ++i) tv[i] = __builtin_nontemporal_load(wp + (size_t)(2 * i) * N);
; template <int SET>
; __device__ __forceinline__ void convert_weights(const Params& p, LAS unsigned char* lds, int gw, int ngw, int wave, int lane) {
;     ...
;             if (r < I_G) { const int mtx = r >> 5, blk = mtx & 3, isI = mtx >> 2;
;                 transpose_item((isI ? p.in[8] : p.in[6]) + blk * 65536, 256, 256, (bf16_t*)(ws + WS_WG), 1, 512 * blk + 128 * isI, nullptr, scr, r & 31, lane); continue; } r -= I_G;
.LBB0_22:
	s_andn2_b64 vcc, exec, s[10:11]
	s_cbranch_vccnz .LBB0_24
	s_add_i32 s6, s76, 0xfffffc00
	s_bfe_u32 s30, s76, 0x20005
	s_and_b32 s31, s6, 0xffffff80
	v_readlane_b32 s60, v250, 2
	s_cmpk_lt_u32 s6, 0x80
	v_readlane_b32 s61, v250, 3
	s_cselect_b32 s6, s25, s61
	s_cselect_b32 s10, s24, s60
	s_lshl_b32 s11, s30, 18
	s_add_u32 s10, s10, s11
	s_addc_u32 s11, s6, 0
	s_and_b32 s77, s38, 0xc0
	v_add_u32_e32 v14, s77, v3
	v_ashrrev_i32_e32 v15, 31, v14
	s_and_b32 s6, s34, 0xe0
	v_lshlrev_b64 v[14:15], 10, v[14:15]
	v_lshl_add_u64 v[14:15], s[10:11], 0, v[14:15]
	s_lshl_b32 s6, s6, 2
	v_lshl_add_u64 v[14:15], v[14:15], 0, s[6:7]
	v_lshl_add_u64 v[14:15], v[14:15], 0, v[4:5]
	s_movk_i32 s6, 0x1000
	v_add_co_u32_e32 v16, vcc, s6, v14
	s_movk_i32 s6, 0x2000
	s_nop 0
	v_addc_co_u32_e32 v17, vcc, 0, v15, vcc
	v_add_co_u32_e32 v18, vcc, s6, v14
	s_movk_i32 s6, 0x6000
	s_nop 0
	v_addc_co_u32_e32 v19, vcc, 0, v15, vcc
	v_add_co_u32_e32 v20, vcc, s80, v14
	s_and_b32 s10, s40, 0x100
	s_nop 0
	v_addc_co_u32_e32 v21, vcc, 0, v15, vcc
	v_add_co_u32_e32 v22, vcc, s57, v14
	s_and_b32 s11, s34, 0x60
	s_nop 0
	v_addc_co_u32_e32 v23, vcc, 0, v15, vcc
	global_load_dword v34, v[18:19], off offset:-4096 nt
	global_load_dword v35, v[18:19], off nt
	global_load_dword v36, v[18:19], off offset:2048 nt
	global_load_dword v37, v[22:23], off offset:-4096 nt
	global_load_dword v38, v[22:23], off nt
	v_add_co_u32_e32 v18, vcc, s44, v14
	s_or_b32 s10, s10, s11
	s_nop 0
	v_addc_co_u32_e32 v19, vcc, 0, v15, vcc
	v_add_co_u32_e32 v24, vcc, s6, v14
	s_mov_b32 s6, 0xa000
	s_nop 0
	v_addc_co_u32_e32 v25, vcc, 0, v15, vcc
	v_add_co_u32_e32 v26, vcc, s81, v14
	v_readlane_b32 s62, v250, 4
	s_nop 0
	v_addc_co_u32_e32 v27, vcc, 0, v15, vcc
	v_add_co_u32_e32 v28, vcc, s58, v14
	v_readlane_b32 s63, v250, 5
	s_nop 0
	v_addc_co_u32_e32 v29, vcc, 0, v15, vcc
	v_add_co_u32_e32 v30, vcc, s82, v14
	v_readlane_b32 s64, v250, 6
	s_nop 0
	v_addc_co_u32_e32 v31, vcc, 0, v15, vcc
	v_add_co_u32_e32 v32, vcc, s6, v14
	s_mov_b32 s6, 0xe000
	s_nop 0
	v_addc_co_u32_e32 v33, vcc, 0, v15, vcc
	global_load_dword v39, v[22:23], off offset:2048 nt
	global_load_dword v40, v[24:25], off offset:-4096 nt
	global_load_dword v41, v[24:25], off nt
	global_load_dword v42, v[24:25], off offset:2048 nt
	global_load_dword v43, v[28:29], off offset:-4096 nt
	global_load_dword v44, v[28:29], off nt
	s_nop 0
	global_load_dword v28, v[28:29], off offset:2048 nt
	s_nop 0
	global_load_dword v29, v[32:33], off offset:-4096 nt
	v_add_co_u32_e32 v22, vcc, s45, v14
	v_readlane_b32 s65, v250, 7
	s_nop 0
	v_addc_co_u32_e32 v23, vcc, 0, v15, vcc
	v_add_co_u32_e32 v24, vcc, s59, v14
	global_load_dword v45, v[14:15], off nt
	global_load_dword v46, v[14:15], off offset:2048 nt
	global_load_dword v47, v[16:17], off offset:2048 nt
	s_nop 0
	global_load_dword v20, v[20:21], off offset:2048 nt
	s_nop 0
	global_load_dword v21, v[18:19], off offset:2048 nt
	s_nop 0
	global_load_dword v26, v[26:27], off offset:2048 nt
	s_nop 0
	global_load_dword v27, v[30:31], off offset:2048 nt
	s_nop 0
	global_load_dword v22, v[22:23], off offset:2048 nt
	v_addc_co_u32_e32 v25, vcc, 0, v15, vcc
	v_add_co_u32_e32 v16, vcc, s83, v14
	v_readlane_b32 s66, v250, 8
	s_nop 0
	v_addc_co_u32_e32 v17, vcc, 0, v15, vcc
	v_add_co_u32_e32 v18, vcc, s6, v14
	s_lshl_b32 s6, s30, 9
	s_nop 0
	v_addc_co_u32_e32 v19, vcc, 0, v15, vcc
	v_add_co_u32_e32 v14, vcc, s92, v14
	global_load_dword v16, v[16:17], off offset:2048 nt
	s_nop 0
	global_load_dword v17, v[32:33], off nt
	global_load_dword v23, v[32:33], off offset:2048 nt
	global_load_dword v30, v[24:25], off offset:-4096 nt
	global_load_dword v31, v[24:25], off nt
	s_nop 0
	global_load_dword v24, v[24:25], off offset:2048 nt
	s_nop 0
	global_load_dword v25, v[18:19], off offset:-4096 nt
	global_load_dword v32, v[18:19], off nt
	s_nop 0
	global_load_dword v18, v[18:19], off offset:2048 nt
	v_addc_co_u32_e32 v15, vcc, 0, v15, vcc
	global_load_dword v19, v[14:15], off nt
	s_nop 0
	global_load_dword v14, v[14:15], off offset:2048 nt
	v_add_u32_e32 v15, 0x400, v48
	s_add_i32 s6, s6, s31
	s_add_i32 s10, s6, s10
	s_lshl_b32 s6, s77, 1
	v_readlane_b32 s67, v250, 9
	v_readlane_b32 s68, v250, 10
	v_readlane_b32 s69, v250, 11
	v_readlane_b32 s70, v250, 12
	v_readlane_b32 s71, v250, 13
	s_waitcnt vmcnt(17)
; #define LAS __attribute__((address_space(3)))
; __device__ __forceinline__ unsigned pk_bf16(float lo, float hi) { f32x2 v = {lo, hi}; return __builtin_bit_cast(unsigned, __builtin_convertvector(v, bf16v2)); }
; __device__ __forceinline__ void transpose_item(const float* W, int K, int N, bf16_t* WT, int mode, int rowoff, const float* g, LAS float* scr, int item, int lane) {
;     ...
;     for (int i = 0; i < 32; ++i) scr[(2 * i + (lane >> 5)) * 33 + (lane & 31)] = tv[i];
;     asm volatile("s_waitcnt lgkmcnt(0)" ::: "memory");
;     const int c = lane & 7;
; #pragma unroll
;     for (int j = 0; j < 4; ++j) { const int n = (lane >> 3) + 8 * j; const LAS float* s = scr + (8 * c) * 33 + n;
;         u32x4 o; o.x = pk_bf16(s[0 * 33], s[1 * 33]); o.y = pk_bf16(s[2 * 33], s[3 * 33]); o.z = pk_bf16(s[4 * 33], s[5 * 33]); o.w = pk_bf16(s[6 * 33], s[7 * 33]);
;         *(u32x4*)(WT + (size_t)(drow0 + n) * K + k0 + 8 * c) = o; }
	ds_write2_b32 v48, v45, v46 offset1:66
	s_waitcnt vmcnt(16)
	ds_write2_b32 v48, v34, v47 offset0:132 offset1:198
	ds_write2_b32 v15, v35, v36 offset0:8 offset1:74
	s_waitcnt vmcnt(15)
	ds_write2_b32 v15, v37, v20 offset0:140 offset1:206
	v_add_u32_e32 v15, 0x800, v48
	ds_write2_b32 v15, v38, v39 offset0:16 offset1:82
	s_waitcnt vmcnt(14)
	ds_write2_b32 v15, v40, v21 offset0:148 offset1:214
	v_add_u32_e32 v15, 0xc00, v48
	ds_write2_b32 v15, v41, v42 offset0:24 offset1:90
	s_waitcnt vmcnt(13)
	ds_write2_b32 v15, v43, v26 offset0:156 offset1:222
	v_add_u32_e32 v15, 0x1000, v48
	ds_write2_b32 v15, v44, v28 offset0:32 offset1:98
	s_waitcnt vmcnt(12)
	ds_write2_b32 v15, v29, v27 offset0:164 offset1:230
	v_add_u32_e32 v15, 0x1400, v48
	s_waitcnt vmcnt(8)
	ds_write2_b32 v15, v17, v23 offset0:40 offset1:106
	s_waitcnt vmcnt(7)
	ds_write2_b32 v15, v30, v22 offset0:172 offset1:238
	v_add_u32_e32 v15, 0x1800, v48
	s_waitcnt vmcnt(5)
	ds_write2_b32 v15, v31, v24 offset0:48 offset1:114
	s_waitcnt vmcnt(4)
	ds_write2_b32 v15, v25, v16 offset0:180 offset1:246
	v_add_u32_e32 v15, 0x1c00, v48
	s_waitcnt vmcnt(2)
	ds_write2_b32 v15, v32, v18 offset0:56 offset1:122
	s_waitcnt vmcnt(0)
	ds_write2_b32 v15, v19, v14 offset0:188 offset1:254
	s_waitcnt lgkmcnt(0)
	ds_read2_b32 v[18:19], v50 offset0:33 offset1:41
	ds_read2_b32 v[20:21], v50 offset1:8
	ds_read2_b32 v[22:23], v50 offset0:66 offset1:74
	ds_read2_b32 v[24:25], v50 offset0:99 offset1:107
	ds_read2_b32 v[26:27], v50 offset0:132 offset1:140
	ds_read2_b32 v[28:29], v50 offset0:165 offset1:173
	ds_read2_b32 v[30:31], v50 offset0:198 offset1:206
	ds_read2_b32 v[32:33], v50 offset0:231 offset1:239
	v_add_u32_e32 v36, s10, v49
	v_ashrrev_i32_e32 v37, 31, v36
	v_lshl_add_u64 v[34:35], v[10:11], 0, s[6:7]
	v_lshlrev_b64 v[36:37], 9, v[36:37]
	s_waitcnt lgkmcnt(6)
	v_cvt_pk_bf16_f32 v14, v20, v18
	s_waitcnt lgkmcnt(4)
	v_cvt_pk_bf16_f32 v15, v22, v24
	s_waitcnt lgkmcnt(2)
	v_cvt_pk_bf16_f32 v16, v26, v28
	s_waitcnt lgkmcnt(0)
	v_cvt_pk_bf16_f32 v17, v30, v32
	v_lshl_add_u64 v[36:37], v[34:35], 0, v[36:37]
	v_add_u32_e32 v18, s10, v51
	global_store_dwordx4 v[36:37], v[14:17], off sc1
	v_readlane_b32 s72, v250, 14
	v_readlane_b32 s73, v250, 15
	v_cvt_pk_bf16_f32 v14, v21, v19
	v_ashrrev_i32_e32 v19, 31, v18
	v_cvt_pk_bf16_f32 v15, v23, v25
	v_cvt_pk_bf16_f32 v16, v27, v29
	v_cvt_pk_bf16_f32 v17, v31, v33
	v_lshlrev_b64 v[18:19], 9, v[18:19]
	ds_read2_b32 v[20:21], v50 offset0:49 offset1:57
	ds_read2_b32 v[22:23], v50 offset0:16 offset1:24
	ds_read2_b32 v[24:25], v50 offset0:82 offset1:90
	ds_read2_b32 v[26:27], v50 offset0:115 offset1:123
	ds_read2_b32 v[28:29], v50 offset0:148 offset1:156
	ds_read2_b32 v[30:31], v50 offset0:181 offset1:189
	ds_read2_b32 v[32:33], v50 offset0:214 offset1:222
	ds_read2_b32 v[36:37], v50 offset0:247 offset1:255
	v_lshl_add_u64 v[18:19], v[34:35], 0, v[18:19]
	global_store_dwordx4 v[18:19], v[14:17], off sc1
	v_add_u32_e32 v18, s10, v52
	v_ashrrev_i32_e32 v19, 31, v18
	v_lshlrev_b64 v[18:19], 9, v[18:19]
	s_waitcnt lgkmcnt(6)
	v_cvt_pk_bf16_f32 v14, v22, v20
	s_waitcnt lgkmcnt(4)
	v_cvt_pk_bf16_f32 v15, v24, v26
	s_waitcnt lgkmcnt(2)
	v_cvt_pk_bf16_f32 v16, v28, v30
	s_waitcnt lgkmcnt(0)
	v_cvt_pk_bf16_f32 v17, v32, v36
	v_lshl_add_u64 v[18:19], v[34:35], 0, v[18:19]
	global_store_dwordx4 v[18:19], v[14:17], off sc1
	v_add_u32_e32 v18, s10, v53
	v_ashrrev_i32_e32 v19, 31, v18
	v_lshlrev_b64 v[18:19], 9, v[18:19]
	v_cvt_pk_bf16_f32 v14, v23, v21
	v_cvt_pk_bf16_f32 v15, v25, v27
	v_cvt_pk_bf16_f32 v16, v29, v31
	v_cvt_pk_bf16_f32 v17, v33, v37
	v_lshl_add_u64 v[18:19], v[34:35], 0, v[18:19]
	global_store_dwordx4 v[18:19], v[14:17], off sc1
	s_waitcnt lgkmcnt(0)
	v_readlane_b32 s74, v250, 16
	v_readlane_b32 s75, v250, 17

; __device__ __forceinline__ unsigned pk_bf16(float lo, float hi) { f32x2 v = {lo, hi}; return __builtin_bit_cast(unsigned, __builtin_convertvector(v, bf16v2)); }
; __device__ __forceinline__ float gelu_tanh(float x) { const float y2 = x * (1.5957691216057308f + 0.07135481627f * x * x); return x * __builtin_amdgcn_rcpf(1.0f + __builtin_amdgcn_exp2f(-y2 * LOG2E)); }
;     __device__ __forceinline__ void operator()(const AccT& acc, const Unit& u, int wr, int wc, int fr, int fq) const {
;     ...
;             for (int m = 0; m < 4; ++m) { const int row = row0 + ai * HALF + m * 16; const float rs = rst[row - row_base]; bf16_t* rowp = base + (size_t)row * DM + col0;
; #pragma unroll
;                 for (int bj = 0; bj < 2; ++bj) { f32x4 v0 = acc[ai][bj][m][0] * rs, v1 = acc[ai][bj][m][1] * rs;
;                     if (isgate) {
; #pragma unroll
;                         for (int e = 0; e < 4; ++e) { v0[e] = gelu_tanh(v0[e]); v1[e] = gelu_tanh(v1[e]); } }
;                     u32x4 w; w.x = pk_bf16(v0[0], v0[1]); w.y = pk_bf16(v0[2], v0[3]); w.z = pk_bf16(v1[0], v1[1]); w.w = pk_bf16(v1[2], v1[3]);
;                     *(u32x4*)(rowp + bj * HALF) = w; } }
.LBB0_124:
	s_and_b64 s[44:45], s[40:41], exec
	s_cselect_b32 s7, s97, s93
	s_cselect_b32 s31, s96, s92
	s_lshl_b32 s6, s6, 8
	s_and_b32 s6, s6, 0x300
	v_add_u32_e32 v122, s6, v154
	v_mov_b32_e32 v120, s31
	v_mov_b32_e32 v121, s7
	v_ashrrev_i32_e32 v123, 31, v122
	v_ashrrev_i32_e32 v145, 31, v144
	v_lshl_add_u64 v[120:121], v[122:123], 1, v[120:121]
	v_lshlrev_b64 v[122:123], 11, v[144:145]
	v_lshl_add_u64 v[122:123], v[120:121], 0, v[122:123]
	v_cvt_pk_bf16_f32 v124, v124, v125
	v_cvt_pk_bf16_f32 v125, v126, v127
	v_cvt_pk_bf16_f32 v126, v150, v151
	v_cvt_pk_bf16_f32 v127, v148, v149
	v_mov_b32_e32 v147, v146
	global_store_dwordx4 v[122:123], v[124:127], off sc1
	s_andn2_b64 vcc, exec, s[40:41]
	s_nop 0
	v_mov_b32_e32 v126, v146
	v_mov_b32_e32 v127, v146
	v_pk_mul_f32 v[124:125], v[116:117], v[146:147]
	v_pk_mul_f32 v[116:117], v[114:115], v[126:127]
	v_cndmask_b32_e64 v114, 0, 1, s[40:41]
	v_pk_mul_f32 v[118:119], v[118:119], v[126:127]
	v_cmp_ne_u32_e64 s[6:7], 1, v114
	v_pk_mul_f32 v[126:127], v[112:113], v[146:147]
	s_cbranch_vccnz .LBB0_126
	v_mul_f32_e32 v145, 0x3d922279, v118
	v_mul_f32_e32 v113, 0x3d922279, v126
	v_fmaak_f32 v145, v118, v145, 0x3fcc422a
	v_mul_f32_e32 v146, 0x3d922279, v116
	v_fmaak_f32 v113, v126, v113, 0x3fcc422a
	v_mul_f32_e32 v114, 0x3d922279, v125
	v_mul_f32_e64 v145, v118, -v145
	v_fmaak_f32 v146, v116, v146, 0x3fcc422a
	v_mul_f32_e64 v113, v126, -v113
	v_fmaak_f32 v114, v125, v114, 0x3fcc422a
	v_mul_f32_e32 v145, 0x3fb8aa3b, v145
	v_mul_f32_e64 v146, v116, -v146
	v_mul_f32_e32 v113, 0x3fb8aa3b, v113
	v_mul_f32_e64 v114, v125, -v114
	v_exp_f32_e32 v145, v145
	v_mul_f32_e32 v146, 0x3fb8aa3b, v146
	v_exp_f32_e32 v113, v113
	v_mul_f32_e32 v114, 0x3fb8aa3b, v114
	v_exp_f32_e32 v147, v146
	v_exp_f32_e32 v115, v114
	v_add_f32_e32 v145, 1.0, v145
	v_add_f32_e32 v113, 1.0, v113
	v_rcp_f32_e32 v146, v145
	v_add_f32_e32 v145, 1.0, v147
	v_mul_f32_e32 v147, 0x3d922279, v119
	v_mul_f32_e32 v112, 0x3d922279, v124
	v_rcp_f32_e32 v114, v113
	v_add_f32_e32 v113, 1.0, v115
	v_mul_f32_e32 v115, 0x3d922279, v127
	v_fmaak_f32 v147, v119, v147, 0x3fcc422a
	v_mul_f32_e32 v148, 0x3d922279, v117
	v_fmaak_f32 v112, v124, v112, 0x3fcc422a
	v_fmaak_f32 v115, v127, v115, 0x3fcc422a
	v_mul_f32_e64 v147, v119, -v147
	v_fmaak_f32 v148, v117, v148, 0x3fcc422a
	v_mul_f32_e64 v112, v124, -v112
	v_mul_f32_e64 v115, v127, -v115
	v_mul_f32_e32 v147, 0x3fb8aa3b, v147
	v_mul_f32_e64 v148, v117, -v148
	v_mul_f32_e32 v112, 0x3fb8aa3b, v112
	v_mul_f32_e32 v115, 0x3fb8aa3b, v115
	v_exp_f32_e32 v147, v147
	v_mul_f32_e32 v148, 0x3fb8aa3b, v148
	v_exp_f32_e32 v112, v112
	v_exp_f32_e32 v115, v115
	v_exp_f32_e32 v149, v148
	v_rcp_f32_e32 v148, v145
	v_add_f32_e32 v145, 1.0, v147
	v_add_f32_e32 v112, 1.0, v112
	v_add_f32_e32 v115, 1.0, v115
	v_rcp_f32_e32 v147, v145
	v_add_f32_e32 v145, 1.0, v149
	v_rcp_f32_e32 v112, v112
	v_rcp_f32_e32 v113, v113
	v_rcp_f32_e32 v149, v145
	v_rcp_f32_e32 v115, v115
	v_pk_mul_f32 v[118:119], v[118:119], v[146:147]
	v_pk_mul_f32 v[124:125], v[124:125], v[112:113]
	v_pk_mul_f32 v[116:117], v[116:117], v[148:149]
	v_pk_mul_f32 v[126:127], v[126:127], v[114:115]
.LBB0_126:
	v_or_b32_e32 v114, 16, v144
	v_subrev_u32_e32 v112, s54, v114
	v_lshl_add_u32 v112, v112, 2, 0
	v_add_u32_e32 v112, 0x20000, v112
	ds_read_b32 v112, v112
	v_cvt_pk_bf16_f32 v124, v124, v125
	v_cvt_pk_bf16_f32 v125, v118, v119
	v_cvt_pk_bf16_f32 v126, v126, v127
	v_cvt_pk_bf16_f32 v127, v116, v117
	s_waitcnt lgkmcnt(0)
	v_pk_mul_f32 v[110:111], v[110:111], v[112:113] op_sel_hi:[1,0]
	v_pk_mul_f32 v[108:109], v[108:109], v[112:113] op_sel_hi:[1,0]
	v_pk_mul_f32 v[106:107], v[106:107], v[112:113] op_sel_hi:[1,0]
	s_and_b64 vcc, exec, s[6:7]
	v_pk_mul_f32 v[116:117], v[104:105], v[112:113] op_sel_hi:[1,0]
	global_store_dwordx4 v[122:123], v[124:127], off offset:256 sc1
	s_cbranch_vccnz .LBB0_128
	v_mul_f32_e32 v115, 0x3d922279, v110
	v_mul_f32_e32 v105, 0x3d922279, v116
	v_fmaak_f32 v115, v110, v115, 0x3fcc422a
	v_mul_f32_e32 v119, 0x3d922279, v106
	v_fmaak_f32 v105, v116, v105, 0x3fcc422a
	v_mul_f32_e32 v113, 0x3d922279, v109
	v_mul_f32_e64 v115, v110, -v115
	v_fmaak_f32 v119, v106, v119, 0x3fcc422a
	v_mul_f32_e64 v105, v116, -v105
	v_fmaak_f32 v113, v109, v113, 0x3fcc422a
	v_mul_f32_e32 v115, 0x3fb8aa3b, v115
	v_mul_f32_e64 v119, v106, -v119
	v_mul_f32_e32 v105, 0x3fb8aa3b, v105
	v_mul_f32_e64 v113, v109, -v113
	v_exp_f32_e32 v115, v115
	v_mul_f32_e32 v119, 0x3fb8aa3b, v119
	v_exp_f32_e32 v105, v105
	v_mul_f32_e32 v113, 0x3fb8aa3b, v113
	v_exp_f32_e32 v119, v119
	v_exp_f32_e32 v113, v113
	v_add_f32_e32 v115, 1.0, v115
	v_add_f32_e32 v105, 1.0, v105
	v_rcp_f32_e32 v122, v115
	v_add_f32_e32 v115, 1.0, v119
	v_mul_f32_e32 v119, 0x3d922279, v111
	v_mul_f32_e32 v104, 0x3d922279, v108
	v_rcp_f32_e32 v118, v105
	v_add_f32_e32 v105, 1.0, v113
	v_mul_f32_e32 v113, 0x3d922279, v117
	v_fmaak_f32 v119, v111, v119, 0x3fcc422a
	v_mul_f32_e32 v123, 0x3d922279, v107
	v_fmaak_f32 v104, v108, v104, 0x3fcc422a
	v_fmaak_f32 v113, v117, v113, 0x3fcc422a
	v_mul_f32_e64 v119, v111, -v119
	v_fmaak_f32 v123, v107, v123, 0x3fcc422a
	v_mul_f32_e64 v104, v108, -v104
	v_mul_f32_e64 v113, v117, -v113
	v_mul_f32_e32 v119, 0x3fb8aa3b, v119
	v_mul_f32_e64 v123, v107, -v123
	v_mul_f32_e32 v104, 0x3fb8aa3b, v104
	v_mul_f32_e32 v113, 0x3fb8aa3b, v113
	v_exp_f32_e32 v119, v119
	v_mul_f32_e32 v123, 0x3fb8aa3b, v123
	v_exp_f32_e32 v104, v104
	v_exp_f32_e32 v113, v113
	v_exp_f32_e32 v125, v123
	v_rcp_f32_e32 v124, v115
	v_add_f32_e32 v115, 1.0, v119
	v_add_f32_e32 v104, 1.0, v104
	v_add_f32_e32 v113, 1.0, v113
	v_rcp_f32_e32 v123, v115
	v_add_f32_e32 v115, 1.0, v125
	v_rcp_f32_e32 v104, v104
	v_rcp_f32_e32 v105, v105
	v_rcp_f32_e32 v125, v115
	v_rcp_f32_e32 v119, v113
	v_pk_mul_f32 v[110:111], v[110:111], v[122:123]
	v_pk_mul_f32 v[108:109], v[108:109], v[104:105]
	v_pk_mul_f32 v[106:107], v[106:107], v[124:125]
	v_pk_mul_f32 v[116:117], v[116:117], v[118:119]
; __device__ __forceinline__ unsigned pk_bf16(float lo, float hi) { f32x2 v = {lo, hi}; return __builtin_bit_cast(unsigned, __builtin_convertvector(v, bf16v2)); }
; __device__ __forceinline__ float gelu_tanh(float x) { const float y2 = x * (1.5957691216057308f + 0.07135481627f * x * x); return x * __builtin_amdgcn_rcpf(1.0f + __builtin_amdgcn_exp2f(-y2 * LOG2E)); }
;     __device__ __forceinline__ void operator()(const AccT& acc, const Unit& u, int wr, int wc, int fr, int fq) const {
;     ...
;             for (int m = 0; m < 4; ++m) { const int row = row0 + ai * HALF + m * 16; const float rs = rst[row - row_base]; bf16_t* rowp = base + (size_t)row * DM + col0;
; #pragma unroll
;                 for (int bj = 0; bj < 2; ++bj) { f32x4 v0 = acc[ai][bj][m][0] * rs, v1 = acc[ai][bj][m][1] * rs;
;                     if (isgate) {
; #pragma unroll
;                         for (int e = 0; e < 4; ++e) { v0[e] = gelu_tanh(v0[e]); v1[e] = gelu_tanh(v1[e]); } }
;                     u32x4 w; w.x = pk_bf16(v0[0], v0[1]); w.y = pk_bf16(v0[2], v0[3]); w.z = pk_bf16(v1[0], v1[1]); w.w = pk_bf16(v1[2], v1[3]);
;                     *(u32x4*)(rowp + bj * HALF) = w; } }
.LBB0_128:
	v_ashrrev_i32_e32 v115, 31, v114
	v_lshlrev_b64 v[104:105], 11, v[114:115]
	v_lshl_add_u64 v[104:105], v[120:121], 0, v[104:105]
	v_cvt_pk_bf16_f32 v108, v108, v109
	v_cvt_pk_bf16_f32 v109, v110, v111
	v_cvt_pk_bf16_f32 v110, v116, v117
	v_cvt_pk_bf16_f32 v111, v106, v107
	v_mov_b32_e32 v113, v112
	global_store_dwordx4 v[104:105], v[108:111], off sc1
	v_pk_mul_f32 v[106:107], v[100:101], v[112:113]
	s_and_b64 vcc, exec, s[6:7]
	v_mov_b32_e32 v108, v112
	v_mov_b32_e32 v109, v112
	v_pk_mul_f32 v[102:103], v[102:103], v[108:109]
	v_pk_mul_f32 v[100:101], v[98:99], v[108:109]
	v_pk_mul_f32 v[108:109], v[96:97], v[112:113]
	s_cbranch_vccnz .LBB0_130
	v_mul_f32_e32 v97, 0x3d922279, v108
	v_fmaak_f32 v97, v108, v97, 0x3fcc422a
	v_mul_f32_e32 v98, 0x3d922279, v107
	v_mul_f32_e64 v97, v108, -v97
	v_fmaak_f32 v98, v107, v98, 0x3fcc422a
	v_mul_f32_e32 v97, 0x3fb8aa3b, v97
	v_mul_f32_e64 v98, v107, -v98
	v_exp_f32_e32 v97, v97
	v_mul_f32_e32 v98, 0x3fb8aa3b, v98
	v_exp_f32_e32 v99, v98
	v_mul_f32_e32 v112, 0x3d922279, v103
	v_fmaak_f32 v112, v103, v112, 0x3fcc422a
	v_mul_f32_e64 v112, v103, -v112
	v_add_f32_e32 v97, 1.0, v97
	v_mul_f32_e32 v111, 0x3d922279, v100
	v_mul_f32_e32 v112, 0x3fb8aa3b, v112
	v_mul_f32_e32 v96, 0x3d922279, v106
	v_rcp_f32_e32 v98, v97
	v_add_f32_e32 v97, 1.0, v99
	v_mul_f32_e32 v99, 0x3d922279, v109
	v_mul_f32_e32 v110, 0x3d922279, v102
	v_fmaak_f32 v111, v100, v111, 0x3fcc422a
	v_exp_f32_e32 v113, v112
	v_mul_f32_e32 v112, 0x3d922279, v101
	v_fmaak_f32 v96, v106, v96, 0x3fcc422a
	v_fmaak_f32 v99, v109, v99, 0x3fcc422a
	v_fmaak_f32 v110, v102, v110, 0x3fcc422a
	v_mul_f32_e64 v111, v100, -v111
	v_fmaak_f32 v112, v101, v112, 0x3fcc422a
	v_mul_f32_e64 v96, v106, -v96
	v_mul_f32_e64 v99, v109, -v99
	v_mul_f32_e64 v110, v102, -v110
	v_mul_f32_e32 v111, 0x3fb8aa3b, v111
	v_mul_f32_e64 v112, v101, -v112
	v_mul_f32_e32 v96, 0x3fb8aa3b, v96
	v_mul_f32_e32 v99, 0x3fb8aa3b, v99
	v_mul_f32_e32 v110, 0x3fb8aa3b, v110
	v_exp_f32_e32 v111, v111
	v_mul_f32_e32 v112, 0x3fb8aa3b, v112
	v_exp_f32_e32 v96, v96
	v_exp_f32_e32 v99, v99
	v_exp_f32_e32 v110, v110
	v_exp_f32_e32 v114, v112
	v_add_f32_e32 v111, 1.0, v111
	v_add_f32_e32 v96, 1.0, v96
	v_add_f32_e32 v99, 1.0, v99
	v_add_f32_e32 v110, 1.0, v110
	v_rcp_f32_e32 v112, v111
	v_add_f32_e32 v111, 1.0, v113
	v_add_f32_e32 v113, 1.0, v114
	v_rcp_f32_e32 v96, v96
	v_rcp_f32_e32 v97, v97
	v_rcp_f32_e32 v110, v110
	v_rcp_f32_e32 v111, v111
	v_rcp_f32_e32 v113, v113
	v_rcp_f32_e32 v99, v99
	v_pk_mul_f32 v[106:107], v[106:107], v[96:97]
	v_pk_mul_f32 v[102:103], v[102:103], v[110:111]
	v_pk_mul_f32 v[100:101], v[100:101], v[112:113]
	v_pk_mul_f32 v[108:109], v[108:109], v[98:99]
.LBB0_130:
	v_or_b32_e32 v98, 32, v144
	v_subrev_u32_e32 v96, s54, v98
	v_lshl_add_u32 v96, v96, 2, 0
	v_add_u32_e32 v96, 0x20000, v96
	ds_read_b32 v96, v96
	v_cvt_pk_bf16_f32 v106, v106, v107
	v_cvt_pk_bf16_f32 v107, v102, v103
	v_cvt_pk_bf16_f32 v108, v108, v109
	v_cvt_pk_bf16_f32 v109, v100, v101
	s_waitcnt lgkmcnt(0)
	v_pk_mul_f32 v[94:95], v[94:95], v[96:97] op_sel_hi:[1,0]
	v_pk_mul_f32 v[92:93], v[92:93], v[96:97] op_sel_hi:[1,0]
	v_pk_mul_f32 v[90:91], v[90:91], v[96:97] op_sel_hi:[1,0]
	s_and_b64 vcc, exec, s[6:7]
	v_pk_mul_f32 v[100:101], v[88:89], v[96:97] op_sel_hi:[1,0]
	global_store_dwordx4 v[104:105], v[106:109], off offset:256 sc1
	s_cbranch_vccnz .LBB0_132
	v_mul_f32_e32 v99, 0x3d922279, v94
	v_mul_f32_e32 v89, 0x3d922279, v100
	v_fmaak_f32 v99, v94, v99, 0x3fcc422a
	v_mul_f32_e32 v103, 0x3d922279, v90
	v_fmaak_f32 v89, v100, v89, 0x3fcc422a
	v_mul_f32_e32 v97, 0x3d922279, v93
	v_mul_f32_e64 v99, v94, -v99
	v_fmaak_f32 v103, v90, v103, 0x3fcc422a
	v_mul_f32_e64 v89, v100, -v89
	v_fmaak_f32 v97, v93, v97, 0x3fcc422a
	v_mul_f32_e32 v99, 0x3fb8aa3b, v99
	v_mul_f32_e64 v103, v90, -v103
	v_mul_f32_e32 v89, 0x3fb8aa3b, v89
	v_mul_f32_e64 v97, v93, -v97
	v_exp_f32_e32 v99, v99
	v_mul_f32_e32 v103, 0x3fb8aa3b, v103
	v_exp_f32_e32 v89, v89
	v_mul_f32_e32 v97, 0x3fb8aa3b, v97
	v_exp_f32_e32 v103, v103
	v_exp_f32_e32 v97, v97
	v_add_f32_e32 v99, 1.0, v99
	v_add_f32_e32 v89, 1.0, v89
	v_rcp_f32_e32 v104, v99
	v_add_f32_e32 v99, 1.0, v103
	v_mul_f32_e32 v103, 0x3d922279, v95
	v_mul_f32_e32 v88, 0x3d922279, v92
	v_rcp_f32_e32 v102, v89
	v_add_f32_e32 v89, 1.0, v97
	v_mul_f32_e32 v97, 0x3d922279, v101
	v_fmaak_f32 v103, v95, v103, 0x3fcc422a
	v_mul_f32_e32 v105, 0x3d922279, v91
	v_fmaak_f32 v88, v92, v88, 0x3fcc422a
	v_fmaak_f32 v97, v101, v97, 0x3fcc422a
	v_mul_f32_e64 v103, v95, -v103
	v_fmaak_f32 v105, v91, v105, 0x3fcc422a
	v_mul_f32_e64 v88, v92, -v88
	v_mul_f32_e64 v97, v101, -v97
	v_mul_f32_e32 v103, 0x3fb8aa3b, v103
	v_mul_f32_e64 v105, v91, -v105
	v_mul_f32_e32 v88, 0x3fb8aa3b, v88
	v_mul_f32_e32 v97, 0x3fb8aa3b, v97
	v_exp_f32_e32 v103, v103
	v_mul_f32_e32 v105, 0x3fb8aa3b, v105
	v_exp_f32_e32 v88, v88
	v_exp_f32_e32 v97, v97
	v_exp_f32_e32 v107, v105
	v_rcp_f32_e32 v106, v99
	v_add_f32_e32 v99, 1.0, v103
	v_add_f32_e32 v88, 1.0, v88
	v_add_f32_e32 v97, 1.0, v97
	v_rcp_f32_e32 v105, v99
	v_add_f32_e32 v99, 1.0, v107
	v_rcp_f32_e32 v88, v88
	v_rcp_f32_e32 v89, v89
	v_rcp_f32_e32 v107, v99
	v_rcp_f32_e32 v103, v97
	v_pk_mul_f32 v[94:95], v[94:95], v[104:105]
	v_pk_mul_f32 v[92:93], v[92:93], v[88:89]
	v_pk_mul_f32 v[90:91], v[90:91], v[106:107]
	v_pk_mul_f32 v[100:101], v[100:101], v[102:103]
; __device__ __forceinline__ unsigned pk_bf16(float lo, float hi) { f32x2 v = {lo, hi}; return __builtin_bit_cast(unsigned, __builtin_convertvector(v, bf16v2)); }
; __device__ __forceinline__ float gelu_tanh(float x) { const float y2 = x * (1.5957691216057308f + 0.07135481627f * x * x); return x * __builtin_amdgcn_rcpf(1.0f + __builtin_amdgcn_exp2f(-y2 * LOG2E)); }
;     __device__ __forceinline__ void operator()(const AccT& acc, const Unit& u, int wr, int wc, int fr, int fq) const {
;     ...
;             for (int m = 0; m < 4; ++m) { const int row = row0 + ai * HALF + m * 16; const float rs = rst[row - row_base]; bf16_t* rowp = base + (size_t)row * DM + col0;
; #pragma unroll
;                 for (int bj = 0; bj < 2; ++bj) { f32x4 v0 = acc[ai][bj][m][0] * rs, v1 = acc[ai][bj][m][1] * rs;
;                     if (isgate) {
; #pragma unroll
;                         for (int e = 0; e < 4; ++e) { v0[e] = gelu_tanh(v0[e]); v1[e] = gelu_tanh(v1[e]); } }
;                     u32x4 w; w.x = pk_bf16(v0[0], v0[1]); w.y = pk_bf16(v0[2], v0[3]); w.z = pk_bf16(v1[0], v1[1]); w.w = pk_bf16(v1[2], v1[3]);
;                     *(u32x4*)(rowp + bj * HALF) = w; } }
.LBB0_132:
	v_ashrrev_i32_e32 v99, 31, v98
	v_lshlrev_b64 v[88:89], 11, v[98:99]
	v_lshl_add_u64 v[88:89], v[120:121], 0, v[88:89]
	v_cvt_pk_bf16_f32 v92, v92, v93
	v_cvt_pk_bf16_f32 v93, v94, v95
	v_cvt_pk_bf16_f32 v94, v100, v101
	v_cvt_pk_bf16_f32 v95, v90, v91
	v_mov_b32_e32 v97, v96
	global_store_dwordx4 v[88:89], v[92:95], off sc1
	v_pk_mul_f32 v[90:91], v[84:85], v[96:97]
	s_and_b64 vcc, exec, s[6:7]
	v_mov_b32_e32 v92, v96
	v_mov_b32_e32 v93, v96
	v_pk_mul_f32 v[86:87], v[86:87], v[92:93]
	v_pk_mul_f32 v[84:85], v[82:83], v[92:93]
	v_pk_mul_f32 v[92:93], v[80:81], v[96:97]
	s_cbranch_vccnz .LBB0_134
	v_mul_f32_e32 v81, 0x3d922279, v92
	v_fmaak_f32 v81, v92, v81, 0x3fcc422a
	v_mul_f32_e32 v82, 0x3d922279, v91
	v_mul_f32_e64 v81, v92, -v81
	v_fmaak_f32 v82, v91, v82, 0x3fcc422a
	v_mul_f32_e32 v81, 0x3fb8aa3b, v81
	v_mul_f32_e64 v82, v91, -v82
	v_exp_f32_e32 v81, v81
	v_mul_f32_e32 v82, 0x3fb8aa3b, v82
	v_exp_f32_e32 v83, v82
	v_mul_f32_e32 v96, 0x3d922279, v87
	v_fmaak_f32 v96, v87, v96, 0x3fcc422a
	v_mul_f32_e64 v96, v87, -v96
	v_add_f32_e32 v81, 1.0, v81
	v_mul_f32_e32 v95, 0x3d922279, v84
	v_mul_f32_e32 v96, 0x3fb8aa3b, v96
	v_mul_f32_e32 v80, 0x3d922279, v90
	v_rcp_f32_e32 v82, v81
	v_add_f32_e32 v81, 1.0, v83
	v_mul_f32_e32 v83, 0x3d922279, v93
	v_mul_f32_e32 v94, 0x3d922279, v86
	v_fmaak_f32 v95, v84, v95, 0x3fcc422a
	v_exp_f32_e32 v97, v96
	v_mul_f32_e32 v96, 0x3d922279, v85
	v_fmaak_f32 v80, v90, v80, 0x3fcc422a
	v_fmaak_f32 v83, v93, v83, 0x3fcc422a
	v_fmaak_f32 v94, v86, v94, 0x3fcc422a
	v_mul_f32_e64 v95, v84, -v95
	v_fmaak_f32 v96, v85, v96, 0x3fcc422a
	v_mul_f32_e64 v80, v90, -v80
	v_mul_f32_e64 v83, v93, -v83
	v_mul_f32_e64 v94, v86, -v94
	v_mul_f32_e32 v95, 0x3fb8aa3b, v95
	v_mul_f32_e64 v96, v85, -v96
	v_mul_f32_e32 v80, 0x3fb8aa3b, v80
	v_mul_f32_e32 v83, 0x3fb8aa3b, v83
	v_mul_f32_e32 v94, 0x3fb8aa3b, v94
	v_exp_f32_e32 v95, v95
	v_mul_f32_e32 v96, 0x3fb8aa3b, v96
	v_exp_f32_e32 v80, v80
	v_exp_f32_e32 v83, v83
	v_exp_f32_e32 v94, v94
	v_exp_f32_e32 v98, v96
	v_add_f32_e32 v95, 1.0, v95
	v_add_f32_e32 v80, 1.0, v80
	v_add_f32_e32 v83, 1.0, v83
	v_add_f32_e32 v94, 1.0, v94
	v_rcp_f32_e32 v96, v95
	v_add_f32_e32 v95, 1.0, v97
	v_add_f32_e32 v97, 1.0, v98
	v_rcp_f32_e32 v80, v80
	v_rcp_f32_e32 v81, v81
	v_rcp_f32_e32 v94, v94
	v_rcp_f32_e32 v95, v95
	v_rcp_f32_e32 v97, v97
	v_rcp_f32_e32 v83, v83
	v_pk_mul_f32 v[90:91], v[90:91], v[80:81]
	v_pk_mul_f32 v[86:87], v[86:87], v[94:95]
	v_pk_mul_f32 v[84:85], v[84:85], v[96:97]
	v_pk_mul_f32 v[92:93], v[92:93], v[82:83]
.LBB0_134:
	v_or_b32_e32 v82, 48, v144
	v_subrev_u32_e32 v80, s54, v82
	v_lshl_add_u32 v80, v80, 2, 0
	v_add_u32_e32 v80, 0x20000, v80
	ds_read_b32 v80, v80
	v_cvt_pk_bf16_f32 v90, v90, v91
	v_cvt_pk_bf16_f32 v91, v86, v87
	v_cvt_pk_bf16_f32 v92, v92, v93
	v_cvt_pk_bf16_f32 v93, v84, v85
	s_waitcnt lgkmcnt(0)
	v_pk_mul_f32 v[78:79], v[78:79], v[80:81] op_sel_hi:[1,0]
	v_pk_mul_f32 v[76:77], v[76:77], v[80:81] op_sel_hi:[1,0]
	v_pk_mul_f32 v[74:75], v[74:75], v[80:81] op_sel_hi:[1,0]
	s_and_b64 vcc, exec, s[6:7]
	v_pk_mul_f32 v[84:85], v[72:73], v[80:81] op_sel_hi:[1,0]
	global_store_dwordx4 v[88:89], v[90:93], off offset:256 sc1
	s_cbranch_vccnz .LBB0_136
	v_mul_f32_e32 v83, 0x3d922279, v78
	v_mul_f32_e32 v73, 0x3d922279, v84
	v_fmaak_f32 v83, v78, v83, 0x3fcc422a
	v_mul_f32_e32 v87, 0x3d922279, v74
	v_fmaak_f32 v73, v84, v73, 0x3fcc422a
	v_mul_f32_e32 v81, 0x3d922279, v77
	v_mul_f32_e64 v83, v78, -v83
	v_fmaak_f32 v87, v74, v87, 0x3fcc422a
	v_mul_f32_e64 v73, v84, -v73
	v_fmaak_f32 v81, v77, v81, 0x3fcc422a
	v_mul_f32_e32 v83, 0x3fb8aa3b, v83
	v_mul_f32_e64 v87, v74, -v87
	v_mul_f32_e32 v73, 0x3fb8aa3b, v73
	v_mul_f32_e64 v81, v77, -v81
	v_exp_f32_e32 v83, v83
	v_mul_f32_e32 v87, 0x3fb8aa3b, v87
	v_exp_f32_e32 v73, v73
	v_mul_f32_e32 v81, 0x3fb8aa3b, v81
	v_exp_f32_e32 v87, v87
	v_exp_f32_e32 v81, v81
	v_add_f32_e32 v83, 1.0, v83
	v_add_f32_e32 v73, 1.0, v73
	v_rcp_f32_e32 v88, v83
	v_add_f32_e32 v83, 1.0, v87
	v_mul_f32_e32 v87, 0x3d922279, v79
	v_mul_f32_e32 v72, 0x3d922279, v76
	v_rcp_f32_e32 v86, v73
	v_add_f32_e32 v73, 1.0, v81
	v_mul_f32_e32 v81, 0x3d922279, v85
	v_fmaak_f32 v87, v79, v87, 0x3fcc422a
	v_mul_f32_e32 v89, 0x3d922279, v75
	v_fmaak_f32 v72, v76, v72, 0x3fcc422a
	v_fmaak_f32 v81, v85, v81, 0x3fcc422a
	v_mul_f32_e64 v87, v79, -v87
	v_fmaak_f32 v89, v75, v89, 0x3fcc422a
	v_mul_f32_e64 v72, v76, -v72
	v_mul_f32_e64 v81, v85, -v81
	v_mul_f32_e32 v87, 0x3fb8aa3b, v87
	v_mul_f32_e64 v89, v75, -v89
	v_mul_f32_e32 v72, 0x3fb8aa3b, v72
	v_mul_f32_e32 v81, 0x3fb8aa3b, v81
	v_exp_f32_e32 v87, v87
	v_mul_f32_e32 v89, 0x3fb8aa3b, v89
	v_exp_f32_e32 v72, v72
	v_exp_f32_e32 v81, v81
	v_exp_f32_e32 v91, v89
	v_rcp_f32_e32 v90, v83
	v_add_f32_e32 v83, 1.0, v87
	v_add_f32_e32 v72, 1.0, v72
	v_add_f32_e32 v81, 1.0, v81
	v_rcp_f32_e32 v89, v83
	v_add_f32_e32 v83, 1.0, v91
	v_rcp_f32_e32 v72, v72
	v_rcp_f32_e32 v73, v73
	v_rcp_f32_e32 v91, v83
	v_rcp_f32_e32 v87, v81
	v_pk_mul_f32 v[78:79], v[78:79], v[88:89]
	v_pk_mul_f32 v[76:77], v[76:77], v[72:73]
	v_pk_mul_f32 v[74:75], v[74:75], v[90:91]
	v_pk_mul_f32 v[84:85], v[84:85], v[86:87]
; __device__ __forceinline__ unsigned pk_bf16(float lo, float hi) { f32x2 v = {lo, hi}; return __builtin_bit_cast(unsigned, __builtin_convertvector(v, bf16v2)); }
; __device__ __forceinline__ float gelu_tanh(float x) { const float y2 = x * (1.5957691216057308f + 0.07135481627f * x * x); return x * __builtin_amdgcn_rcpf(1.0f + __builtin_amdgcn_exp2f(-y2 * LOG2E)); }
;     __device__ __forceinline__ void operator()(const AccT& acc, const Unit& u, int wr, int wc, int fr, int fq) const {
;     ...
;             for (int m = 0; m < 4; ++m) { const int row = row0 + ai * HALF + m * 16; const float rs = rst[row - row_base]; bf16_t* rowp = base + (size_t)row * DM + col0;
; #pragma unroll
;                 for (int bj = 0; bj < 2; ++bj) { f32x4 v0 = acc[ai][bj][m][0] * rs, v1 = acc[ai][bj][m][1] * rs;
;                     if (isgate) {
; #pragma unroll
;                         for (int e = 0; e < 4; ++e) { v0[e] = gelu_tanh(v0[e]); v1[e] = gelu_tanh(v1[e]); } }
;                     u32x4 w; w.x = pk_bf16(v0[0], v0[1]); w.y = pk_bf16(v0[2], v0[3]); w.z = pk_bf16(v1[0], v1[1]); w.w = pk_bf16(v1[2], v1[3]);
;                     *(u32x4*)(rowp + bj * HALF) = w; } }
.LBB0_136:
	v_ashrrev_i32_e32 v83, 31, v82
	v_lshlrev_b64 v[72:73], 11, v[82:83]
	v_lshl_add_u64 v[72:73], v[120:121], 0, v[72:73]
	v_cvt_pk_bf16_f32 v76, v76, v77
	v_cvt_pk_bf16_f32 v77, v78, v79
	v_cvt_pk_bf16_f32 v78, v84, v85
	v_cvt_pk_bf16_f32 v79, v74, v75
	v_mov_b32_e32 v81, v80
	global_store_dwordx4 v[72:73], v[76:79], off sc1
	v_pk_mul_f32 v[74:75], v[68:69], v[80:81]
	s_and_b64 vcc, exec, s[6:7]
	v_mov_b32_e32 v76, v80
	v_mov_b32_e32 v77, v80
	v_pk_mul_f32 v[70:71], v[70:71], v[76:77]
	v_pk_mul_f32 v[68:69], v[66:67], v[76:77]
	v_pk_mul_f32 v[76:77], v[64:65], v[80:81]
	s_cbranch_vccnz .LBB0_138
	v_mul_f32_e32 v65, 0x3d922279, v76
	v_fmaak_f32 v65, v76, v65, 0x3fcc422a
	v_mul_f32_e32 v66, 0x3d922279, v75
	v_mul_f32_e64 v65, v76, -v65
	v_fmaak_f32 v66, v75, v66, 0x3fcc422a
	v_mul_f32_e32 v65, 0x3fb8aa3b, v65
	v_mul_f32_e64 v66, v75, -v66
	v_exp_f32_e32 v65, v65
	v_mul_f32_e32 v66, 0x3fb8aa3b, v66
	v_exp_f32_e32 v67, v66
	v_mul_f32_e32 v80, 0x3d922279, v71
	v_fmaak_f32 v80, v71, v80, 0x3fcc422a
	v_mul_f32_e64 v80, v71, -v80
	v_add_f32_e32 v65, 1.0, v65
	v_mul_f32_e32 v79, 0x3d922279, v68
	v_mul_f32_e32 v80, 0x3fb8aa3b, v80
	v_mul_f32_e32 v64, 0x3d922279, v74
	v_rcp_f32_e32 v66, v65
	v_add_f32_e32 v65, 1.0, v67
	v_mul_f32_e32 v67, 0x3d922279, v77
	v_mul_f32_e32 v78, 0x3d922279, v70
	v_fmaak_f32 v79, v68, v79, 0x3fcc422a
	v_exp_f32_e32 v81, v80
	v_mul_f32_e32 v80, 0x3d922279, v69
	v_fmaak_f32 v64, v74, v64, 0x3fcc422a
	v_fmaak_f32 v67, v77, v67, 0x3fcc422a
	v_fmaak_f32 v78, v70, v78, 0x3fcc422a
	v_mul_f32_e64 v79, v68, -v79
	v_fmaak_f32 v80, v69, v80, 0x3fcc422a
	v_mul_f32_e64 v64, v74, -v64
	v_mul_f32_e64 v67, v77, -v67
	v_mul_f32_e64 v78, v70, -v78
	v_mul_f32_e32 v79, 0x3fb8aa3b, v79
	v_mul_f32_e64 v80, v69, -v80
	v_mul_f32_e32 v64, 0x3fb8aa3b, v64
	v_mul_f32_e32 v67, 0x3fb8aa3b, v67
	v_mul_f32_e32 v78, 0x3fb8aa3b, v78
	v_exp_f32_e32 v79, v79
	v_mul_f32_e32 v80, 0x3fb8aa3b, v80
	v_exp_f32_e32 v64, v64
	v_exp_f32_e32 v67, v67
	v_exp_f32_e32 v78, v78
	v_exp_f32_e32 v82, v80
	v_add_f32_e32 v79, 1.0, v79
	v_add_f32_e32 v64, 1.0, v64
	v_add_f32_e32 v67, 1.0, v67
	v_add_f32_e32 v78, 1.0, v78
	v_rcp_f32_e32 v80, v79
	v_add_f32_e32 v79, 1.0, v81
	v_add_f32_e32 v81, 1.0, v82
	v_rcp_f32_e32 v64, v64
	v_rcp_f32_e32 v65, v65
	v_rcp_f32_e32 v78, v78
	v_rcp_f32_e32 v79, v79
	v_rcp_f32_e32 v81, v81
	v_rcp_f32_e32 v67, v67
	v_pk_mul_f32 v[74:75], v[74:75], v[64:65]
	v_pk_mul_f32 v[70:71], v[70:71], v[78:79]
	v_pk_mul_f32 v[68:69], v[68:69], v[80:81]
	v_pk_mul_f32 v[76:77], v[76:77], v[66:67]
.LBB0_138:
	v_add_u32_e32 v66, 0x80, v144
	v_subrev_u32_e32 v64, s54, v66
	v_lshl_add_u32 v64, v64, 2, 0
	v_add_u32_e32 v64, 0x20000, v64
	ds_read_b32 v64, v64
	v_cvt_pk_bf16_f32 v74, v74, v75
	v_cvt_pk_bf16_f32 v75, v70, v71
	v_cvt_pk_bf16_f32 v76, v76, v77
	v_cvt_pk_bf16_f32 v77, v68, v69
	s_waitcnt lgkmcnt(0)
	v_pk_mul_f32 v[62:63], v[62:63], v[64:65] op_sel_hi:[1,0]
	v_pk_mul_f32 v[60:61], v[60:61], v[64:65] op_sel_hi:[1,0]
	v_pk_mul_f32 v[58:59], v[58:59], v[64:65] op_sel_hi:[1,0]
	s_and_b64 vcc, exec, s[6:7]
	v_pk_mul_f32 v[68:69], v[56:57], v[64:65] op_sel_hi:[1,0]
	global_store_dwordx4 v[72:73], v[74:77], off offset:256 sc1
	s_cbranch_vccnz .LBB0_140
	v_mul_f32_e32 v67, 0x3d922279, v62
	v_mul_f32_e32 v57, 0x3d922279, v68
	v_fmaak_f32 v67, v62, v67, 0x3fcc422a
	v_mul_f32_e32 v71, 0x3d922279, v58
	v_fmaak_f32 v57, v68, v57, 0x3fcc422a
	v_mul_f32_e32 v65, 0x3d922279, v61
	v_mul_f32_e64 v67, v62, -v67
	v_fmaak_f32 v71, v58, v71, 0x3fcc422a
	v_mul_f32_e64 v57, v68, -v57
	v_fmaak_f32 v65, v61, v65, 0x3fcc422a
	v_mul_f32_e32 v67, 0x3fb8aa3b, v67
	v_mul_f32_e64 v71, v58, -v71
	v_mul_f32_e32 v57, 0x3fb8aa3b, v57
	v_mul_f32_e64 v65, v61, -v65
	v_exp_f32_e32 v67, v67
	v_mul_f32_e32 v71, 0x3fb8aa3b, v71
	v_exp_f32_e32 v57, v57
	v_mul_f32_e32 v65, 0x3fb8aa3b, v65
	v_exp_f32_e32 v71, v71
	v_exp_f32_e32 v65, v65
	v_add_f32_e32 v67, 1.0, v67
	v_add_f32_e32 v57, 1.0, v57
	v_rcp_f32_e32 v72, v67
	v_add_f32_e32 v67, 1.0, v71
	v_mul_f32_e32 v71, 0x3d922279, v63
	v_mul_f32_e32 v56, 0x3d922279, v60
	v_rcp_f32_e32 v70, v57
	v_add_f32_e32 v57, 1.0, v65
	v_mul_f32_e32 v65, 0x3d922279, v69
	v_fmaak_f32 v71, v63, v71, 0x3fcc422a
	v_mul_f32_e32 v73, 0x3d922279, v59
	v_fmaak_f32 v56, v60, v56, 0x3fcc422a
	v_fmaak_f32 v65, v69, v65, 0x3fcc422a
	v_mul_f32_e64 v71, v63, -v71
	v_fmaak_f32 v73, v59, v73, 0x3fcc422a
	v_mul_f32_e64 v56, v60, -v56
	v_mul_f32_e64 v65, v69, -v65
	v_mul_f32_e32 v71, 0x3fb8aa3b, v71
	v_mul_f32_e64 v73, v59, -v73
	v_mul_f32_e32 v56, 0x3fb8aa3b, v56
	v_mul_f32_e32 v65, 0x3fb8aa3b, v65
	v_exp_f32_e32 v71, v71
	v_mul_f32_e32 v73, 0x3fb8aa3b, v73
	v_exp_f32_e32 v56, v56
	v_exp_f32_e32 v65, v65
	v_exp_f32_e32 v75, v73
	v_rcp_f32_e32 v74, v67
	v_add_f32_e32 v67, 1.0, v71
	v_add_f32_e32 v56, 1.0, v56
	v_add_f32_e32 v65, 1.0, v65
	v_rcp_f32_e32 v73, v67
	v_add_f32_e32 v67, 1.0, v75
	v_rcp_f32_e32 v56, v56
	v_rcp_f32_e32 v57, v57
	v_rcp_f32_e32 v75, v67
	v_rcp_f32_e32 v71, v65
	v_pk_mul_f32 v[62:63], v[62:63], v[72:73]
	v_pk_mul_f32 v[60:61], v[60:61], v[56:57]
	v_pk_mul_f32 v[58:59], v[58:59], v[74:75]
	v_pk_mul_f32 v[68:69], v[68:69], v[70:71]
; __device__ __forceinline__ unsigned pk_bf16(float lo, float hi) { f32x2 v = {lo, hi}; return __builtin_bit_cast(unsigned, __builtin_convertvector(v, bf16v2)); }
; __device__ __forceinline__ float gelu_tanh(float x) { const float y2 = x * (1.5957691216057308f + 0.07135481627f * x * x); return x * __builtin_amdgcn_rcpf(1.0f + __builtin_amdgcn_exp2f(-y2 * LOG2E)); }
;     __device__ __forceinline__ void operator()(const AccT& acc, const Unit& u, int wr, int wc, int fr, int fq) const {
;     ...
;             for (int m = 0; m < 4; ++m) { const int row = row0 + ai * HALF + m * 16; const float rs = rst[row - row_base]; bf16_t* rowp = base + (size_t)row * DM + col0;
; #pragma unroll
;                 for (int bj = 0; bj < 2; ++bj) { f32x4 v0 = acc[ai][bj][m][0] * rs, v1 = acc[ai][bj][m][1] * rs;
;                     if (isgate) {
; #pragma unroll
;                         for (int e = 0; e < 4; ++e) { v0[e] = gelu_tanh(v0[e]); v1[e] = gelu_tanh(v1[e]); } }
;                     u32x4 w; w.x = pk_bf16(v0[0], v0[1]); w.y = pk_bf16(v0[2], v0[3]); w.z = pk_bf16(v1[0], v1[1]); w.w = pk_bf16(v1[2], v1[3]);
;                     *(u32x4*)(rowp + bj * HALF) = w; } }
.LBB0_140:
	v_ashrrev_i32_e32 v67, 31, v66
	v_lshlrev_b64 v[56:57], 11, v[66:67]
	v_lshl_add_u64 v[56:57], v[120:121], 0, v[56:57]
	v_cvt_pk_bf16_f32 v60, v60, v61
	v_cvt_pk_bf16_f32 v61, v62, v63
	v_cvt_pk_bf16_f32 v62, v68, v69
	v_cvt_pk_bf16_f32 v63, v58, v59
	v_mov_b32_e32 v65, v64
	global_store_dwordx4 v[56:57], v[60:63], off sc1
	v_pk_mul_f32 v[58:59], v[52:53], v[64:65]
	s_and_b64 vcc, exec, s[6:7]
	v_mov_b32_e32 v60, v64
	v_mov_b32_e32 v61, v64
	v_pk_mul_f32 v[54:55], v[54:55], v[60:61]
	v_pk_mul_f32 v[52:53], v[50:51], v[60:61]
	v_pk_mul_f32 v[60:61], v[48:49], v[64:65]
	s_cbranch_vccnz .LBB0_142
	v_mul_f32_e32 v49, 0x3d922279, v60
	v_fmaak_f32 v49, v60, v49, 0x3fcc422a
	v_mul_f32_e32 v50, 0x3d922279, v59
	v_mul_f32_e64 v49, v60, -v49
	v_fmaak_f32 v50, v59, v50, 0x3fcc422a
	v_mul_f32_e32 v49, 0x3fb8aa3b, v49
	v_mul_f32_e64 v50, v59, -v50
	v_exp_f32_e32 v49, v49
	v_mul_f32_e32 v50, 0x3fb8aa3b, v50
	v_exp_f32_e32 v51, v50
	v_mul_f32_e32 v64, 0x3d922279, v55
	v_fmaak_f32 v64, v55, v64, 0x3fcc422a
	v_mul_f32_e64 v64, v55, -v64
	v_add_f32_e32 v49, 1.0, v49
	v_mul_f32_e32 v63, 0x3d922279, v52
	v_mul_f32_e32 v64, 0x3fb8aa3b, v64
	v_mul_f32_e32 v48, 0x3d922279, v58
	v_rcp_f32_e32 v50, v49
	v_add_f32_e32 v49, 1.0, v51
	v_mul_f32_e32 v51, 0x3d922279, v61
	v_mul_f32_e32 v62, 0x3d922279, v54
	v_fmaak_f32 v63, v52, v63, 0x3fcc422a
	v_exp_f32_e32 v65, v64
	v_mul_f32_e32 v64, 0x3d922279, v53
	v_fmaak_f32 v48, v58, v48, 0x3fcc422a
	v_fmaak_f32 v51, v61, v51, 0x3fcc422a
	v_fmaak_f32 v62, v54, v62, 0x3fcc422a
	v_mul_f32_e64 v63, v52, -v63
	v_fmaak_f32 v64, v53, v64, 0x3fcc422a
	v_mul_f32_e64 v48, v58, -v48
	v_mul_f32_e64 v51, v61, -v51
	v_mul_f32_e64 v62, v54, -v62
	v_mul_f32_e32 v63, 0x3fb8aa3b, v63
	v_mul_f32_e64 v64, v53, -v64
	v_mul_f32_e32 v48, 0x3fb8aa3b, v48
	v_mul_f32_e32 v51, 0x3fb8aa3b, v51
	v_mul_f32_e32 v62, 0x3fb8aa3b, v62
	v_exp_f32_e32 v63, v63
	v_mul_f32_e32 v64, 0x3fb8aa3b, v64
	v_exp_f32_e32 v48, v48
	v_exp_f32_e32 v51, v51
	v_exp_f32_e32 v62, v62
	v_exp_f32_e32 v66, v64
	v_add_f32_e32 v63, 1.0, v63
	v_add_f32_e32 v48, 1.0, v48
	v_add_f32_e32 v51, 1.0, v51
	v_add_f32_e32 v62, 1.0, v62
	v_rcp_f32_e32 v64, v63
	v_add_f32_e32 v63, 1.0, v65
	v_add_f32_e32 v65, 1.0, v66
	v_rcp_f32_e32 v48, v48
	v_rcp_f32_e32 v49, v49
	v_rcp_f32_e32 v62, v62
	v_rcp_f32_e32 v63, v63
	v_rcp_f32_e32 v65, v65
	v_rcp_f32_e32 v51, v51
	v_pk_mul_f32 v[58:59], v[58:59], v[48:49]
	v_pk_mul_f32 v[54:55], v[54:55], v[62:63]
	v_pk_mul_f32 v[52:53], v[52:53], v[64:65]
	v_pk_mul_f32 v[60:61], v[60:61], v[50:51]
.LBB0_142:
	v_add_u32_e32 v50, 0x90, v144
	v_subrev_u32_e32 v48, s54, v50
	v_lshl_add_u32 v48, v48, 2, 0
	v_add_u32_e32 v48, 0x20000, v48
	ds_read_b32 v48, v48
	v_cvt_pk_bf16_f32 v58, v58, v59
	v_cvt_pk_bf16_f32 v59, v54, v55
	v_cvt_pk_bf16_f32 v60, v60, v61
	v_cvt_pk_bf16_f32 v61, v52, v53
	s_waitcnt lgkmcnt(0)
	v_pk_mul_f32 v[46:47], v[46:47], v[48:49] op_sel_hi:[1,0]
	v_pk_mul_f32 v[44:45], v[44:45], v[48:49] op_sel_hi:[1,0]
	v_pk_mul_f32 v[42:43], v[42:43], v[48:49] op_sel_hi:[1,0]
	s_and_b64 vcc, exec, s[6:7]
	v_pk_mul_f32 v[52:53], v[40:41], v[48:49] op_sel_hi:[1,0]
	global_store_dwordx4 v[56:57], v[58:61], off offset:256 sc1
	s_cbranch_vccnz .LBB0_144
	v_mul_f32_e32 v51, 0x3d922279, v46
	v_mul_f32_e32 v41, 0x3d922279, v52
	v_fmaak_f32 v51, v46, v51, 0x3fcc422a
	v_mul_f32_e32 v55, 0x3d922279, v42
	v_fmaak_f32 v41, v52, v41, 0x3fcc422a
	v_mul_f32_e32 v49, 0x3d922279, v45
	v_mul_f32_e64 v51, v46, -v51
	v_fmaak_f32 v55, v42, v55, 0x3fcc422a
	v_mul_f32_e64 v41, v52, -v41
	v_fmaak_f32 v49, v45, v49, 0x3fcc422a
	v_mul_f32_e32 v51, 0x3fb8aa3b, v51
	v_mul_f32_e64 v55, v42, -v55
	v_mul_f32_e32 v41, 0x3fb8aa3b, v41
	v_mul_f32_e64 v49, v45, -v49
	v_exp_f32_e32 v51, v51
	v_mul_f32_e32 v55, 0x3fb8aa3b, v55
	v_exp_f32_e32 v41, v41
	v_mul_f32_e32 v49, 0x3fb8aa3b, v49
	v_exp_f32_e32 v55, v55
	v_exp_f32_e32 v49, v49
	v_add_f32_e32 v51, 1.0, v51
	v_add_f32_e32 v41, 1.0, v41
	v_rcp_f32_e32 v56, v51
	v_add_f32_e32 v51, 1.0, v55
	v_mul_f32_e32 v55, 0x3d922279, v47
	v_mul_f32_e32 v40, 0x3d922279, v44
	v_rcp_f32_e32 v54, v41
	v_add_f32_e32 v41, 1.0, v49
	v_mul_f32_e32 v49, 0x3d922279, v53
	v_fmaak_f32 v55, v47, v55, 0x3fcc422a
	v_mul_f32_e32 v57, 0x3d922279, v43
	v_fmaak_f32 v40, v44, v40, 0x3fcc422a
	v_fmaak_f32 v49, v53, v49, 0x3fcc422a
	v_mul_f32_e64 v55, v47, -v55
	v_fmaak_f32 v57, v43, v57, 0x3fcc422a
	v_mul_f32_e64 v40, v44, -v40
	v_mul_f32_e64 v49, v53, -v49
	v_mul_f32_e32 v55, 0x3fb8aa3b, v55
	v_mul_f32_e64 v57, v43, -v57
	v_mul_f32_e32 v40, 0x3fb8aa3b, v40
	v_mul_f32_e32 v49, 0x3fb8aa3b, v49
	v_exp_f32_e32 v55, v55
	v_mul_f32_e32 v57, 0x3fb8aa3b, v57
	v_exp_f32_e32 v40, v40
	v_exp_f32_e32 v49, v49
	v_exp_f32_e32 v59, v57
	v_rcp_f32_e32 v58, v51
	v_add_f32_e32 v51, 1.0, v55
	v_add_f32_e32 v40, 1.0, v40
	v_add_f32_e32 v49, 1.0, v49
	v_rcp_f32_e32 v57, v51
	v_add_f32_e32 v51, 1.0, v59
	v_rcp_f32_e32 v40, v40
	v_rcp_f32_e32 v41, v41
	v_rcp_f32_e32 v59, v51
	v_rcp_f32_e32 v55, v49
	v_pk_mul_f32 v[46:47], v[46:47], v[56:57]
	v_pk_mul_f32 v[44:45], v[44:45], v[40:41]
	v_pk_mul_f32 v[42:43], v[42:43], v[58:59]
	v_pk_mul_f32 v[52:53], v[52:53], v[54:55]
; __device__ __forceinline__ unsigned pk_bf16(float lo, float hi) { f32x2 v = {lo, hi}; return __builtin_bit_cast(unsigned, __builtin_convertvector(v, bf16v2)); }
; __device__ __forceinline__ float gelu_tanh(float x) { const float y2 = x * (1.5957691216057308f + 0.07135481627f * x * x); return x * __builtin_amdgcn_rcpf(1.0f + __builtin_amdgcn_exp2f(-y2 * LOG2E)); }
;     __device__ __forceinline__ void operator()(const AccT& acc, const Unit& u, int wr, int wc, int fr, int fq) const {
;     ...
;             for (int m = 0; m < 4; ++m) { const int row = row0 + ai * HALF + m * 16; const float rs = rst[row - row_base]; bf16_t* rowp = base + (size_t)row * DM + col0;
; #pragma unroll
;                 for (int bj = 0; bj < 2; ++bj) { f32x4 v0 = acc[ai][bj][m][0] * rs, v1 = acc[ai][bj][m][1] * rs;
;                     if (isgate) {
; #pragma unroll
;                         for (int e = 0; e < 4; ++e) { v0[e] = gelu_tanh(v0[e]); v1[e] = gelu_tanh(v1[e]); } }
;                     u32x4 w; w.x = pk_bf16(v0[0], v0[1]); w.y = pk_bf16(v0[2], v0[3]); w.z = pk_bf16(v1[0], v1[1]); w.w = pk_bf16(v1[2], v1[3]);
;                     *(u32x4*)(rowp + bj * HALF) = w; } }
.LBB0_144:
	v_ashrrev_i32_e32 v51, 31, v50
	v_lshlrev_b64 v[40:41], 11, v[50:51]
	v_lshl_add_u64 v[40:41], v[120:121], 0, v[40:41]
	v_cvt_pk_bf16_f32 v44, v44, v45
	v_cvt_pk_bf16_f32 v45, v46, v47
	v_cvt_pk_bf16_f32 v46, v52, v53
	v_cvt_pk_bf16_f32 v47, v42, v43
	v_mov_b32_e32 v49, v48
	global_store_dwordx4 v[40:41], v[44:47], off sc1
	v_pk_mul_f32 v[42:43], v[36:37], v[48:49]
	s_and_b64 vcc, exec, s[6:7]
	v_mov_b32_e32 v44, v48
	v_mov_b32_e32 v45, v48
	v_pk_mul_f32 v[38:39], v[38:39], v[44:45]
	v_pk_mul_f32 v[36:37], v[34:35], v[44:45]
	v_pk_mul_f32 v[44:45], v[32:33], v[48:49]
	s_cbranch_vccnz .LBB0_146
	v_mul_f32_e32 v33, 0x3d922279, v44
	v_fmaak_f32 v33, v44, v33, 0x3fcc422a
	v_mul_f32_e32 v34, 0x3d922279, v43
	v_mul_f32_e64 v33, v44, -v33
	v_fmaak_f32 v34, v43, v34, 0x3fcc422a
	v_mul_f32_e32 v33, 0x3fb8aa3b, v33
	v_mul_f32_e64 v34, v43, -v34
	v_exp_f32_e32 v33, v33
	v_mul_f32_e32 v34, 0x3fb8aa3b, v34
	v_exp_f32_e32 v35, v34
	v_mul_f32_e32 v48, 0x3d922279, v39
	v_fmaak_f32 v48, v39, v48, 0x3fcc422a
	v_mul_f32_e64 v48, v39, -v48
	v_add_f32_e32 v33, 1.0, v33
	v_mul_f32_e32 v47, 0x3d922279, v36
	v_mul_f32_e32 v48, 0x3fb8aa3b, v48
	v_mul_f32_e32 v32, 0x3d922279, v42
	v_rcp_f32_e32 v34, v33
	v_add_f32_e32 v33, 1.0, v35
	v_mul_f32_e32 v35, 0x3d922279, v45
	v_mul_f32_e32 v46, 0x3d922279, v38
	v_fmaak_f32 v47, v36, v47, 0x3fcc422a
	v_exp_f32_e32 v49, v48
	v_mul_f32_e32 v48, 0x3d922279, v37
	v_fmaak_f32 v32, v42, v32, 0x3fcc422a
	v_fmaak_f32 v35, v45, v35, 0x3fcc422a
	v_fmaak_f32 v46, v38, v46, 0x3fcc422a
	v_mul_f32_e64 v47, v36, -v47
	v_fmaak_f32 v48, v37, v48, 0x3fcc422a
	v_mul_f32_e64 v32, v42, -v32
	v_mul_f32_e64 v35, v45, -v35
	v_mul_f32_e64 v46, v38, -v46
	v_mul_f32_e32 v47, 0x3fb8aa3b, v47
	v_mul_f32_e64 v48, v37, -v48
	v_mul_f32_e32 v32, 0x3fb8aa3b, v32
	v_mul_f32_e32 v35, 0x3fb8aa3b, v35
	v_mul_f32_e32 v46, 0x3fb8aa3b, v46
	v_exp_f32_e32 v47, v47
	v_mul_f32_e32 v48, 0x3fb8aa3b, v48
	v_exp_f32_e32 v32, v32
	v_exp_f32_e32 v35, v35
	v_exp_f32_e32 v46, v46
	v_exp_f32_e32 v50, v48
	v_add_f32_e32 v47, 1.0, v47
	v_add_f32_e32 v32, 1.0, v32
	v_add_f32_e32 v35, 1.0, v35
	v_add_f32_e32 v46, 1.0, v46
	v_rcp_f32_e32 v48, v47
	v_add_f32_e32 v47, 1.0, v49
	v_add_f32_e32 v49, 1.0, v50
	v_rcp_f32_e32 v32, v32
	v_rcp_f32_e32 v33, v33
	v_rcp_f32_e32 v46, v46
	v_rcp_f32_e32 v47, v47
	v_rcp_f32_e32 v49, v49
	v_rcp_f32_e32 v35, v35
	v_pk_mul_f32 v[42:43], v[42:43], v[32:33]
	v_pk_mul_f32 v[38:39], v[38:39], v[46:47]
	v_pk_mul_f32 v[36:37], v[36:37], v[48:49]
	v_pk_mul_f32 v[44:45], v[44:45], v[34:35]
.LBB0_146:
	v_add_u32_e32 v34, 0xa0, v144
	v_subrev_u32_e32 v32, s54, v34
	v_lshl_add_u32 v32, v32, 2, 0
	v_add_u32_e32 v32, 0x20000, v32
	ds_read_b32 v32, v32
	v_cvt_pk_bf16_f32 v42, v42, v43
	v_cvt_pk_bf16_f32 v43, v38, v39
	v_cvt_pk_bf16_f32 v44, v44, v45
	v_cvt_pk_bf16_f32 v45, v36, v37
	s_waitcnt lgkmcnt(0)
	v_pk_mul_f32 v[30:31], v[30:31], v[32:33] op_sel_hi:[1,0]
	v_pk_mul_f32 v[28:29], v[28:29], v[32:33] op_sel_hi:[1,0]
	v_pk_mul_f32 v[26:27], v[26:27], v[32:33] op_sel_hi:[1,0]
	s_and_b64 vcc, exec, s[6:7]
	v_pk_mul_f32 v[36:37], v[24:25], v[32:33] op_sel_hi:[1,0]
	global_store_dwordx4 v[40:41], v[42:45], off offset:256 sc1
	s_cbranch_vccnz .LBB0_148
	v_mul_f32_e32 v35, 0x3d922279, v30
	v_mul_f32_e32 v25, 0x3d922279, v36
	v_fmaak_f32 v35, v30, v35, 0x3fcc422a
	v_mul_f32_e32 v39, 0x3d922279, v26
	v_fmaak_f32 v25, v36, v25, 0x3fcc422a
	v_mul_f32_e32 v33, 0x3d922279, v29
	v_mul_f32_e64 v35, v30, -v35
	v_fmaak_f32 v39, v26, v39, 0x3fcc422a
	v_mul_f32_e64 v25, v36, -v25
	v_fmaak_f32 v33, v29, v33, 0x3fcc422a
	v_mul_f32_e32 v35, 0x3fb8aa3b, v35
	v_mul_f32_e64 v39, v26, -v39
	v_mul_f32_e32 v25, 0x3fb8aa3b, v25
	v_mul_f32_e64 v33, v29, -v33
	v_exp_f32_e32 v35, v35
	v_mul_f32_e32 v39, 0x3fb8aa3b, v39
	v_exp_f32_e32 v25, v25
	v_mul_f32_e32 v33, 0x3fb8aa3b, v33
	v_exp_f32_e32 v39, v39
	v_exp_f32_e32 v33, v33
	v_add_f32_e32 v35, 1.0, v35
	v_add_f32_e32 v25, 1.0, v25
	v_rcp_f32_e32 v40, v35
	v_add_f32_e32 v35, 1.0, v39
	v_mul_f32_e32 v39, 0x3d922279, v31
	v_mul_f32_e32 v24, 0x3d922279, v28
	v_rcp_f32_e32 v38, v25
	v_add_f32_e32 v25, 1.0, v33
	v_mul_f32_e32 v33, 0x3d922279, v37
	v_fmaak_f32 v39, v31, v39, 0x3fcc422a
	v_mul_f32_e32 v41, 0x3d922279, v27
	v_fmaak_f32 v24, v28, v24, 0x3fcc422a
	v_fmaak_f32 v33, v37, v33, 0x3fcc422a
	v_mul_f32_e64 v39, v31, -v39
	v_fmaak_f32 v41, v27, v41, 0x3fcc422a
	v_mul_f32_e64 v24, v28, -v24
	v_mul_f32_e64 v33, v37, -v33
	v_mul_f32_e32 v39, 0x3fb8aa3b, v39
	v_mul_f32_e64 v41, v27, -v41
	v_mul_f32_e32 v24, 0x3fb8aa3b, v24
	v_mul_f32_e32 v33, 0x3fb8aa3b, v33
	v_exp_f32_e32 v39, v39
	v_mul_f32_e32 v41, 0x3fb8aa3b, v41
	v_exp_f32_e32 v24, v24
	v_exp_f32_e32 v33, v33
	v_exp_f32_e32 v43, v41
	v_rcp_f32_e32 v42, v35
	v_add_f32_e32 v35, 1.0, v39
	v_add_f32_e32 v24, 1.0, v24
	v_add_f32_e32 v33, 1.0, v33
	v_rcp_f32_e32 v41, v35
	v_add_f32_e32 v35, 1.0, v43
	v_rcp_f32_e32 v24, v24
	v_rcp_f32_e32 v25, v25
	v_rcp_f32_e32 v43, v35
	v_rcp_f32_e32 v39, v33
	v_pk_mul_f32 v[30:31], v[30:31], v[40:41]
	v_pk_mul_f32 v[28:29], v[28:29], v[24:25]
	v_pk_mul_f32 v[26:27], v[26:27], v[42:43]
	v_pk_mul_f32 v[36:37], v[36:37], v[38:39]
; __device__ __forceinline__ unsigned pk_bf16(float lo, float hi) { f32x2 v = {lo, hi}; return __builtin_bit_cast(unsigned, __builtin_convertvector(v, bf16v2)); }
; __device__ __forceinline__ float gelu_tanh(float x) { const float y2 = x * (1.5957691216057308f + 0.07135481627f * x * x); return x * __builtin_amdgcn_rcpf(1.0f + __builtin_amdgcn_exp2f(-y2 * LOG2E)); }
;     __device__ __forceinline__ void operator()(const AccT& acc, const Unit& u, int wr, int wc, int fr, int fq) const {
;     ...
;             for (int m = 0; m < 4; ++m) { const int row = row0 + ai * HALF + m * 16; const float rs = rst[row - row_base]; bf16_t* rowp = base + (size_t)row * DM + col0;
; #pragma unroll
;                 for (int bj = 0; bj < 2; ++bj) { f32x4 v0 = acc[ai][bj][m][0] * rs, v1 = acc[ai][bj][m][1] * rs;
;                     if (isgate) {
; #pragma unroll
;                         for (int e = 0; e < 4; ++e) { v0[e] = gelu_tanh(v0[e]); v1[e] = gelu_tanh(v1[e]); } }
;                     u32x4 w; w.x = pk_bf16(v0[0], v0[1]); w.y = pk_bf16(v0[2], v0[3]); w.z = pk_bf16(v1[0], v1[1]); w.w = pk_bf16(v1[2], v1[3]);
;                     *(u32x4*)(rowp + bj * HALF) = w; } }
.LBB0_148:
	v_ashrrev_i32_e32 v35, 31, v34
	v_lshlrev_b64 v[24:25], 11, v[34:35]
	v_lshl_add_u64 v[24:25], v[120:121], 0, v[24:25]
	v_cvt_pk_bf16_f32 v28, v28, v29
	v_cvt_pk_bf16_f32 v29, v30, v31
	v_cvt_pk_bf16_f32 v30, v36, v37
	v_cvt_pk_bf16_f32 v31, v26, v27
	v_mov_b32_e32 v33, v32
	global_store_dwordx4 v[24:25], v[28:31], off sc1
	v_pk_mul_f32 v[26:27], v[20:21], v[32:33]
	s_and_b64 vcc, exec, s[6:7]
	v_mov_b32_e32 v28, v32
	v_mov_b32_e32 v29, v32
	v_pk_mul_f32 v[22:23], v[22:23], v[28:29]
	v_pk_mul_f32 v[20:21], v[18:19], v[28:29]
	v_pk_mul_f32 v[28:29], v[16:17], v[32:33]
	s_cbranch_vccnz .LBB0_150
	v_mul_f32_e32 v17, 0x3d922279, v28
	v_fmaak_f32 v17, v28, v17, 0x3fcc422a
	v_mul_f32_e32 v18, 0x3d922279, v27
	v_mul_f32_e64 v17, v28, -v17
	v_fmaak_f32 v18, v27, v18, 0x3fcc422a
	v_mul_f32_e32 v17, 0x3fb8aa3b, v17
	v_mul_f32_e64 v18, v27, -v18
	v_exp_f32_e32 v17, v17
	v_mul_f32_e32 v18, 0x3fb8aa3b, v18
	v_exp_f32_e32 v19, v18
	v_mul_f32_e32 v32, 0x3d922279, v23
	v_fmaak_f32 v32, v23, v32, 0x3fcc422a
	v_mul_f32_e64 v32, v23, -v32
	v_add_f32_e32 v17, 1.0, v17
	v_mul_f32_e32 v31, 0x3d922279, v20
	v_mul_f32_e32 v32, 0x3fb8aa3b, v32
	v_mul_f32_e32 v16, 0x3d922279, v26
	v_rcp_f32_e32 v18, v17
	v_add_f32_e32 v17, 1.0, v19
	v_mul_f32_e32 v19, 0x3d922279, v29
	v_mul_f32_e32 v30, 0x3d922279, v22
	v_fmaak_f32 v31, v20, v31, 0x3fcc422a
	v_exp_f32_e32 v33, v32
	v_mul_f32_e32 v32, 0x3d922279, v21
	v_fmaak_f32 v16, v26, v16, 0x3fcc422a
	v_fmaak_f32 v19, v29, v19, 0x3fcc422a
	v_fmaak_f32 v30, v22, v30, 0x3fcc422a
	v_mul_f32_e64 v31, v20, -v31
	v_fmaak_f32 v32, v21, v32, 0x3fcc422a
	v_mul_f32_e64 v16, v26, -v16
	v_mul_f32_e64 v19, v29, -v19
	v_mul_f32_e64 v30, v22, -v30
	v_mul_f32_e32 v31, 0x3fb8aa3b, v31
	v_mul_f32_e64 v32, v21, -v32
	v_mul_f32_e32 v16, 0x3fb8aa3b, v16
	v_mul_f32_e32 v19, 0x3fb8aa3b, v19
	v_mul_f32_e32 v30, 0x3fb8aa3b, v30
	v_exp_f32_e32 v31, v31
	v_mul_f32_e32 v32, 0x3fb8aa3b, v32
	v_exp_f32_e32 v16, v16
	v_exp_f32_e32 v19, v19
	v_exp_f32_e32 v30, v30
	v_exp_f32_e32 v34, v32
	v_add_f32_e32 v31, 1.0, v31
	v_add_f32_e32 v16, 1.0, v16
	v_add_f32_e32 v19, 1.0, v19
	v_add_f32_e32 v30, 1.0, v30
	v_rcp_f32_e32 v32, v31
	v_add_f32_e32 v31, 1.0, v33
	v_add_f32_e32 v33, 1.0, v34
	v_rcp_f32_e32 v16, v16
	v_rcp_f32_e32 v17, v17
	v_rcp_f32_e32 v30, v30
	v_rcp_f32_e32 v31, v31
	v_rcp_f32_e32 v33, v33
	v_rcp_f32_e32 v19, v19
	v_pk_mul_f32 v[26:27], v[26:27], v[16:17]
	v_pk_mul_f32 v[22:23], v[22:23], v[30:31]
	v_pk_mul_f32 v[20:21], v[20:21], v[32:33]
	v_pk_mul_f32 v[28:29], v[28:29], v[18:19]
.LBB0_150:
	v_add_u32_e32 v18, 0xb0, v144
	v_subrev_u32_e32 v16, s54, v18
	v_lshl_add_u32 v16, v16, 2, 0
	v_add_u32_e32 v16, 0x20000, v16
	ds_read_b32 v16, v16
	v_cvt_pk_bf16_f32 v26, v26, v27
	v_cvt_pk_bf16_f32 v27, v22, v23
	v_cvt_pk_bf16_f32 v28, v28, v29
	v_cvt_pk_bf16_f32 v29, v20, v21
	s_waitcnt lgkmcnt(0)
	v_pk_mul_f32 v[14:15], v[14:15], v[16:17] op_sel_hi:[1,0]
	v_pk_mul_f32 v[12:13], v[12:13], v[16:17] op_sel_hi:[1,0]
	v_pk_mul_f32 v[10:11], v[10:11], v[16:17] op_sel_hi:[1,0]
	s_and_b64 vcc, exec, s[6:7]
	v_pk_mul_f32 v[20:21], v[8:9], v[16:17] op_sel_hi:[1,0]
	global_store_dwordx4 v[24:25], v[26:29], off offset:256 sc1
	s_cbranch_vccnz .LBB0_152
	v_mul_f32_e32 v19, 0x3d922279, v14
	v_mul_f32_e32 v9, 0x3d922279, v20
	v_fmaak_f32 v19, v14, v19, 0x3fcc422a
	v_mul_f32_e32 v23, 0x3d922279, v10
	v_fmaak_f32 v9, v20, v9, 0x3fcc422a
	v_mul_f32_e32 v17, 0x3d922279, v13
	v_mul_f32_e64 v19, v14, -v19
	v_fmaak_f32 v23, v10, v23, 0x3fcc422a
	v_mul_f32_e64 v9, v20, -v9
	v_fmaak_f32 v17, v13, v17, 0x3fcc422a
	v_mul_f32_e32 v19, 0x3fb8aa3b, v19
	v_mul_f32_e64 v23, v10, -v23
	v_mul_f32_e32 v9, 0x3fb8aa3b, v9
	v_mul_f32_e64 v17, v13, -v17
	v_exp_f32_e32 v19, v19
	v_mul_f32_e32 v23, 0x3fb8aa3b, v23
	v_exp_f32_e32 v9, v9
	v_mul_f32_e32 v17, 0x3fb8aa3b, v17
	v_exp_f32_e32 v23, v23
	v_exp_f32_e32 v17, v17
	v_add_f32_e32 v19, 1.0, v19
	v_add_f32_e32 v9, 1.0, v9
	v_rcp_f32_e32 v24, v19
	v_add_f32_e32 v19, 1.0, v23
	v_mul_f32_e32 v23, 0x3d922279, v15
	v_mul_f32_e32 v8, 0x3d922279, v12
	v_rcp_f32_e32 v22, v9
	v_add_f32_e32 v9, 1.0, v17
	v_mul_f32_e32 v17, 0x3d922279, v21
	v_fmaak_f32 v23, v15, v23, 0x3fcc422a
	v_mul_f32_e32 v25, 0x3d922279, v11
	v_fmaak_f32 v8, v12, v8, 0x3fcc422a
	v_fmaak_f32 v17, v21, v17, 0x3fcc422a
	v_mul_f32_e64 v23, v15, -v23
	v_fmaak_f32 v25, v11, v25, 0x3fcc422a
	v_mul_f32_e64 v8, v12, -v8
	v_mul_f32_e64 v17, v21, -v17
	v_mul_f32_e32 v23, 0x3fb8aa3b, v23
	v_mul_f32_e64 v25, v11, -v25
	v_mul_f32_e32 v8, 0x3fb8aa3b, v8
	v_mul_f32_e32 v17, 0x3fb8aa3b, v17
	v_exp_f32_e32 v23, v23
	v_mul_f32_e32 v25, 0x3fb8aa3b, v25
	v_exp_f32_e32 v8, v8
	v_exp_f32_e32 v17, v17
	v_exp_f32_e32 v27, v25
	v_rcp_f32_e32 v26, v19
	v_add_f32_e32 v19, 1.0, v23
	v_add_f32_e32 v8, 1.0, v8
	v_add_f32_e32 v17, 1.0, v17
	v_rcp_f32_e32 v25, v19
	v_add_f32_e32 v19, 1.0, v27
	v_rcp_f32_e32 v8, v8
	v_rcp_f32_e32 v9, v9
	v_rcp_f32_e32 v27, v19
	v_rcp_f32_e32 v23, v17
	v_pk_mul_f32 v[14:15], v[14:15], v[24:25]
	v_pk_mul_f32 v[12:13], v[12:13], v[8:9]
	v_pk_mul_f32 v[10:11], v[10:11], v[26:27]
	v_pk_mul_f32 v[20:21], v[20:21], v[22:23]
; __device__ __forceinline__ unsigned pk_bf16(float lo, float hi) { f32x2 v = {lo, hi}; return __builtin_bit_cast(unsigned, __builtin_convertvector(v, bf16v2)); }
; __device__ __forceinline__ float gelu_tanh(float x) { const float y2 = x * (1.5957691216057308f + 0.07135481627f * x * x); return x * __builtin_amdgcn_rcpf(1.0f + __builtin_amdgcn_exp2f(-y2 * LOG2E)); }
; #define PG8_BAR __builtin_amdgcn_s_barrier()
;     __device__ __forceinline__ void operator()(const AccT& acc, const Unit& u, int wr, int wc, int fr, int fq) const {
;     ...
;             for (int m = 0; m < 4; ++m) { const int row = row0 + ai * HALF + m * 16; const float rs = rst[row - row_base]; bf16_t* rowp = base + (size_t)row * DM + col0;
; #pragma unroll
;                 for (int bj = 0; bj < 2; ++bj) { f32x4 v0 = acc[ai][bj][m][0] * rs, v1 = acc[ai][bj][m][1] * rs;
;                     if (isgate) {
; #pragma unroll
;                         for (int e = 0; e < 4; ++e) { v0[e] = gelu_tanh(v0[e]); v1[e] = gelu_tanh(v1[e]); } }
;                     u32x4 w; w.x = pk_bf16(v0[0], v0[1]); w.y = pk_bf16(v0[2], v0[3]); w.z = pk_bf16(v1[0], v1[1]); w.w = pk_bf16(v1[2], v1[3]);
;                     *(u32x4*)(rowp + bj * HALF) = w; } }
; template <class Epi, class Sched, bool ALIGN_EPI = false, bool SP2 = false>
; __device__ __forceinline__ void gemm_phase(PG8_LAS unsigned char* lds, const Gemm g, const Sched& S, const Epi& E, const int wid) {
;     ...
;         if constexpr (ALIGN_EPI) { if (wr == 0) PG8_BAR; }
;         if constexpr (!Epi::AFTER_DRAIN) { E(acc, cur, wr, wc, fr, fq); S.done(cur); }
;         if (!has_next) break;
; #pragma unroll
;         for (int a = 0; a < 2; ++a)
; #pragma unroll
;             for (int b = 0; b < 2; ++b)
; #pragma unroll
;                 for (int m = 0; m < 4; ++m)
; #pragma unroll
;                     for (int n = 0; n < 2; ++n) acc[a][b][m][n] = (f32x4){0.f, 0.f, 0.f, 0.f};
;         cur = nxt; cA = nA; cB = nB; ++ui;
;         if constexpr (ALIGN_EPI) { if (wr == 1) PG8_BAR; }
.LBB0_152:
	v_ashrrev_i32_e32 v19, 31, v18
	v_mov_b32_e32 v17, v16
	v_lshlrev_b64 v[8:9], 11, v[18:19]
	v_cvt_pk_bf16_f32 v12, v12, v13
	v_cvt_pk_bf16_f32 v13, v14, v15
	v_cvt_pk_bf16_f32 v15, v10, v11
	v_mov_b32_e32 v10, v16
	v_mov_b32_e32 v11, v16
	v_lshl_add_u64 v[8:9], v[120:121], 0, v[8:9]
	v_cvt_pk_bf16_f32 v14, v20, v21
	v_pk_mul_f32 v[6:7], v[6:7], v[10:11]
	v_pk_mul_f32 v[4:5], v[4:5], v[16:17]
	v_pk_mul_f32 v[2:3], v[2:3], v[10:11]
	s_and_b64 vcc, exec, s[6:7]
	v_pk_mul_f32 v[0:1], v[0:1], v[16:17]
	global_store_dwordx4 v[8:9], v[12:15], off sc1
	s_cbranch_vccnz .LBB0_154
	v_mul_f32_e32 v11, 0x3d922279, v0
	v_fmaak_f32 v11, v0, v11, 0x3fcc422a
	v_mul_f32_e32 v12, 0x3d922279, v5
	v_mul_f32_e64 v11, v0, -v11
	v_fmaak_f32 v12, v5, v12, 0x3fcc422a
	v_mul_f32_e32 v11, 0x3fb8aa3b, v11
	v_mul_f32_e64 v12, v5, -v12
	v_exp_f32_e32 v11, v11
	v_mul_f32_e32 v12, 0x3fb8aa3b, v12
	v_exp_f32_e32 v13, v12
	v_mul_f32_e32 v16, 0x3d922279, v7
	v_fmaak_f32 v16, v7, v16, 0x3fcc422a
	v_mul_f32_e64 v16, v7, -v16
	v_add_f32_e32 v11, 1.0, v11
	v_mul_f32_e32 v15, 0x3d922279, v2
	v_mul_f32_e32 v16, 0x3fb8aa3b, v16
	v_mul_f32_e32 v10, 0x3d922279, v4
	v_rcp_f32_e32 v12, v11
	v_add_f32_e32 v11, 1.0, v13
	v_mul_f32_e32 v13, 0x3d922279, v1
	v_mul_f32_e32 v14, 0x3d922279, v6
	v_fmaak_f32 v15, v2, v15, 0x3fcc422a
	v_exp_f32_e32 v17, v16
	v_mul_f32_e32 v16, 0x3d922279, v3
	v_fmaak_f32 v10, v4, v10, 0x3fcc422a
	v_fmaak_f32 v13, v1, v13, 0x3fcc422a
	v_fmaak_f32 v14, v6, v14, 0x3fcc422a
	v_mul_f32_e64 v15, v2, -v15
	v_fmaak_f32 v16, v3, v16, 0x3fcc422a
	v_mul_f32_e64 v10, v4, -v10
	v_mul_f32_e64 v13, v1, -v13
	v_mul_f32_e64 v14, v6, -v14
	v_mul_f32_e32 v15, 0x3fb8aa3b, v15
	v_mul_f32_e64 v16, v3, -v16
	v_mul_f32_e32 v10, 0x3fb8aa3b, v10
	v_mul_f32_e32 v13, 0x3fb8aa3b, v13
	v_mul_f32_e32 v14, 0x3fb8aa3b, v14
	v_exp_f32_e32 v15, v15
	v_mul_f32_e32 v16, 0x3fb8aa3b, v16
	v_exp_f32_e32 v10, v10
	v_exp_f32_e32 v13, v13
	v_exp_f32_e32 v14, v14
	v_exp_f32_e32 v18, v16
	v_add_f32_e32 v15, 1.0, v15
	v_add_f32_e32 v10, 1.0, v10
	v_add_f32_e32 v13, 1.0, v13
	v_add_f32_e32 v14, 1.0, v14
	v_rcp_f32_e32 v16, v15
	v_add_f32_e32 v15, 1.0, v17
	v_add_f32_e32 v17, 1.0, v18
	v_rcp_f32_e32 v10, v10
	v_rcp_f32_e32 v11, v11
	v_rcp_f32_e32 v14, v14
	v_rcp_f32_e32 v15, v15
	v_rcp_f32_e32 v17, v17
	v_rcp_f32_e32 v13, v13
	v_pk_mul_f32 v[4:5], v[4:5], v[10:11]
	v_pk_mul_f32 v[6:7], v[6:7], v[14:15]
	v_pk_mul_f32 v[2:3], v[2:3], v[16:17]
	v_pk_mul_f32 v[0:1], v[0:1], v[12:13]
.LBB0_154:
	v_cvt_pk_bf16_f32 v4, v4, v5
	v_cvt_pk_bf16_f32 v5, v6, v7
	v_cvt_pk_bf16_f32 v6, v0, v1
	v_cvt_pk_bf16_f32 v7, v2, v3
	s_andn2_b64 vcc, exec, s[4:5]
	s_mov_b64 s[4:5], -1
	global_store_dwordx4 v[8:9], v[4:7], off offset:256 sc1
	s_cbranch_vccnz .LBB0_110
	s_andn2_b64 vcc, exec, s[10:11]
	s_cbranch_vccnz .LBB0_109
	s_barrier
	s_branch .LBB0_109

; __device__ __forceinline__ float bf_lo(unsigned w) { return __uint_as_float(w << 16); }
; __device__ __forceinline__ float bf_hi(unsigned w) { return __uint_as_float(w & 0xffff0000u); }
; __device__ __forceinline__ void conv_phase(const bf16_t* xbr, const float* cw, const float* cb, bf16_t* xc, int gt, int ngt) {
;     ...
;         for (int t = 0; t < TCH; ++t) {
;             const u32x4 xw = *(const u32x4*)(src + (size_t)t * DM);
;             float cur[8] = {bf_lo(xw.x), bf_hi(xw.x), bf_lo(xw.y), bf_hi(xw.y), bf_lo(xw.z), bf_hi(xw.z), bf_lo(xw.w), bf_hi(xw.w)};
;             float o[8];
; #pragma unroll
;             for (int e = 0; e < 8; ++e) { o[e] = bias[e] + w[0][e] * xm[0][e] + w[1][e] * xm[1][e] + w[2][e] * xm[2][e] + w[3][e] * cur[e]; xm[0][e] = xm[1][e]; xm[1][e] = xm[2][e]; xm[2][e] = cur[e]; }
.LBB0_207:
	v_lshl_add_u64 v[60:61], v[40:41], 0, s[4:5]
	v_add_co_u32_e32 v88, vcc, s38, v60
	v_pk_fma_f32 v[62:63], v[32:33], v[62:63], v[36:37]
	s_nop 0
	v_addc_co_u32_e32 v89, vcc, 0, v61, vcc
	v_add_co_u32_e32 v90, vcc, s40, v60
	v_pk_fma_f32 v[66:67], v[34:35], v[66:67], v[38:39]
	s_nop 0
	v_addc_co_u32_e32 v91, vcc, 0, v61, vcc
	v_add_co_u32_e32 v104, vcc, s39, v60
	v_pk_fma_f32 v[72:73], v[24:25], v[72:73], v[28:29]
	s_nop 0
	v_addc_co_u32_e32 v105, vcc, 0, v61, vcc
	v_add_co_u32_e32 v106, vcc, s41, v60
	v_pk_fma_f32 v[76:77], v[26:27], v[76:77], v[30:31]
	s_nop 0
	v_addc_co_u32_e32 v107, vcc, 0, v61, vcc
	v_add_co_u32_e32 v92, vcc, s44, v60
	v_pk_fma_f32 v[78:79], v[32:33], v[54:55], v[36:37]
	s_nop 0
	v_addc_co_u32_e32 v93, vcc, 0, v61, vcc
	v_add_co_u32_e32 v100, vcc, s46, v60
	v_pk_fma_f32 v[80:81], v[34:35], v[56:57], v[38:39]
	s_nop 0
	v_addc_co_u32_e32 v101, vcc, 0, v61, vcc
	v_add_co_u32_e32 v114, vcc, s45, v60
	v_pk_fma_f32 v[82:83], v[24:25], v[58:59], v[28:29]
	s_nop 0
	v_addc_co_u32_e32 v115, vcc, 0, v61, vcc
	v_add_co_u32_e32 v116, vcc, s47, v60
	v_pk_fma_f32 v[84:85], v[26:27], v[50:51], v[30:31]
	v_pk_fma_f32 v[62:63], v[0:1], v[54:55], v[62:63]
	v_pk_fma_f32 v[66:67], v[2:3], v[56:57], v[66:67]
	v_pk_fma_f32 v[72:73], v[8:9], v[58:59], v[72:73]
	v_pk_fma_f32 v[50:51], v[10:11], v[50:51], v[76:77]
	v_pk_fma_f32 v[108:109], v[0:1], v[42:43], v[78:79]
	v_pk_fma_f32 v[110:111], v[2:3], v[44:45], v[80:81]
	v_pk_fma_f32 v[112:113], v[8:9], v[48:49], v[82:83]
	v_addc_co_u32_e32 v117, vcc, 0, v61, vcc
	global_load_dwordx4 v[54:57], v[90:91], off offset:-4096
	global_load_dwordx4 v[58:61], v[88:89], off offset:2048
	global_load_dwordx4 v[76:79], v[90:91], off
	global_load_dwordx4 v[80:83], v[90:91], off offset:2048
	s_nop 0
	global_load_dwordx4 v[88:91], v[100:101], off offset:-4096
	s_nop 0
	global_load_dwordx4 v[92:95], v[92:93], off offset:2048
	s_nop 0
	global_load_dwordx4 v[96:99], v[100:101], off
	s_nop 0
	global_load_dwordx4 v[100:103], v[100:101], off offset:2048
	v_pk_fma_f32 v[64:65], v[32:33], v[42:43], v[36:37]
	v_pk_fma_f32 v[68:69], v[34:35], v[44:45], v[38:39]
	v_pk_fma_f32 v[70:71], v[24:25], v[48:49], v[28:29]
	v_pk_fma_f32 v[74:75], v[26:27], v[46:47], v[30:31]
	v_pk_fma_f32 v[84:85], v[10:11], v[46:47], v[84:85]
	v_pk_fma_f32 v[118:119], v[4:5], v[42:43], v[62:63]
	v_pk_fma_f32 v[120:121], v[6:7], v[44:45], v[66:67]
	v_pk_fma_f32 v[122:123], v[12:13], v[48:49], v[72:73]
	v_pk_fma_f32 v[124:125], v[14:15], v[46:47], v[50:51]
	s_add_u32 s4, s4, 0x4000
	s_addc_u32 s5, s5, 0
	s_cmpk_eq_u32 s4, 0x8000
	s_waitcnt vmcnt(7)
	v_lshlrev_b32_e32 v126, 16, v54
	v_and_b32_e32 v127, 0xffff0000, v54
	v_lshlrev_b32_e32 v128, 16, v55
	v_and_b32_e32 v129, 0xffff0000, v55
	v_lshlrev_b32_e32 v130, 16, v56
	v_and_b32_e32 v131, 0xffff0000, v56
	v_lshlrev_b32_e32 v132, 16, v57
	v_and_b32_e32 v133, 0xffff0000, v57
	s_waitcnt vmcnt(6)
	v_lshlrev_b32_e32 v134, 16, v58
	v_and_b32_e32 v135, 0xffff0000, v58
	v_lshlrev_b32_e32 v136, 16, v59
	v_and_b32_e32 v137, 0xffff0000, v59
	v_lshlrev_b32_e32 v138, 16, v60
	v_and_b32_e32 v139, 0xffff0000, v60
	v_lshlrev_b32_e32 v60, 16, v61
	v_and_b32_e32 v61, 0xffff0000, v61
	s_waitcnt vmcnt(5)
	v_lshlrev_b32_e32 v140, 16, v76
	v_and_b32_e32 v141, 0xffff0000, v76
	v_lshlrev_b32_e32 v142, 16, v77
	v_and_b32_e32 v143, 0xffff0000, v77
	v_lshlrev_b32_e32 v144, 16, v78
	v_and_b32_e32 v145, 0xffff0000, v78
	v_lshlrev_b32_e32 v78, 16, v79
	v_and_b32_e32 v79, 0xffff0000, v79
	s_waitcnt vmcnt(4)
	v_lshlrev_b32_e32 v146, 16, v80
	v_and_b32_e32 v147, 0xffff0000, v80
	v_lshlrev_b32_e32 v80, 16, v81
	v_and_b32_e32 v81, 0xffff0000, v81
	v_lshlrev_b32_e32 v148, 16, v82
	v_and_b32_e32 v149, 0xffff0000, v82
	v_lshlrev_b32_e32 v82, 16, v83
	v_and_b32_e32 v83, 0xffff0000, v83
	s_waitcnt vmcnt(3)
	v_lshlrev_b32_e32 v150, 16, v88
	v_and_b32_e32 v151, 0xffff0000, v88
	v_lshlrev_b32_e32 v88, 16, v89
	v_and_b32_e32 v89, 0xffff0000, v89
	v_lshlrev_b32_e32 v152, 16, v90
	v_and_b32_e32 v153, 0xffff0000, v90
	v_lshlrev_b32_e32 v90, 16, v91
	v_and_b32_e32 v91, 0xffff0000, v91
	s_waitcnt vmcnt(2)
	v_lshlrev_b32_e32 v62, 16, v92
	v_and_b32_e32 v63, 0xffff0000, v92
	v_lshlrev_b32_e32 v66, 16, v93
	v_and_b32_e32 v67, 0xffff0000, v93
	v_lshlrev_b32_e32 v72, 16, v94
	v_and_b32_e32 v73, 0xffff0000, v94
	v_lshlrev_b32_e32 v76, 16, v95
	v_and_b32_e32 v77, 0xffff0000, v95
	s_waitcnt vmcnt(1)
	v_lshlrev_b32_e32 v54, 16, v96
	v_and_b32_e32 v55, 0xffff0000, v96
	v_lshlrev_b32_e32 v56, 16, v97
	v_and_b32_e32 v57, 0xffff0000, v97
	v_lshlrev_b32_e32 v58, 16, v98
	v_and_b32_e32 v59, 0xffff0000, v98
	v_lshlrev_b32_e32 v50, 16, v99
	v_and_b32_e32 v51, 0xffff0000, v99
	s_waitcnt vmcnt(0)
; __device__ __forceinline__ unsigned pk_bf16(float lo, float hi) { f32x2 v = {lo, hi}; return __builtin_bit_cast(unsigned, __builtin_convertvector(v, bf16v2)); }
; __device__ __forceinline__ float bf_lo(unsigned w) { return __uint_as_float(w << 16); }
; __device__ __forceinline__ float bf_hi(unsigned w) { return __uint_as_float(w & 0xffff0000u); }
; __device__ __forceinline__ void conv_phase(const bf16_t* xbr, const float* cw, const float* cb, bf16_t* xc, int gt, int ngt) {
;     ...
;         for (int t = 0; t < TCH; ++t) {
;             const u32x4 xw = *(const u32x4*)(src + (size_t)t * DM);
;             float cur[8] = {bf_lo(xw.x), bf_hi(xw.x), bf_lo(xw.y), bf_hi(xw.y), bf_lo(xw.z), bf_hi(xw.z), bf_lo(xw.w), bf_hi(xw.w)};
;             float o[8];
; #pragma unroll
;             for (int e = 0; e < 8; ++e) { o[e] = bias[e] + w[0][e] * xm[0][e] + w[1][e] * xm[1][e] + w[2][e] * xm[2][e] + w[3][e] * cur[e]; xm[0][e] = xm[1][e]; xm[1][e] = xm[2][e]; xm[2][e] = cur[e]; }
;             u32x4 ow; ow.x = pk_bf16(o[0], o[1]); ow.y = pk_bf16(o[2], o[3]); ow.z = pk_bf16(o[4], o[5]); ow.w = pk_bf16(o[6], o[7]);
;             *(u32x4*)(dst + (size_t)t * DM) = ow;
	v_lshlrev_b32_e32 v42, 16, v100
	v_and_b32_e32 v43, 0xffff0000, v100
	v_lshlrev_b32_e32 v44, 16, v101
	v_and_b32_e32 v45, 0xffff0000, v101
	v_lshlrev_b32_e32 v48, 16, v102
	v_and_b32_e32 v49, 0xffff0000, v102
	v_lshlrev_b32_e32 v46, 16, v103
	v_and_b32_e32 v47, 0xffff0000, v103
	v_pk_fma_f32 v[92:93], v[16:17], v[126:127], v[118:119]
	v_pk_fma_f32 v[94:95], v[18:19], v[128:129], v[120:121]
	v_pk_fma_f32 v[96:97], v[20:21], v[130:131], v[122:123]
	v_pk_fma_f32 v[98:99], v[22:23], v[132:133], v[124:125]
	v_pk_fma_f32 v[100:101], v[4:5], v[126:127], v[108:109]
	v_pk_fma_f32 v[102:103], v[6:7], v[128:129], v[110:111]
	v_pk_fma_f32 v[108:109], v[12:13], v[130:131], v[112:113]
	v_pk_fma_f32 v[84:85], v[14:15], v[132:133], v[84:85]
	v_pk_fma_f32 v[64:65], v[0:1], v[126:127], v[64:65]
	v_pk_fma_f32 v[110:111], v[2:3], v[128:129], v[68:69]
	v_pk_fma_f32 v[112:113], v[8:9], v[130:131], v[70:71]
	v_pk_fma_f32 v[74:75], v[10:11], v[132:133], v[74:75]
	v_pk_fma_f32 v[118:119], v[32:33], v[126:127], v[36:37]
	v_pk_fma_f32 v[120:121], v[34:35], v[128:129], v[38:39]
	v_pk_fma_f32 v[122:123], v[24:25], v[130:131], v[28:29]
	v_pk_fma_f32 v[124:125], v[26:27], v[132:133], v[30:31]
	v_pk_fma_f32 v[126:127], v[32:33], v[134:135], v[36:37]
	v_pk_fma_f32 v[128:129], v[34:35], v[136:137], v[38:39]
	v_pk_fma_f32 v[130:131], v[24:25], v[138:139], v[28:29]
	v_pk_fma_f32 v[132:133], v[26:27], v[60:61], v[30:31]
	v_pk_fma_f32 v[154:155], v[32:33], v[140:141], v[36:37]
	v_pk_fma_f32 v[156:157], v[34:35], v[142:143], v[38:39]
	v_pk_fma_f32 v[158:159], v[24:25], v[144:145], v[28:29]
	v_pk_fma_f32 v[160:161], v[26:27], v[78:79], v[30:31]
	v_pk_fma_f32 v[162:163], v[32:33], v[146:147], v[36:37]
	v_pk_fma_f32 v[164:165], v[34:35], v[80:81], v[38:39]
	v_pk_fma_f32 v[166:167], v[24:25], v[148:149], v[28:29]
	v_pk_fma_f32 v[168:169], v[26:27], v[82:83], v[30:31]
	v_pk_fma_f32 v[170:171], v[32:33], v[150:151], v[36:37]
	v_pk_fma_f32 v[172:173], v[34:35], v[88:89], v[38:39]
	v_pk_fma_f32 v[174:175], v[24:25], v[152:153], v[28:29]
	v_pk_fma_f32 v[176:177], v[26:27], v[90:91], v[30:31]
	v_cvt_pk_bf16_f32 v68, v92, v93
	v_cvt_pk_bf16_f32 v69, v94, v95
	v_cvt_pk_bf16_f32 v70, v96, v97
	v_cvt_pk_bf16_f32 v71, v98, v99
	v_pk_fma_f32 v[92:93], v[16:17], v[134:135], v[100:101]
	v_pk_fma_f32 v[94:95], v[18:19], v[136:137], v[102:103]
	v_pk_fma_f32 v[96:97], v[20:21], v[138:139], v[108:109]
	v_pk_fma_f32 v[84:85], v[22:23], v[60:61], v[84:85]
	v_pk_fma_f32 v[64:65], v[4:5], v[134:135], v[64:65]
	v_pk_fma_f32 v[98:99], v[6:7], v[136:137], v[110:111]
	v_pk_fma_f32 v[100:101], v[12:13], v[138:139], v[112:113]
	v_pk_fma_f32 v[74:75], v[14:15], v[60:61], v[74:75]
	v_pk_fma_f32 v[102:103], v[0:1], v[134:135], v[118:119]
	v_pk_fma_f32 v[108:109], v[2:3], v[136:137], v[120:121]
	v_pk_fma_f32 v[110:111], v[8:9], v[138:139], v[122:123]
	v_pk_fma_f32 v[60:61], v[10:11], v[60:61], v[124:125]
	v_pk_fma_f32 v[112:113], v[0:1], v[140:141], v[126:127]
	v_pk_fma_f32 v[118:119], v[2:3], v[142:143], v[128:129]
	v_pk_fma_f32 v[120:121], v[8:9], v[144:145], v[130:131]
	v_pk_fma_f32 v[122:123], v[10:11], v[78:79], v[132:133]
	v_pk_fma_f32 v[124:125], v[0:1], v[146:147], v[154:155]
	v_pk_fma_f32 v[126:127], v[2:3], v[80:81], v[156:157]
	v_pk_fma_f32 v[128:129], v[8:9], v[148:149], v[158:159]
	v_pk_fma_f32 v[130:131], v[10:11], v[82:83], v[160:161]
	v_pk_fma_f32 v[132:133], v[0:1], v[150:151], v[162:163]
	v_pk_fma_f32 v[134:135], v[2:3], v[88:89], v[164:165]
	v_pk_fma_f32 v[136:137], v[8:9], v[152:153], v[166:167]
	v_pk_fma_f32 v[138:139], v[10:11], v[90:91], v[168:169]
	v_pk_fma_f32 v[154:155], v[0:1], v[62:63], v[170:171]
	v_pk_fma_f32 v[156:157], v[2:3], v[66:67], v[172:173]
	v_pk_fma_f32 v[158:159], v[8:9], v[72:73], v[174:175]
	v_pk_fma_f32 v[160:161], v[10:11], v[76:77], v[176:177]
	global_store_dwordx4 v[106:107], v[68:71], off offset:-4096 sc1
	v_pk_fma_f32 v[64:65], v[16:17], v[140:141], v[64:65]
	v_pk_fma_f32 v[74:75], v[22:23], v[78:79], v[74:75]
; __device__ __forceinline__ unsigned pk_bf16(float lo, float hi) { f32x2 v = {lo, hi}; return __builtin_bit_cast(unsigned, __builtin_convertvector(v, bf16v2)); }
; __device__ __forceinline__ float bf_lo(unsigned w) { return __uint_as_float(w << 16); }
; __device__ __forceinline__ float bf_hi(unsigned w) { return __uint_as_float(w & 0xffff0000u); }
; __device__ __forceinline__ void conv_phase(const bf16_t* xbr, const float* cw, const float* cb, bf16_t* xc, int gt, int ngt) {
;     ...
;         for (int t = 0; t < TCH; ++t) {
;             const u32x4 xw = *(const u32x4*)(src + (size_t)t * DM);
;             float cur[8] = {bf_lo(xw.x), bf_hi(xw.x), bf_lo(xw.y), bf_hi(xw.y), bf_lo(xw.z), bf_hi(xw.z), bf_lo(xw.w), bf_hi(xw.w)};
;             float o[8];
; #pragma unroll
;             for (int e = 0; e < 8; ++e) { o[e] = bias[e] + w[0][e] * xm[0][e] + w[1][e] * xm[1][e] + w[2][e] * xm[2][e] + w[3][e] * cur[e]; xm[0][e] = xm[1][e]; xm[1][e] = xm[2][e]; xm[2][e] = cur[e]; }
;             u32x4 ow; ow.x = pk_bf16(o[0], o[1]); ow.y = pk_bf16(o[2], o[3]); ow.z = pk_bf16(o[4], o[5]); ow.w = pk_bf16(o[6], o[7]);
;             *(u32x4*)(dst + (size_t)t * DM) = ow;
	v_cvt_pk_bf16_f32 v68, v92, v93
	v_cvt_pk_bf16_f32 v69, v94, v95
	v_cvt_pk_bf16_f32 v70, v96, v97
	v_cvt_pk_bf16_f32 v71, v84, v85
	v_pk_fma_f32 v[84:85], v[18:19], v[142:143], v[98:99]
	v_pk_fma_f32 v[92:93], v[20:21], v[144:145], v[100:101]
	v_pk_fma_f32 v[94:95], v[4:5], v[140:141], v[102:103]
	v_pk_fma_f32 v[96:97], v[6:7], v[142:143], v[108:109]
	v_pk_fma_f32 v[98:99], v[12:13], v[144:145], v[110:111]
	v_pk_fma_f32 v[60:61], v[14:15], v[78:79], v[60:61]
	v_pk_fma_f32 v[78:79], v[4:5], v[146:147], v[112:113]
	v_pk_fma_f32 v[100:101], v[6:7], v[80:81], v[118:119]
	v_pk_fma_f32 v[102:103], v[12:13], v[148:149], v[120:121]
	v_pk_fma_f32 v[108:109], v[14:15], v[82:83], v[122:123]
	v_pk_fma_f32 v[110:111], v[4:5], v[150:151], v[124:125]
	v_pk_fma_f32 v[112:113], v[6:7], v[88:89], v[126:127]
	v_pk_fma_f32 v[118:119], v[12:13], v[152:153], v[128:129]
	v_pk_fma_f32 v[120:121], v[14:15], v[90:91], v[130:131]
	v_pk_fma_f32 v[122:123], v[4:5], v[62:63], v[132:133]
	v_pk_fma_f32 v[124:125], v[6:7], v[66:67], v[134:135]
	v_pk_fma_f32 v[126:127], v[12:13], v[72:73], v[136:137]
	v_pk_fma_f32 v[128:129], v[14:15], v[76:77], v[138:139]
	v_pk_fma_f32 v[130:131], v[4:5], v[54:55], v[154:155]
	v_pk_fma_f32 v[132:133], v[6:7], v[56:57], v[156:157]
	v_pk_fma_f32 v[134:135], v[12:13], v[58:59], v[158:159]
	v_pk_fma_f32 v[136:137], v[14:15], v[50:51], v[160:161]
	global_store_dwordx4 v[104:105], v[68:71], off offset:2048 sc1
	v_pk_fma_f32 v[60:61], v[22:23], v[82:83], v[60:61]
	v_pk_fma_f32 v[78:79], v[16:17], v[150:151], v[78:79]
	v_cvt_pk_bf16_f32 v68, v64, v65
	v_cvt_pk_bf16_f32 v69, v84, v85
	v_cvt_pk_bf16_f32 v70, v92, v93
	v_cvt_pk_bf16_f32 v71, v74, v75
	v_pk_fma_f32 v[64:65], v[16:17], v[146:147], v[94:95]
	v_pk_fma_f32 v[74:75], v[18:19], v[80:81], v[96:97]
	v_pk_fma_f32 v[80:81], v[20:21], v[148:149], v[98:99]
	v_pk_fma_f32 v[82:83], v[18:19], v[88:89], v[100:101]
	v_pk_fma_f32 v[84:85], v[20:21], v[152:153], v[102:103]
	v_pk_fma_f32 v[88:89], v[22:23], v[90:91], v[108:109]
	v_pk_fma_f32 v[90:91], v[16:17], v[62:63], v[110:111]
	v_pk_fma_f32 v[92:93], v[18:19], v[66:67], v[112:113]
	v_pk_fma_f32 v[94:95], v[20:21], v[72:73], v[118:119]
	v_pk_fma_f32 v[96:97], v[22:23], v[76:77], v[120:121]
	v_pk_fma_f32 v[98:99], v[16:17], v[54:55], v[122:123]
	v_pk_fma_f32 v[100:101], v[18:19], v[56:57], v[124:125]
	v_pk_fma_f32 v[102:103], v[20:21], v[58:59], v[126:127]
	v_pk_fma_f32 v[104:105], v[22:23], v[50:51], v[128:129]
	v_pk_fma_f32 v[108:109], v[16:17], v[42:43], v[130:131]
	v_pk_fma_f32 v[110:111], v[18:19], v[44:45], v[132:133]
	v_pk_fma_f32 v[112:113], v[20:21], v[48:49], v[134:135]
	v_pk_fma_f32 v[118:119], v[22:23], v[46:47], v[136:137]
	global_store_dwordx4 v[106:107], v[68:71], off sc1
	v_cvt_pk_bf16_f32 v78, v78, v79
	v_cvt_pk_bf16_f32 v79, v82, v83
	v_cvt_pk_bf16_f32 v68, v64, v65
	v_cvt_pk_bf16_f32 v69, v74, v75
	v_cvt_pk_bf16_f32 v70, v80, v81
	v_cvt_pk_bf16_f32 v71, v60, v61
	v_cvt_pk_bf16_f32 v80, v84, v85
	v_cvt_pk_bf16_f32 v81, v88, v89
	v_cvt_pk_bf16_f32 v82, v90, v91
	v_cvt_pk_bf16_f32 v83, v92, v93
	v_cvt_pk_bf16_f32 v84, v94, v95
	v_cvt_pk_bf16_f32 v85, v96, v97
	v_cvt_pk_bf16_f32 v88, v98, v99
	v_cvt_pk_bf16_f32 v89, v100, v101
	v_cvt_pk_bf16_f32 v90, v102, v103
	v_cvt_pk_bf16_f32 v91, v104, v105
	v_cvt_pk_bf16_f32 v92, v108, v109
	v_cvt_pk_bf16_f32 v93, v110, v111
	v_cvt_pk_bf16_f32 v94, v112, v113
	v_cvt_pk_bf16_f32 v95, v118, v119
	global_store_dwordx4 v[106:107], v[68:71], off offset:2048 sc1
	global_store_dwordx4 v[116:117], v[78:81], off offset:-4096 sc1
	global_store_dwordx4 v[114:115], v[82:85], off offset:2048 sc1
	global_store_dwordx4 v[116:117], v[88:91], off sc1
	global_store_dwordx4 v[116:117], v[92:95], off offset:2048 sc1
	s_cbranch_scc0 .LBB0_207
	v_add_u32_e32 v86, s3, v86
	v_cmp_lt_i32_e32 vcc, s48, v86
	s_or_b64 s[10:11], vcc, s[10:11]
	v_add_u32_e32 v87, s34, v87
	s_andn2_b64 exec, exec, s[10:11]
	s_cbranch_execnz .LBB0_200

; __device__ __forceinline__ unsigned pk_bf16(float lo, float hi) { f32x2 v = {lo, hi}; return __builtin_bit_cast(unsigned, __builtin_convertvector(v, bf16v2)); }
; #define PG8_LAS __attribute__((address_space(3)))
; __device__ __forceinline__ void tile_row_ss(const AccT& acc, PG8_LAS float* P, int wr, int wc, int fr, int fq) {
; #pragma unroll
;     for (int ai = 0; ai < 2; ++ai)
; #pragma unroll
;         for (int m = 0; m < 4; ++m) { float ss = 0.f;
; #pragma unroll
;             for (int bj = 0; bj < 2; ++bj) { const f32x4 v0 = acc[ai][bj][m][0], v1 = acc[ai][bj][m][1];
;                 ss += (v0[0] * v0[0] + v0[1] * v0[1]) + (v0[2] * v0[2] + v0[3] * v0[3]) + (v1[0] * v1[0] + v1[1] * v1[1]) + (v1[2] * v1[2] + v1[3] * v1[3]); }
;             ss += __shfl_xor(ss, 16); ss += __shfl_xor(ss, 32);
;             if (fq == 0) P[(ai * HALF + wr * 64 + m * 16 + fr) * 4 + wc] = ss; }
;     __device__ __forceinline__ void fused(AccT& acc, const Unit& u, int wr, int wc, int fr, int fq, PG8_LAS unsigned char* lds, int wid, int lane) const {
;     ...
;                 for (int bj = 0; bj < 2; ++bj) { const f32x4 v0 = acc[ai][bj][m][0], v1 = acc[ai][bj][m][1];
;                     u32x4 w; w.x = pk_bf16(v0[0], v0[1]); w.y = pk_bf16(v0[2], v0[3]); w.z = pk_bf16(v1[0], v1[1]); w.w = pk_bf16(v1[2], v1[3]);
;                     *(u32x4*)(xb + off0 + (unsigned)(ai * HALF + m * 16) * DM + bj * HALF) = w; }
;         tile_row_ss(acc, P, wr, wc, fr, fq);
.LBB0_410:
	s_lshl_b32 s5, s10, 8
	s_add_i32 s6, s5, s72
	v_or_b32_e32 v128, s6, v146
	v_lshlrev_b32_e32 v128, 10, v128
	s_lshl_b32 s6, s4, 8
	v_add3_u32 v132, s6, v147, v128
	v_mov_b32_e32 v133, 0
	v_cvt_pk_bf16_f32 v128, v124, v125
	v_cvt_pk_bf16_f32 v129, v126, v127
	v_cvt_pk_bf16_f32 v130, v120, v121
	v_cvt_pk_bf16_f32 v131, v122, v123
	v_lshl_add_u64 v[132:133], v[132:133], 1, s[94:95]
	s_mov_b32 s6, 0x8000
	s_barrier
	global_store_dwordx4 v[132:133], v[128:131], off sc1
	v_add_co_u32_e32 v134, vcc, s6, v132
	s_nop 0
	v_cvt_pk_bf16_f32 v128, v116, v117
	v_cvt_pk_bf16_f32 v129, v118, v119
	v_cvt_pk_bf16_f32 v130, v112, v113
	v_cvt_pk_bf16_f32 v131, v114, v115
	global_store_dwordx4 v[132:133], v[128:131], off offset:256 sc1
	v_addc_co_u32_e32 v135, vcc, 0, v133, vcc
	s_nop 0
	v_cvt_pk_bf16_f32 v128, v108, v109
	v_cvt_pk_bf16_f32 v129, v110, v111
	v_cvt_pk_bf16_f32 v130, v104, v105
	v_cvt_pk_bf16_f32 v131, v106, v107
	global_store_dwordx4 v[134:135], v[128:131], off sc1
	s_mov_b32 s6, 0x10000
	v_mul_f32_e32 v125, v125, v125
	v_cvt_pk_bf16_f32 v128, v96, v97
	v_cvt_pk_bf16_f32 v129, v98, v99
	v_cvt_pk_bf16_f32 v130, v88, v89
	v_cvt_pk_bf16_f32 v131, v90, v91
	global_store_dwordx4 v[134:135], v[128:131], off offset:256 sc1
	v_add_co_u32_e32 v134, vcc, s6, v132
	s_nop 0
	v_cvt_pk_bf16_f32 v128, v100, v101
	v_cvt_pk_bf16_f32 v129, v102, v103
	v_cvt_pk_bf16_f32 v130, v92, v93
	v_cvt_pk_bf16_f32 v131, v94, v95
	v_addc_co_u32_e32 v135, vcc, 0, v133, vcc
	global_store_dwordx4 v[134:135], v[128:131], off sc1
	s_mov_b32 s6, 0x18000
	v_mul_f32_e32 v117, v117, v117
	v_cvt_pk_bf16_f32 v128, v80, v81
	v_cvt_pk_bf16_f32 v129, v82, v83
	v_cvt_pk_bf16_f32 v130, v72, v73
	v_cvt_pk_bf16_f32 v131, v74, v75
	global_store_dwordx4 v[134:135], v[128:131], off offset:256 sc1
	v_add_co_u32_e32 v134, vcc, s6, v132
	s_nop 0
	v_cvt_pk_bf16_f32 v128, v84, v85
	v_cvt_pk_bf16_f32 v129, v86, v87
	v_cvt_pk_bf16_f32 v130, v76, v77
	v_cvt_pk_bf16_f32 v131, v78, v79
	v_addc_co_u32_e32 v135, vcc, 0, v133, vcc
	global_store_dwordx4 v[134:135], v[128:131], off sc1
	s_mov_b32 s6, 0x40000
	v_fmac_f32_e32 v125, v124, v124
	v_cvt_pk_bf16_f32 v128, v68, v69
	v_cvt_pk_bf16_f32 v129, v70, v71
	v_cvt_pk_bf16_f32 v130, v64, v65
	v_cvt_pk_bf16_f32 v131, v66, v67
	global_store_dwordx4 v[134:135], v[128:131], off offset:256 sc1
	v_add_co_u32_e32 v134, vcc, s6, v132
	s_nop 0
	v_cvt_pk_bf16_f32 v128, v52, v53
	v_cvt_pk_bf16_f32 v129, v54, v55
	v_cvt_pk_bf16_f32 v130, v40, v41
	v_cvt_pk_bf16_f32 v131, v42, v43
	v_addc_co_u32_e32 v135, vcc, 0, v133, vcc
	global_store_dwordx4 v[134:135], v[128:131], off sc1
	s_mov_b32 s6, 0x48000
	v_mul_f32_e32 v124, v127, v127
	v_cvt_pk_bf16_f32 v128, v20, v21
	v_cvt_pk_bf16_f32 v129, v22, v23
	v_cvt_pk_bf16_f32 v130, v8, v9
	v_cvt_pk_bf16_f32 v131, v10, v11
	global_store_dwordx4 v[134:135], v[128:131], off offset:256 sc1
	v_add_co_u32_e32 v134, vcc, s6, v132
	s_nop 0
	v_cvt_pk_bf16_f32 v128, v28, v29
	v_cvt_pk_bf16_f32 v129, v30, v31
	v_cvt_pk_bf16_f32 v130, v12, v13
	v_cvt_pk_bf16_f32 v131, v14, v15
	v_addc_co_u32_e32 v135, vcc, 0, v133, vcc
	global_store_dwordx4 v[134:135], v[128:131], off sc1
	s_mov_b32 s6, 0x50000
	v_fmac_f32_e32 v117, v116, v116
	v_cvt_pk_bf16_f32 v128, v56, v57
	v_cvt_pk_bf16_f32 v129, v58, v59
	v_cvt_pk_bf16_f32 v130, v44, v45
	v_cvt_pk_bf16_f32 v131, v46, v47
	global_store_dwordx4 v[134:135], v[128:131], off offset:256 sc1
	v_add_co_u32_e32 v134, vcc, s6, v132
	s_nop 0
	v_cvt_pk_bf16_f32 v128, v60, v61
	v_cvt_pk_bf16_f32 v129, v62, v63
	v_cvt_pk_bf16_f32 v130, v48, v49
	v_cvt_pk_bf16_f32 v131, v50, v51
	v_addc_co_u32_e32 v135, vcc, 0, v133, vcc
	global_store_dwordx4 v[134:135], v[128:131], off sc1
	s_mov_b32 s6, 0x58000
	v_mul_f32_e32 v116, v119, v119
	v_cvt_pk_bf16_f32 v128, v32, v33
	v_cvt_pk_bf16_f32 v129, v34, v35
	v_cvt_pk_bf16_f32 v130, v16, v17
	v_cvt_pk_bf16_f32 v131, v18, v19
	global_store_dwordx4 v[134:135], v[128:131], off offset:256 sc1
	v_add_co_u32_e32 v134, vcc, s6, v132
	s_nop 0
	v_cvt_pk_bf16_f32 v128, v36, v37
	v_cvt_pk_bf16_f32 v129, v38, v39
	v_cvt_pk_bf16_f32 v130, v24, v25
	v_cvt_pk_bf16_f32 v131, v26, v27
	v_addc_co_u32_e32 v135, vcc, 0, v133, vcc
	global_store_dwordx4 v[134:135], v[128:131], off sc1
	v_fmac_f32_e32 v124, v126, v126
	v_mul_f32_e32 v121, v121, v121
	v_mbcnt_hi_u32_b32 v129, -1, v178
	v_fmac_f32_e32 v116, v118, v118
	v_mul_f32_e32 v113, v113, v113
	v_and_b32_e32 v136, 64, v129
	v_add_f32_e32 v124, v125, v124
	v_fmac_f32_e32 v121, v120, v120
	v_add_f32_e32 v116, v117, v116
	v_fmac_f32_e32 v113, v112, v112
	v_xor_b32_e32 v128, 16, v129
	v_add_u32_e32 v136, 64, v136
	v_add_f32_e32 v120, v121, v124
	v_mul_f32_e32 v121, v123, v123
	v_add_f32_e32 v112, v113, v116
	v_mul_f32_e32 v113, v115, v115
	v_cmp_lt_i32_e32 vcc, v128, v136
	v_fmac_f32_e32 v121, v122, v122
	v_fmac_f32_e32 v113, v114, v114
	v_cndmask_b32_e32 v128, v129, v128, vcc
	v_add_f32_e32 v120, v121, v120
	v_add_f32_e32 v112, v113, v112
	v_lshlrev_b32_e32 v128, 2, v128
	v_add_f32_e32 v113, v112, v120
	ds_bpermute_b32 v114, v128, v113
	v_xor_b32_e32 v112, 32, v129
	v_cmp_lt_i32_e32 vcc, v112, v136
	s_lshl_b32 s6, s48, 2
	v_cvt_pk_bf16_f32 v130, v4, v5
	v_cndmask_b32_e32 v112, v129, v112, vcc
	v_lshlrev_b32_e32 v112, 2, v112
	s_waitcnt lgkmcnt(0)
	v_add_f32_e32 v113, v113, v114
	ds_bpermute_b32 v114, v112, v113
	v_cvt_pk_bf16_f32 v131, v6, v7
	v_cvt_pk_bf16_f32 v132, v0, v1
	v_cvt_pk_bf16_f32 v133, v2, v3
	v_cmp_gt_u32_e32 vcc, 16, v144
	s_add_i32 s8, s6, 0
	global_store_dwordx4 v[134:135], v[130:133], off offset:256 sc1
	s_and_saveexec_b64 s[6:7], vcc
	s_cbranch_execz .LBB0_412
	s_lshl_b32 s9, s1, 10
	s_add_i32 s9, s8, s9
	v_add_u32_e32 v115, s9, v145
	s_waitcnt lgkmcnt(0)
	v_add_f32_e32 v113, v113, v114
	ds_write_b32 v115, v113

; __device__ __forceinline__ unsigned pk_bf16(float lo, float hi) { f32x2 v = {lo, hi}; return __builtin_bit_cast(unsigned, __builtin_convertvector(v, bf16v2)); }
; __device__ __forceinline__ float fast_sigmoid(float v) { return __builtin_amdgcn_rcpf(1.0f + __builtin_amdgcn_exp2f(-v * LOG2E)); }
;     __device__ __forceinline__ void operator()(const AccT& acc, const Unit& u, int wr, int wc, int fr, int fq) const {
;     ...
;             for (int m = 0; m < 4; ++m) { const int row = row0 + ai * HALF + m * 16; const float rs = rst[row - row_base];
;                 float hv[8];
; #pragma unroll
;                 for (int n = 0; n < 2; ++n)
; #pragma unroll
;                     for (int e = 0; e < 4; ++e) { const float g = acc[ai][0][m][n][e] * rs, uu = acc[ai][1][m][n][e] * rs; hv[4 * n + e] = g * fast_sigmoid(g) * uu; }
;                 u32x4 w; w.x = pk_bf16(hv[0], hv[1]); w.y = pk_bf16(hv[2], hv[3]); w.z = pk_bf16(hv[4], hv[5]); w.w = pk_bf16(hv[6], hv[7]);
;                 *(u32x4*)(hid + (size_t)row * DFF + col0) = w; }
.LBB0_490:
	v_lshl_add_u32 v170, s73, 8, v141
	v_add_u32_e32 v175, 0x90, v170
	v_lshl_add_u32 v138, s8, 7, v161
	s_add_i32 s8, 0, 0x20000
	v_or_b32_e32 v171, 16, v170
	v_or_b32_e32 v172, 32, v170
	v_or_b32_e32 v173, 48, v170
	v_add_u32_e32 v174, 0x80, v170
	v_subrev_u32_e32 v176, s16, v175
	v_add_u32_e32 v179, 0xa0, v170
	v_subrev_u32_e32 v139, s16, v170
	v_subrev_u32_e32 v140, s16, v171
	v_subrev_u32_e32 v142, s16, v172
	v_subrev_u32_e32 v160, s16, v173
	v_subrev_u32_e32 v162, s16, v174
	v_lshl_add_u32 v177, v176, 2, s8
	v_subrev_u32_e32 v176, s16, v179
	v_add_u32_e32 v183, 0xb0, v170
	v_lshl_add_u32 v139, v139, 2, s8
	v_lshl_add_u32 v140, v140, 2, s8
	v_lshl_add_u32 v142, v142, 2, s8
	v_lshl_add_u32 v160, v160, 2, s8
	v_lshl_add_u32 v162, v162, 2, s8
	v_lshl_add_u32 v181, v176, 2, s8
	v_subrev_u32_e32 v176, s16, v183
	v_lshl_add_u32 v184, v176, 2, s8
	ds_read_b32 v176, v139
	ds_read_b32 v178, v140
	ds_read_b32 v180, v142
	ds_read_b32 v182, v160
	ds_read_b32 v162, v162
	ds_read_b32 v160, v177
	ds_read_b32 v142, v181
	ds_read_b32 v140, v184
	s_waitcnt lgkmcnt(0)
	v_pk_mul_f32 v[124:125], v[124:125], v[176:177] op_sel_hi:[1,0]
	v_pk_mul_f32 v[108:109], v[108:109], v[178:179] op_sel_hi:[1,0]
	v_mul_f32_e32 v139, 0xbfb8aa3b, v124
	v_exp_f32_e32 v177, v139
	v_mul_f32_e32 v181, 0xbfb8aa3b, v125
	v_exp_f32_e32 v181, v181
	v_ashrrev_i32_e32 v139, 31, v138
	v_add_f32_e32 v177, 1.0, v177
	v_rcp_f32_e32 v184, v177
	v_pk_mul_f32 v[120:121], v[120:121], v[176:177] op_sel_hi:[1,0]
	v_add_f32_e32 v177, 1.0, v181
	v_pk_mul_f32 v[126:127], v[126:127], v[176:177] op_sel_hi:[1,0]
	v_pk_mul_f32 v[110:111], v[110:111], v[178:179] op_sel_hi:[1,0]
	v_mul_f32_e32 v181, 0xbfb8aa3b, v126
	v_exp_f32_e32 v181, v181
	v_mul_f32_e32 v185, 0xbfb8aa3b, v127
	v_exp_f32_e32 v187, v185
	v_rcp_f32_e32 v185, v177
	v_add_f32_e32 v177, 1.0, v181
	v_rcp_f32_e32 v186, v177
	v_add_f32_e32 v177, 1.0, v187
	v_rcp_f32_e32 v187, v177
	v_pk_mul_f32 v[124:125], v[124:125], v[184:185]
	v_pk_mul_f32 v[116:117], v[116:117], v[176:177] op_sel_hi:[1,0]
	v_pk_mul_f32 v[120:121], v[120:121], v[124:125]
	v_pk_mul_f32 v[124:125], v[126:127], v[186:187]
	v_mul_f32_e32 v126, 0xbfb8aa3b, v116
	v_exp_f32_e32 v126, v126
	v_pk_mul_f32 v[122:123], v[122:123], v[176:177] op_sel_hi:[1,0]
	v_pk_mul_f32 v[118:119], v[118:119], v[176:177] op_sel_hi:[1,0]
	v_pk_mul_f32 v[122:123], v[122:123], v[124:125]
	v_mul_f32_e32 v124, 0xbfb8aa3b, v117
	v_exp_f32_e32 v125, v124
	v_add_f32_e32 v124, 1.0, v126
	v_mul_f32_e32 v126, 0xbfb8aa3b, v118
	v_mul_f32_e32 v127, 0xbfb8aa3b, v119
	v_exp_f32_e32 v126, v126
	v_exp_f32_e32 v127, v127
	v_add_f32_e32 v125, 1.0, v125
	v_rcp_f32_e32 v124, v124
	v_rcp_f32_e32 v125, v125
	v_add_f32_e32 v126, 1.0, v126
	v_add_f32_e32 v127, 1.0, v127
	v_rcp_f32_e32 v126, v126
	v_rcp_f32_e32 v127, v127
	v_pk_mul_f32 v[112:113], v[112:113], v[176:177] op_sel_hi:[1,0]
	v_pk_mul_f32 v[116:117], v[116:117], v[124:125]
	v_pk_mul_f32 v[114:115], v[114:115], v[176:177] op_sel_hi:[1,0]
	v_pk_mul_f32 v[112:113], v[112:113], v[116:117]
	v_pk_mul_f32 v[116:117], v[118:119], v[126:127]
	v_cvt_pk_bf16_f32 v118, v112, v113
	v_pk_mul_f32 v[114:115], v[114:115], v[116:117]
	v_mov_b64_e32 v[112:113], s[96:97]
	v_cvt_pk_bf16_f32 v116, v120, v121
	v_cvt_pk_bf16_f32 v119, v114, v115
	v_mad_i64_i32 v[120:121], s[56:57], v170, s38, v[112:113]
	v_lshlrev_b64 v[114:115], 1, v[138:139]
	v_cvt_pk_bf16_f32 v117, v122, v123
	v_lshl_add_u64 v[120:121], v[120:121], 0, v[114:115]
	v_mul_f32_e32 v122, 0xbfb8aa3b, v108
	global_store_dwordx4 v[120:121], v[116:119], off sc1
	v_exp_f32_e32 v122, v122
	v_pk_mul_f32 v[104:105], v[104:105], v[178:179] op_sel_hi:[1,0]
	v_mul_f32_e32 v116, 0xbfb8aa3b, v109
	v_exp_f32_e32 v117, v116
	v_mul_f32_e32 v118, 0xbfb8aa3b, v110
	v_mul_f32_e32 v119, 0xbfb8aa3b, v111
	v_exp_f32_e32 v118, v118
	v_exp_f32_e32 v119, v119
	v_add_f32_e32 v116, 1.0, v122
	v_add_f32_e32 v117, 1.0, v117
	v_rcp_f32_e32 v116, v116
	v_rcp_f32_e32 v117, v117
	v_add_f32_e32 v118, 1.0, v118
	v_add_f32_e32 v119, 1.0, v119
	v_rcp_f32_e32 v118, v118
	v_rcp_f32_e32 v119, v119
	v_pk_mul_f32 v[108:109], v[108:109], v[116:117]
	v_pk_mul_f32 v[100:101], v[100:101], v[178:179] op_sel_hi:[1,0]
	v_pk_mul_f32 v[104:105], v[104:105], v[108:109]
	v_pk_mul_f32 v[108:109], v[110:111], v[118:119]
	v_mul_f32_e32 v110, 0xbfb8aa3b, v100
	v_exp_f32_e32 v110, v110
	v_pk_mul_f32 v[106:107], v[106:107], v[178:179] op_sel_hi:[1,0]
	v_pk_mul_f32 v[102:103], v[102:103], v[178:179] op_sel_hi:[1,0]
	v_pk_mul_f32 v[106:107], v[106:107], v[108:109]
	v_mul_f32_e32 v108, 0xbfb8aa3b, v101
	v_exp_f32_e32 v109, v108
	v_add_f32_e32 v108, 1.0, v110
	v_mul_f32_e32 v110, 0xbfb8aa3b, v102
	v_mul_f32_e32 v111, 0xbfb8aa3b, v103
	v_exp_f32_e32 v110, v110
	v_exp_f32_e32 v111, v111
	v_add_f32_e32 v109, 1.0, v109
	v_rcp_f32_e32 v108, v108
	v_rcp_f32_e32 v109, v109
	v_add_f32_e32 v110, 1.0, v110
	v_add_f32_e32 v111, 1.0, v111
	v_rcp_f32_e32 v110, v110
	v_rcp_f32_e32 v111, v111
	v_pk_mul_f32 v[96:97], v[96:97], v[178:179] op_sel_hi:[1,0]
	v_pk_mul_f32 v[100:101], v[100:101], v[108:109]
	v_pk_mul_f32 v[92:93], v[92:93], v[180:181] op_sel_hi:[1,0]
	v_pk_mul_f32 v[100:101], v[96:97], v[100:101]
	v_pk_mul_f32 v[96:97], v[98:99], v[178:179] op_sel_hi:[1,0]
	v_pk_mul_f32 v[98:99], v[102:103], v[110:111]
	v_pk_mul_f32 v[94:95], v[94:95], v[180:181] op_sel_hi:[1,0]
	v_pk_mul_f32 v[102:103], v[96:97], v[98:99]
	v_cvt_pk_bf16_f32 v98, v100, v101
	v_mad_i64_i32 v[100:101], s[56:57], v171, s38, v[112:113]
	v_cvt_pk_bf16_f32 v96, v104, v105
	v_cvt_pk_bf16_f32 v97, v106, v107
	v_cvt_pk_bf16_f32 v99, v102, v103
	v_lshl_add_u64 v[100:101], v[100:101], 0, v[114:115]
	v_mul_f32_e32 v102, 0xbfb8aa3b, v92
; __device__ __forceinline__ unsigned pk_bf16(float lo, float hi) { f32x2 v = {lo, hi}; return __builtin_bit_cast(unsigned, __builtin_convertvector(v, bf16v2)); }
; __device__ __forceinline__ float fast_sigmoid(float v) { return __builtin_amdgcn_rcpf(1.0f + __builtin_amdgcn_exp2f(-v * LOG2E)); }
;     __device__ __forceinline__ void operator()(const AccT& acc, const Unit& u, int wr, int wc, int fr, int fq) const {
;     ...
;             for (int m = 0; m < 4; ++m) { const int row = row0 + ai * HALF + m * 16; const float rs = rst[row - row_base];
;                 float hv[8];
; #pragma unroll
;                 for (int n = 0; n < 2; ++n)
; #pragma unroll
;                     for (int e = 0; e < 4; ++e) { const float g = acc[ai][0][m][n][e] * rs, uu = acc[ai][1][m][n][e] * rs; hv[4 * n + e] = g * fast_sigmoid(g) * uu; }
;                 u32x4 w; w.x = pk_bf16(hv[0], hv[1]); w.y = pk_bf16(hv[2], hv[3]); w.z = pk_bf16(hv[4], hv[5]); w.w = pk_bf16(hv[6], hv[7]);
;                 *(u32x4*)(hid + (size_t)row * DFF + col0) = w; }
	global_store_dwordx4 v[100:101], v[96:99], off sc1
	v_exp_f32_e32 v102, v102
	v_pk_mul_f32 v[88:89], v[88:89], v[180:181] op_sel_hi:[1,0]
	v_mul_f32_e32 v96, 0xbfb8aa3b, v93
	v_exp_f32_e32 v97, v96
	v_mul_f32_e32 v98, 0xbfb8aa3b, v94
	v_mul_f32_e32 v99, 0xbfb8aa3b, v95
	v_exp_f32_e32 v98, v98
	v_exp_f32_e32 v99, v99
	v_add_f32_e32 v96, 1.0, v102
	v_add_f32_e32 v97, 1.0, v97
	v_rcp_f32_e32 v96, v96
	v_rcp_f32_e32 v97, v97
	v_add_f32_e32 v98, 1.0, v98
	v_add_f32_e32 v99, 1.0, v99
	v_rcp_f32_e32 v98, v98
	v_rcp_f32_e32 v99, v99
	v_pk_mul_f32 v[92:93], v[92:93], v[96:97]
	v_pk_mul_f32 v[84:85], v[84:85], v[180:181] op_sel_hi:[1,0]
	v_pk_mul_f32 v[88:89], v[88:89], v[92:93]
	v_pk_mul_f32 v[92:93], v[94:95], v[98:99]
	v_mul_f32_e32 v94, 0xbfb8aa3b, v84
	v_exp_f32_e32 v94, v94
	v_pk_mul_f32 v[90:91], v[90:91], v[180:181] op_sel_hi:[1,0]
	v_pk_mul_f32 v[86:87], v[86:87], v[180:181] op_sel_hi:[1,0]
	v_pk_mul_f32 v[90:91], v[90:91], v[92:93]
	v_mul_f32_e32 v92, 0xbfb8aa3b, v85
	v_exp_f32_e32 v93, v92
	v_add_f32_e32 v92, 1.0, v94
	v_mul_f32_e32 v94, 0xbfb8aa3b, v86
	v_mul_f32_e32 v95, 0xbfb8aa3b, v87
	v_exp_f32_e32 v94, v94
	v_exp_f32_e32 v95, v95
	v_add_f32_e32 v93, 1.0, v93
	v_rcp_f32_e32 v92, v92
	v_rcp_f32_e32 v93, v93
	v_add_f32_e32 v94, 1.0, v94
	v_add_f32_e32 v95, 1.0, v95
	v_rcp_f32_e32 v94, v94
	v_rcp_f32_e32 v95, v95
	v_pk_mul_f32 v[80:81], v[80:81], v[180:181] op_sel_hi:[1,0]
	v_pk_mul_f32 v[84:85], v[84:85], v[92:93]
	v_pk_mul_f32 v[76:77], v[76:77], v[182:183] op_sel_hi:[1,0]
	v_pk_mul_f32 v[84:85], v[80:81], v[84:85]
	v_pk_mul_f32 v[80:81], v[82:83], v[180:181] op_sel_hi:[1,0]
	v_pk_mul_f32 v[82:83], v[86:87], v[94:95]
	v_pk_mul_f32 v[78:79], v[78:79], v[182:183] op_sel_hi:[1,0]
	v_pk_mul_f32 v[86:87], v[80:81], v[82:83]
	v_cvt_pk_bf16_f32 v82, v84, v85
	v_mad_i64_i32 v[84:85], s[56:57], v172, s38, v[112:113]
	v_cvt_pk_bf16_f32 v80, v88, v89
	v_cvt_pk_bf16_f32 v81, v90, v91
	v_cvt_pk_bf16_f32 v83, v86, v87
	v_lshl_add_u64 v[84:85], v[84:85], 0, v[114:115]
	v_mul_f32_e32 v86, 0xbfb8aa3b, v76
	global_store_dwordx4 v[84:85], v[80:83], off sc1
	v_exp_f32_e32 v86, v86
	v_pk_mul_f32 v[72:73], v[72:73], v[182:183] op_sel_hi:[1,0]
	v_mul_f32_e32 v80, 0xbfb8aa3b, v77
	v_exp_f32_e32 v81, v80
	v_mul_f32_e32 v82, 0xbfb8aa3b, v78
	v_mul_f32_e32 v83, 0xbfb8aa3b, v79
	v_exp_f32_e32 v82, v82
	v_exp_f32_e32 v83, v83
	v_add_f32_e32 v80, 1.0, v86
	v_add_f32_e32 v81, 1.0, v81
	v_rcp_f32_e32 v80, v80
	v_rcp_f32_e32 v81, v81
	v_add_f32_e32 v82, 1.0, v82
	v_add_f32_e32 v83, 1.0, v83
	v_rcp_f32_e32 v82, v82
	v_rcp_f32_e32 v83, v83
	v_pk_mul_f32 v[76:77], v[76:77], v[80:81]
	v_pk_mul_f32 v[68:69], v[68:69], v[182:183] op_sel_hi:[1,0]
	v_pk_mul_f32 v[72:73], v[72:73], v[76:77]
	v_pk_mul_f32 v[76:77], v[78:79], v[82:83]
	v_mul_f32_e32 v78, 0xbfb8aa3b, v68
	v_exp_f32_e32 v78, v78
	v_pk_mul_f32 v[74:75], v[74:75], v[182:183] op_sel_hi:[1,0]
	v_pk_mul_f32 v[70:71], v[70:71], v[182:183] op_sel_hi:[1,0]
	v_pk_mul_f32 v[74:75], v[74:75], v[76:77]
	v_mul_f32_e32 v76, 0xbfb8aa3b, v69
	v_exp_f32_e32 v77, v76
	v_add_f32_e32 v76, 1.0, v78
	v_mul_f32_e32 v78, 0xbfb8aa3b, v70
	v_mul_f32_e32 v79, 0xbfb8aa3b, v71
	v_exp_f32_e32 v78, v78
	v_exp_f32_e32 v79, v79
	v_add_f32_e32 v77, 1.0, v77
	v_rcp_f32_e32 v76, v76
	v_rcp_f32_e32 v77, v77
	v_add_f32_e32 v78, 1.0, v78
	v_add_f32_e32 v79, 1.0, v79
	v_rcp_f32_e32 v78, v78
	v_rcp_f32_e32 v79, v79
	v_pk_mul_f32 v[64:65], v[64:65], v[182:183] op_sel_hi:[1,0]
	v_pk_mul_f32 v[68:69], v[68:69], v[76:77]
	v_pk_mul_f32 v[60:61], v[60:61], v[162:163] op_sel_hi:[1,0]
	v_pk_mul_f32 v[68:69], v[64:65], v[68:69]
	v_pk_mul_f32 v[64:65], v[66:67], v[182:183] op_sel_hi:[1,0]
	v_pk_mul_f32 v[66:67], v[70:71], v[78:79]
	v_pk_mul_f32 v[62:63], v[62:63], v[162:163] op_sel_hi:[1,0]
	v_pk_mul_f32 v[70:71], v[64:65], v[66:67]
	v_cvt_pk_bf16_f32 v66, v68, v69
	v_mad_i64_i32 v[68:69], s[56:57], v173, s38, v[112:113]
	v_cvt_pk_bf16_f32 v64, v72, v73
	v_cvt_pk_bf16_f32 v65, v74, v75
	v_cvt_pk_bf16_f32 v67, v70, v71
	v_lshl_add_u64 v[68:69], v[68:69], 0, v[114:115]
	v_mul_f32_e32 v70, 0xbfb8aa3b, v60
	global_store_dwordx4 v[68:69], v[64:67], off sc1
	v_exp_f32_e32 v70, v70
	v_pk_mul_f32 v[56:57], v[56:57], v[162:163] op_sel_hi:[1,0]
	v_mul_f32_e32 v64, 0xbfb8aa3b, v61
	v_exp_f32_e32 v65, v64
	v_mul_f32_e32 v66, 0xbfb8aa3b, v62
	v_mul_f32_e32 v67, 0xbfb8aa3b, v63
	v_exp_f32_e32 v66, v66
	v_exp_f32_e32 v67, v67
	v_add_f32_e32 v64, 1.0, v70
	v_add_f32_e32 v65, 1.0, v65
	v_rcp_f32_e32 v64, v64
	v_rcp_f32_e32 v65, v65
	v_add_f32_e32 v66, 1.0, v66
	v_add_f32_e32 v67, 1.0, v67
	v_rcp_f32_e32 v66, v66
	v_rcp_f32_e32 v67, v67
	v_pk_mul_f32 v[60:61], v[60:61], v[64:65]
	v_pk_mul_f32 v[52:53], v[52:53], v[162:163] op_sel_hi:[1,0]
	v_pk_mul_f32 v[56:57], v[56:57], v[60:61]
	v_pk_mul_f32 v[60:61], v[62:63], v[66:67]
	v_mul_f32_e32 v62, 0xbfb8aa3b, v52
	v_exp_f32_e32 v62, v62
	v_pk_mul_f32 v[58:59], v[58:59], v[162:163] op_sel_hi:[1,0]
	v_pk_mul_f32 v[54:55], v[54:55], v[162:163] op_sel_hi:[1,0]
	v_pk_mul_f32 v[58:59], v[58:59], v[60:61]
	v_mul_f32_e32 v60, 0xbfb8aa3b, v53
	v_exp_f32_e32 v61, v60
	v_add_f32_e32 v60, 1.0, v62
	v_mul_f32_e32 v62, 0xbfb8aa3b, v54
	v_mul_f32_e32 v63, 0xbfb8aa3b, v55
	v_exp_f32_e32 v62, v62
	v_exp_f32_e32 v63, v63
	v_add_f32_e32 v61, 1.0, v61
	v_rcp_f32_e32 v60, v60
	v_rcp_f32_e32 v61, v61
	v_add_f32_e32 v62, 1.0, v62
	v_add_f32_e32 v63, 1.0, v63
	v_rcp_f32_e32 v62, v62
	v_rcp_f32_e32 v63, v63
	v_pk_mul_f32 v[48:49], v[48:49], v[162:163] op_sel_hi:[1,0]
	v_pk_mul_f32 v[52:53], v[52:53], v[60:61]
	v_pk_mul_f32 v[44:45], v[44:45], v[160:161] op_sel_hi:[1,0]
	v_pk_mul_f32 v[52:53], v[48:49], v[52:53]
	v_pk_mul_f32 v[48:49], v[50:51], v[162:163] op_sel_hi:[1,0]
; __device__ __forceinline__ unsigned pk_bf16(float lo, float hi) { f32x2 v = {lo, hi}; return __builtin_bit_cast(unsigned, __builtin_convertvector(v, bf16v2)); }
; __device__ __forceinline__ float fast_sigmoid(float v) { return __builtin_amdgcn_rcpf(1.0f + __builtin_amdgcn_exp2f(-v * LOG2E)); }
; #define PG8_BAR __builtin_amdgcn_s_barrier()
;     __device__ __forceinline__ void operator()(const AccT& acc, const Unit& u, int wr, int wc, int fr, int fq) const {
;     ...
;             for (int m = 0; m < 4; ++m) { const int row = row0 + ai * HALF + m * 16; const float rs = rst[row - row_base];
;                 float hv[8];
; #pragma unroll
;                 for (int n = 0; n < 2; ++n)
; #pragma unroll
;                     for (int e = 0; e < 4; ++e) { const float g = acc[ai][0][m][n][e] * rs, uu = acc[ai][1][m][n][e] * rs; hv[4 * n + e] = g * fast_sigmoid(g) * uu; }
;                 u32x4 w; w.x = pk_bf16(hv[0], hv[1]); w.y = pk_bf16(hv[2], hv[3]); w.z = pk_bf16(hv[4], hv[5]); w.w = pk_bf16(hv[6], hv[7]);
;                 *(u32x4*)(hid + (size_t)row * DFF + col0) = w; }
; template <class Epi, class Sched, bool ALIGN_EPI = false, bool SP2 = false>
; __device__ __forceinline__ void gemm_phase(PG8_LAS unsigned char* lds, const Gemm g, const Sched& S, const Epi& E, const int wid) {
;     ...
;         if constexpr (ALIGN_EPI) { if (wr == 0) PG8_BAR; }
;         if constexpr (!Epi::AFTER_DRAIN) { E(acc, cur, wr, wc, fr, fq); S.done(cur); }
;         if (!has_next) break;
; #pragma unroll
;         for (int a = 0; a < 2; ++a)
; #pragma unroll
;             for (int b = 0; b < 2; ++b)
; #pragma unroll
;                 for (int m = 0; m < 4; ++m)
; #pragma unroll
;                     for (int n = 0; n < 2; ++n) acc[a][b][m][n] = (f32x4){0.f, 0.f, 0.f, 0.f};
;         cur = nxt; cA = nA; cB = nB; ++ui;
;         if constexpr (ALIGN_EPI) { if (wr == 1) PG8_BAR; }
	v_pk_mul_f32 v[50:51], v[54:55], v[62:63]
	v_pk_mul_f32 v[46:47], v[46:47], v[160:161] op_sel_hi:[1,0]
	v_pk_mul_f32 v[54:55], v[48:49], v[50:51]
	v_cvt_pk_bf16_f32 v50, v52, v53
	v_mad_i64_i32 v[52:53], s[56:57], v174, s38, v[112:113]
	v_cvt_pk_bf16_f32 v48, v56, v57
	v_cvt_pk_bf16_f32 v49, v58, v59
	v_cvt_pk_bf16_f32 v51, v54, v55
	v_lshl_add_u64 v[52:53], v[52:53], 0, v[114:115]
	v_mul_f32_e32 v54, 0xbfb8aa3b, v44
	global_store_dwordx4 v[52:53], v[48:51], off sc1
	v_exp_f32_e32 v54, v54
	v_pk_mul_f32 v[40:41], v[40:41], v[160:161] op_sel_hi:[1,0]
	v_mul_f32_e32 v48, 0xbfb8aa3b, v45
	v_exp_f32_e32 v49, v48
	v_mul_f32_e32 v50, 0xbfb8aa3b, v46
	v_mul_f32_e32 v51, 0xbfb8aa3b, v47
	v_exp_f32_e32 v50, v50
	v_exp_f32_e32 v51, v51
	v_add_f32_e32 v48, 1.0, v54
	v_add_f32_e32 v49, 1.0, v49
	v_rcp_f32_e32 v48, v48
	v_rcp_f32_e32 v49, v49
	v_add_f32_e32 v50, 1.0, v50
	v_add_f32_e32 v51, 1.0, v51
	v_rcp_f32_e32 v50, v50
	v_rcp_f32_e32 v51, v51
	v_pk_mul_f32 v[44:45], v[44:45], v[48:49]
	v_pk_mul_f32 v[36:37], v[36:37], v[160:161] op_sel_hi:[1,0]
	v_pk_mul_f32 v[40:41], v[40:41], v[44:45]
	v_pk_mul_f32 v[44:45], v[46:47], v[50:51]
	v_mul_f32_e32 v46, 0xbfb8aa3b, v36
	v_exp_f32_e32 v46, v46
	v_pk_mul_f32 v[42:43], v[42:43], v[160:161] op_sel_hi:[1,0]
	v_pk_mul_f32 v[38:39], v[38:39], v[160:161] op_sel_hi:[1,0]
	v_pk_mul_f32 v[42:43], v[42:43], v[44:45]
	v_mul_f32_e32 v44, 0xbfb8aa3b, v37
	v_exp_f32_e32 v45, v44
	v_add_f32_e32 v44, 1.0, v46
	v_mul_f32_e32 v46, 0xbfb8aa3b, v38
	v_mul_f32_e32 v47, 0xbfb8aa3b, v39
	v_exp_f32_e32 v46, v46
	v_exp_f32_e32 v47, v47
	v_add_f32_e32 v45, 1.0, v45
	v_rcp_f32_e32 v44, v44
	v_rcp_f32_e32 v45, v45
	v_add_f32_e32 v46, 1.0, v46
	v_add_f32_e32 v47, 1.0, v47
	v_rcp_f32_e32 v46, v46
	v_rcp_f32_e32 v47, v47
	v_pk_mul_f32 v[32:33], v[32:33], v[160:161] op_sel_hi:[1,0]
	v_pk_mul_f32 v[36:37], v[36:37], v[44:45]
	v_pk_mul_f32 v[28:29], v[28:29], v[142:143] op_sel_hi:[1,0]
	v_pk_mul_f32 v[36:37], v[32:33], v[36:37]
	v_pk_mul_f32 v[32:33], v[34:35], v[160:161] op_sel_hi:[1,0]
	v_pk_mul_f32 v[34:35], v[38:39], v[46:47]
	v_pk_mul_f32 v[30:31], v[30:31], v[142:143] op_sel_hi:[1,0]
	v_pk_mul_f32 v[38:39], v[32:33], v[34:35]
	v_cvt_pk_bf16_f32 v34, v36, v37
	v_mad_i64_i32 v[36:37], s[56:57], v175, s38, v[112:113]
	v_cvt_pk_bf16_f32 v32, v40, v41
	v_cvt_pk_bf16_f32 v33, v42, v43
	v_cvt_pk_bf16_f32 v35, v38, v39
	v_lshl_add_u64 v[36:37], v[36:37], 0, v[114:115]
	v_mul_f32_e32 v38, 0xbfb8aa3b, v28
	global_store_dwordx4 v[36:37], v[32:35], off sc1
	v_exp_f32_e32 v38, v38
	v_pk_mul_f32 v[24:25], v[24:25], v[142:143] op_sel_hi:[1,0]
	v_mul_f32_e32 v32, 0xbfb8aa3b, v29
	v_exp_f32_e32 v33, v32
	v_mul_f32_e32 v34, 0xbfb8aa3b, v30
	v_mul_f32_e32 v35, 0xbfb8aa3b, v31
	v_exp_f32_e32 v34, v34
	v_exp_f32_e32 v35, v35
	v_add_f32_e32 v32, 1.0, v38
	v_add_f32_e32 v33, 1.0, v33
	v_rcp_f32_e32 v32, v32
	v_rcp_f32_e32 v33, v33
	v_add_f32_e32 v34, 1.0, v34
	v_add_f32_e32 v35, 1.0, v35
	v_rcp_f32_e32 v34, v34
	v_rcp_f32_e32 v35, v35
	v_pk_mul_f32 v[28:29], v[28:29], v[32:33]
	v_pk_mul_f32 v[20:21], v[20:21], v[142:143] op_sel_hi:[1,0]
	v_pk_mul_f32 v[24:25], v[24:25], v[28:29]
	v_pk_mul_f32 v[28:29], v[30:31], v[34:35]
	v_mul_f32_e32 v30, 0xbfb8aa3b, v20
	v_exp_f32_e32 v30, v30
	v_pk_mul_f32 v[26:27], v[26:27], v[142:143] op_sel_hi:[1,0]
	v_pk_mul_f32 v[22:23], v[22:23], v[142:143] op_sel_hi:[1,0]
	v_pk_mul_f32 v[26:27], v[26:27], v[28:29]
	v_mul_f32_e32 v28, 0xbfb8aa3b, v21
	v_exp_f32_e32 v29, v28
	v_add_f32_e32 v28, 1.0, v30
	v_mul_f32_e32 v30, 0xbfb8aa3b, v22
	v_mul_f32_e32 v31, 0xbfb8aa3b, v23
	v_exp_f32_e32 v30, v30
	v_exp_f32_e32 v31, v31
	v_add_f32_e32 v29, 1.0, v29
	v_rcp_f32_e32 v28, v28
	v_rcp_f32_e32 v29, v29
	v_add_f32_e32 v30, 1.0, v30
	v_add_f32_e32 v31, 1.0, v31
	v_rcp_f32_e32 v30, v30
	v_rcp_f32_e32 v31, v31
	v_pk_mul_f32 v[16:17], v[16:17], v[142:143] op_sel_hi:[1,0]
	v_pk_mul_f32 v[20:21], v[20:21], v[28:29]
	v_pk_mul_f32 v[12:13], v[12:13], v[140:141] op_sel_hi:[1,0]
	v_pk_mul_f32 v[20:21], v[16:17], v[20:21]
	v_pk_mul_f32 v[16:17], v[18:19], v[142:143] op_sel_hi:[1,0]
	v_pk_mul_f32 v[18:19], v[22:23], v[30:31]
	v_pk_mul_f32 v[14:15], v[14:15], v[140:141] op_sel_hi:[1,0]
	v_pk_mul_f32 v[22:23], v[16:17], v[18:19]
	v_cvt_pk_bf16_f32 v18, v20, v21
	v_mad_i64_i32 v[20:21], s[56:57], v179, s38, v[112:113]
	v_cvt_pk_bf16_f32 v16, v24, v25
	v_cvt_pk_bf16_f32 v17, v26, v27
	v_cvt_pk_bf16_f32 v19, v22, v23
	v_lshl_add_u64 v[20:21], v[20:21], 0, v[114:115]
	v_mul_f32_e32 v22, 0xbfb8aa3b, v12
	global_store_dwordx4 v[20:21], v[16:19], off sc1
	v_exp_f32_e32 v22, v22
	v_pk_mul_f32 v[8:9], v[8:9], v[140:141] op_sel_hi:[1,0]
	v_mul_f32_e32 v16, 0xbfb8aa3b, v13
	v_exp_f32_e32 v17, v16
	v_mul_f32_e32 v18, 0xbfb8aa3b, v14
	v_mul_f32_e32 v19, 0xbfb8aa3b, v15
	v_exp_f32_e32 v18, v18
	v_exp_f32_e32 v19, v19
	v_add_f32_e32 v16, 1.0, v22
	v_add_f32_e32 v17, 1.0, v17
	v_rcp_f32_e32 v16, v16
	v_rcp_f32_e32 v17, v17
	v_add_f32_e32 v18, 1.0, v18
	v_add_f32_e32 v19, 1.0, v19
	v_rcp_f32_e32 v18, v18
	v_rcp_f32_e32 v19, v19
	v_pk_mul_f32 v[12:13], v[12:13], v[16:17]
	v_pk_mul_f32 v[4:5], v[4:5], v[140:141] op_sel_hi:[1,0]
	v_pk_mul_f32 v[8:9], v[8:9], v[12:13]
	v_pk_mul_f32 v[12:13], v[14:15], v[18:19]
	v_mul_f32_e32 v14, 0xbfb8aa3b, v4
	v_exp_f32_e32 v14, v14
	v_pk_mul_f32 v[10:11], v[10:11], v[140:141] op_sel_hi:[1,0]
	v_pk_mul_f32 v[6:7], v[6:7], v[140:141] op_sel_hi:[1,0]
	v_pk_mul_f32 v[10:11], v[10:11], v[12:13]
	v_mul_f32_e32 v12, 0xbfb8aa3b, v5
	v_exp_f32_e32 v13, v12
	v_add_f32_e32 v12, 1.0, v14
	v_mul_f32_e32 v14, 0xbfb8aa3b, v6
	v_mul_f32_e32 v15, 0xbfb8aa3b, v7
	v_exp_f32_e32 v14, v14
	v_exp_f32_e32 v15, v15
	v_add_f32_e32 v13, 1.0, v13
	v_rcp_f32_e32 v12, v12
	v_rcp_f32_e32 v13, v13
	v_add_f32_e32 v14, 1.0, v14
	v_add_f32_e32 v15, 1.0, v15
	v_rcp_f32_e32 v14, v14
	v_rcp_f32_e32 v15, v15
	v_pk_mul_f32 v[0:1], v[0:1], v[140:141] op_sel_hi:[1,0]
	v_pk_mul_f32 v[4:5], v[4:5], v[12:13]
	s_andn2_b64 vcc, exec, s[44:45]
	v_pk_mul_f32 v[4:5], v[0:1], v[4:5]
	v_pk_mul_f32 v[0:1], v[2:3], v[140:141] op_sel_hi:[1,0]
	v_pk_mul_f32 v[2:3], v[6:7], v[14:15]
	s_mov_b64 s[44:45], -1
	v_pk_mul_f32 v[6:7], v[0:1], v[2:3]
	v_cvt_pk_bf16_f32 v2, v4, v5
	v_mad_i64_i32 v[4:5], s[56:57], v183, s38, v[112:113]
	v_cvt_pk_bf16_f32 v0, v8, v9
	v_cvt_pk_bf16_f32 v1, v10, v11
	v_cvt_pk_bf16_f32 v3, v6, v7
	v_lshl_add_u64 v[4:5], v[4:5], 0, v[114:115]
	global_store_dwordx4 v[4:5], v[0:3], off sc1
	s_cbranch_vccnz .LBB0_482
	s_and_b64 vcc, exec, s[42:43]
	s_cbranch_vccnz .LBB0_481
	s_barrier
	s_branch .LBB0_481

; #define LAS __attribute__((address_space(3)))
; __device__ __forceinline__ void transpose_item(const float* W, int K, int N, bf16_t* WT, int mode, int rowoff, const float* g, LAS float* scr, int item, int lane) {
;     const int nblk = N / 32, kb = item / nblk, nb = item % nblk, k0 = 64 * kb, n0 = 32 * nb;
;     const int drow0 = rowoff + (mode ? 256 * (n0 >> 7) + (n0 & 127) : n0);
;     float tv[32];
;     const float* wp = W + (size_t)(k0 + (lane >> 5)) * N + n0 + (lane & 31);
; #pragma unroll
;     for (int i = 0; i < 32; ++i) tv[i] = __builtin_nontemporal_load(wp + (size_t)(2 * i) * N);
; template <int SET>
; __device__ __forceinline__ void convert_weights(const Params& p, LAS unsigned char* lds, int gw, int ngw, int wave, int lane) {
;     ...
;         for (int it = gw; it < I_DN; it += ngw) transpose_item(p.in[16] + (size_t)DM * DFF, DFF, DM, (bf16_t*)(ws + WS_WD1), 0, 0, nullptr, scr, it, lane);
.LBB0_500:
	s_ashr_i32 s4, s43, 31
	s_lshr_b32 s4, s4, 27
	s_add_i32 s4, s43, s4
	s_ashr_i32 s4, s4, 5
	s_lshl_b32 s10, s4, 6
	v_add_u32_e32 v2, s10, v4
	s_lshl_b32 s4, s4, 10
	v_ashrrev_i32_e32 v3, 31, v2
	s_sub_i32 s4, s8, s4
	v_lshlrev_b64 v[2:3], 12, v[2:3]
	v_lshl_add_u64 v[2:3], s[68:69], 0, v[2:3]
	s_ashr_i32 s5, s4, 31
	v_lshl_add_u64 v[2:3], s[4:5], 2, v[2:3]
	v_lshl_add_u64 v[2:3], v[2:3], 0, v[146:147]
	v_add_co_u32_e32 v8, vcc, s67, v2
	global_load_dword v10, v[2:3], off nt
	s_nop 0
	v_addc_co_u32_e32 v9, vcc, 0, v3, vcc
	global_load_dword v11, v[8:9], off nt
	v_add_co_u32_e32 v8, vcc, s65, v2
	s_ashr_i32 s11, s10, 31
	s_nop 0
	v_addc_co_u32_e32 v9, vcc, 0, v3, vcc
	global_load_dword v12, v[8:9], off nt
	v_add_co_u32_e32 v8, vcc, s50, v2
	s_add_i32 s43, s43, s23
	s_nop 0
	v_addc_co_u32_e32 v9, vcc, 0, v3, vcc
	global_load_dword v13, v[8:9], off nt
	v_add_co_u32_e32 v8, vcc, s39, v2
	s_add_i32 s8, s8, s42
	s_nop 0
	v_addc_co_u32_e32 v9, vcc, 0, v3, vcc
	global_load_dword v14, v[8:9], off nt
	v_add_co_u32_e32 v8, vcc, s71, v2
	s_cmpk_lt_i32 s43, 0x580
	s_nop 0
	v_addc_co_u32_e32 v9, vcc, 0, v3, vcc
	global_load_dword v15, v[8:9], off nt
	v_add_co_u32_e32 v8, vcc, s75, v2
	s_nop 1
	v_addc_co_u32_e32 v9, vcc, 0, v3, vcc
	global_load_dword v16, v[8:9], off nt
	v_add_co_u32_e32 v8, vcc, s63, v2
	s_nop 1
	v_addc_co_u32_e32 v9, vcc, 0, v3, vcc
	global_load_dword v17, v[8:9], off nt
	v_add_co_u32_e32 v8, vcc, s52, v2
	s_nop 1
	v_addc_co_u32_e32 v9, vcc, 0, v3, vcc
	global_load_dword v18, v[8:9], off nt
	v_add_co_u32_e32 v8, vcc, s54, v2
	s_nop 1
	v_addc_co_u32_e32 v9, vcc, 0, v3, vcc
	global_load_dword v19, v[8:9], off nt
	v_add_co_u32_e32 v8, vcc, s55, v2
	s_nop 1
	v_addc_co_u32_e32 v9, vcc, 0, v3, vcc
	global_load_dword v20, v[8:9], off nt
	v_add_co_u32_e32 v8, vcc, s64, v2
	s_nop 1
	v_addc_co_u32_e32 v9, vcc, 0, v3, vcc
	global_load_dword v21, v[8:9], off nt
	v_add_co_u32_e32 v8, vcc, s73, v2
	s_nop 1
	v_addc_co_u32_e32 v9, vcc, 0, v3, vcc
	global_load_dword v22, v[8:9], off nt
	v_add_co_u32_e32 v8, vcc, s70, v2
	s_nop 1
	v_addc_co_u32_e32 v9, vcc, 0, v3, vcc
	global_load_dword v23, v[8:9], off nt
	v_add_co_u32_e32 v8, vcc, s53, v2
	s_nop 1
	v_addc_co_u32_e32 v9, vcc, 0, v3, vcc
	global_load_dword v24, v[8:9], off nt
	v_add_co_u32_e32 v8, vcc, s74, v2
	s_nop 1
	v_addc_co_u32_e32 v9, vcc, 0, v3, vcc
	global_load_dword v25, v[8:9], off nt
	v_add_co_u32_e32 v8, vcc, s66, v2
	s_nop 1
	v_addc_co_u32_e32 v9, vcc, 0, v3, vcc
	global_load_dword v26, v[8:9], off nt
	v_add_co_u32_e32 v8, vcc, s62, v2
	s_nop 1
	v_addc_co_u32_e32 v9, vcc, 0, v3, vcc
	global_load_dword v27, v[8:9], off nt
	v_add_co_u32_e32 v8, vcc, s82, v2
	s_nop 1
	v_addc_co_u32_e32 v9, vcc, 0, v3, vcc
	global_load_dword v28, v[8:9], off nt
	v_add_co_u32_e32 v8, vcc, s83, v2
	s_nop 1
	v_addc_co_u32_e32 v9, vcc, 0, v3, vcc
	global_load_dword v29, v[8:9], off nt
	v_add_co_u32_e32 v8, vcc, s59, v2
	s_nop 1
	v_addc_co_u32_e32 v9, vcc, 0, v3, vcc
	global_load_dword v30, v[8:9], off nt
	v_add_co_u32_e32 v8, vcc, s58, v2
	s_nop 1
	v_addc_co_u32_e32 v9, vcc, 0, v3, vcc
	global_load_dword v31, v[8:9], off nt
	v_add_co_u32_e32 v8, vcc, s61, v2
	s_nop 1
	v_addc_co_u32_e32 v9, vcc, 0, v3, vcc
	global_load_dword v32, v[8:9], off nt
	v_add_co_u32_e32 v8, vcc, s51, v2
	s_nop 1
	v_addc_co_u32_e32 v9, vcc, 0, v3, vcc
	global_load_dword v33, v[8:9], off nt
	v_add_co_u32_e32 v8, vcc, s44, v2
	s_nop 1
	v_addc_co_u32_e32 v9, vcc, 0, v3, vcc
	global_load_dword v34, v[8:9], off nt
	v_add_co_u32_e32 v8, vcc, s60, v2
	s_nop 1
	v_addc_co_u32_e32 v9, vcc, 0, v3, vcc
	global_load_dword v35, v[8:9], off nt
	v_add_co_u32_e32 v8, vcc, s56, v2
	s_nop 1
	v_addc_co_u32_e32 v9, vcc, 0, v3, vcc
	global_load_dword v36, v[8:9], off nt
	v_add_co_u32_e32 v8, vcc, s57, v2
	s_nop 1
	v_addc_co_u32_e32 v9, vcc, 0, v3, vcc
	global_load_dword v37, v[8:9], off nt
	v_add_co_u32_e32 v8, vcc, s76, v2
	s_nop 1
	v_addc_co_u32_e32 v9, vcc, 0, v3, vcc
	global_load_dword v38, v[8:9], off nt
	v_add_co_u32_e32 v8, vcc, s45, v2
	s_nop 1
	v_addc_co_u32_e32 v9, vcc, 0, v3, vcc
	global_load_dword v39, v[8:9], off nt
	v_add_co_u32_e32 v8, vcc, s26, v2
	s_nop 1
	v_addc_co_u32_e32 v9, vcc, 0, v3, vcc
	v_add_co_u32_e32 v2, vcc, s27, v2
	global_load_dword v8, v[8:9], off nt
	s_nop 0
	v_addc_co_u32_e32 v3, vcc, 0, v3, vcc
	global_load_dword v2, v[2:3], off nt
	v_add_u32_e32 v3, 0x400, v7
	s_waitcnt vmcnt(0)
; #define LAS __attribute__((address_space(3)))
; __device__ __forceinline__ unsigned pk_bf16(float lo, float hi) { f32x2 v = {lo, hi}; return __builtin_bit_cast(unsigned, __builtin_convertvector(v, bf16v2)); }
; __device__ __forceinline__ void transpose_item(const float* W, int K, int N, bf16_t* WT, int mode, int rowoff, const float* g, LAS float* scr, int item, int lane) {
;     ...
;     for (int i = 0; i < 32; ++i) scr[(2 * i + (lane >> 5)) * 33 + (lane & 31)] = tv[i];
;     asm volatile("s_waitcnt lgkmcnt(0)" ::: "memory");
;     const int c = lane & 7;
; #pragma unroll
;     for (int j = 0; j < 4; ++j) { const int n = (lane >> 3) + 8 * j; const LAS float* s = scr + (8 * c) * 33 + n;
;         u32x4 o; o.x = pk_bf16(s[0 * 33], s[1 * 33]); o.y = pk_bf16(s[2 * 33], s[3 * 33]); o.z = pk_bf16(s[4 * 33], s[5 * 33]); o.w = pk_bf16(s[6 * 33], s[7 * 33]);
;         *(u32x4*)(WT + (size_t)(drow0 + n) * K + k0 + 8 * c) = o; }
	ds_write2_b32 v7, v10, v11 offset1:66
	ds_write2_b32 v7, v12, v13 offset0:132 offset1:198
	ds_write2_b32 v3, v14, v15 offset0:8 offset1:74
	ds_write2_b32 v3, v16, v17 offset0:140 offset1:206
	v_add_u32_e32 v3, 0x800, v7
	ds_write2_b32 v3, v18, v19 offset0:16 offset1:82
	ds_write2_b32 v3, v20, v21 offset0:148 offset1:214
	v_add_u32_e32 v3, 0xc00, v7
	ds_write2_b32 v3, v22, v23 offset0:24 offset1:90
	ds_write2_b32 v3, v24, v25 offset0:156 offset1:222
	v_add_u32_e32 v3, 0x1000, v7
	ds_write2_b32 v3, v26, v27 offset0:32 offset1:98
	ds_write2_b32 v3, v28, v29 offset0:164 offset1:230
	v_add_u32_e32 v3, 0x1400, v7
	ds_write2_b32 v3, v30, v31 offset0:40 offset1:106
	ds_write2_b32 v3, v32, v33 offset0:172 offset1:238
	v_add_u32_e32 v3, 0x1800, v7
	ds_write2_b32 v3, v34, v35 offset0:48 offset1:114
	ds_write2_b32 v3, v36, v37 offset0:180 offset1:246
	v_add_u32_e32 v3, 0x1c00, v7
	ds_write2_b32 v3, v38, v39 offset0:56 offset1:122
	ds_write2_b32 v3, v8, v2 offset0:188 offset1:254
	s_waitcnt lgkmcnt(0)
	ds_read2_b32 v[12:13], v6 offset0:33 offset1:41
	ds_read2_b32 v[14:15], v6 offset1:8
	ds_read2_b32 v[16:17], v6 offset0:66 offset1:74
	ds_read2_b32 v[18:19], v6 offset0:99 offset1:107
	ds_read2_b32 v[20:21], v6 offset0:132 offset1:140
	ds_read2_b32 v[22:23], v6 offset0:165 offset1:173
	ds_read2_b32 v[24:25], v6 offset0:198 offset1:206
	ds_read2_b32 v[26:27], v6 offset0:231 offset1:239
	v_lshl_add_u64 v[2:3], s[10:11], 1, v[0:1]
	v_add_u32_e32 v30, s4, v5
	s_waitcnt lgkmcnt(6)
	v_cvt_pk_bf16_f32 v8, v14, v12
	s_waitcnt lgkmcnt(4)
	v_cvt_pk_bf16_f32 v9, v16, v18
	s_waitcnt lgkmcnt(2)
	v_cvt_pk_bf16_f32 v10, v20, v22
	s_waitcnt lgkmcnt(0)
	v_cvt_pk_bf16_f32 v11, v24, v26
	v_mad_i64_i32 v[28:29], s[4:5], v30, s38, v[2:3]
	v_add_u32_e32 v12, 8, v30
	global_store_dwordx4 v[28:29], v[8:11], off sc1
	s_nop 1
	v_cvt_pk_bf16_f32 v8, v15, v13
	v_cvt_pk_bf16_f32 v9, v17, v19
	v_cvt_pk_bf16_f32 v10, v21, v23
	v_cvt_pk_bf16_f32 v11, v25, v27
	v_mad_i64_i32 v[12:13], s[4:5], v12, s38, v[2:3]
	global_store_dwordx4 v[12:13], v[8:11], off sc1
	ds_read2_b32 v[12:13], v6 offset0:49 offset1:57
	ds_read2_b32 v[14:15], v6 offset0:16 offset1:24
	ds_read2_b32 v[16:17], v6 offset0:82 offset1:90
	ds_read2_b32 v[18:19], v6 offset0:115 offset1:123
	ds_read2_b32 v[20:21], v6 offset0:148 offset1:156
	ds_read2_b32 v[22:23], v6 offset0:181 offset1:189
	ds_read2_b32 v[24:25], v6 offset0:214 offset1:222
	ds_read2_b32 v[26:27], v6 offset0:247 offset1:255
	s_waitcnt lgkmcnt(6)
	v_cvt_pk_bf16_f32 v8, v14, v12
	v_add_u32_e32 v12, 16, v30
	s_waitcnt lgkmcnt(4)
	v_cvt_pk_bf16_f32 v9, v16, v18
	s_waitcnt lgkmcnt(2)
	v_cvt_pk_bf16_f32 v10, v20, v22
	s_waitcnt lgkmcnt(0)
	v_cvt_pk_bf16_f32 v11, v24, v26
	v_mad_i64_i32 v[28:29], s[4:5], v12, s38, v[2:3]
	v_add_u32_e32 v12, 24, v30
	global_store_dwordx4 v[28:29], v[8:11], off sc1
	v_mad_i64_i32 v[2:3], s[4:5], v12, s38, v[2:3]
	s_nop 0
	v_cvt_pk_bf16_f32 v8, v15, v13
	v_cvt_pk_bf16_f32 v9, v17, v19
	v_cvt_pk_bf16_f32 v10, v21, v23
	v_cvt_pk_bf16_f32 v11, v25, v27
	global_store_dwordx4 v[2:3], v[8:11], off sc1
	s_waitcnt lgkmcnt(0)
	s_cbranch_scc1 .LBB0_500

; __device__ __forceinline__ void transpose_item(const float* W, int K, int N, bf16_t* WT, int mode, int rowoff, const float* g, LAS float* scr, int item, int lane) {
;     const int nblk = N / 32, kb = item / nblk, nb = item % nblk, k0 = 64 * kb, n0 = 32 * nb;
;     const int drow0 = rowoff + (mode ? 256 * (n0 >> 7) + (n0 & 127) : n0);
;     float tv[32];
;     const float* wp = W + (size_t)(k0 + (lane >> 5)) * N + n0 + (lane & 31);
; #pragma unroll
;     for (int i = 0; i < 32; ++i) tv[i] = __builtin_nontemporal_load(wp + (size_t)(2 * i) * N);
; template <int SET>
; __device__ __forceinline__ void convert_weights(const Params& p, LAS unsigned char* lds, int gw, int ngw, int wave, int lane) {
;     ...
;             if (r < I_DN) { transpose_item(p.in[16], DFF, DM, (bf16_t*)(ws + WS_WD0), 0, 0, nullptr, scr, r, lane); continue; } r -= I_DN;
;             if (r < I_QKV) { transpose_item(p.in[12], DM, 3072, (bf16_t*)(ws + WS_WQKV), 0, 0, p.in[1] + DM, scr, r, lane); continue; } r -= I_QKV;
;             if (r < I_SQ) { transpose_item(p.in[13], DM, DM, (bf16_t*)(ws + WS_WBO), 0, 0, nullptr, scr, r, lane); continue; } r -= I_SQ;
;             { const int isUp = r / I_FF;
;                 transpose_item((isUp ? p.in[15] : p.in[14]) + (size_t)DM * DFF, DM, DFF, (bf16_t*)(ws + WS_WGU1), 1, 128 * isUp, p.in[2] + DM, scr, r % I_FF, lane); }
.LBB0_506:
	s_cmpk_gt_i32 s50, 0x57f
	s_mov_b64 s[4:5], -1
	s_cbranch_scc0 .LBB0_516
	s_cmpk_gt_u32 s50, 0xb7f
	s_cbranch_scc0 .LBB0_513
	s_cmpk_gt_u32 s50, 0xd7f
	s_cbranch_scc0 .LBB0_510
	s_add_i32 s4, s50, 0xfffff280
	s_cmpk_gt_u32 s4, 0x57f
	s_cselect_b32 s5, 0x80, 0
	s_add_i32 s8, s50, 0xed00
	v_readlane_b32 s52, v250, 2
	s_cmpk_lt_u32 s4, 0x580
	v_readlane_b32 s53, v250, 3
	v_readlane_b32 s54, v250, 4
	v_readlane_b32 s55, v250, 5
	v_readlane_b32 s56, v250, 6
	v_readlane_b32 s57, v250, 7
	v_readlane_b32 s58, v250, 8
	v_readlane_b32 s59, v250, 9
	v_readlane_b32 s60, v250, 10
	v_readlane_b32 s61, v250, 11
	v_readlane_b32 s62, v250, 12
	v_readlane_b32 s63, v250, 13
	v_readlane_b32 s64, v250, 14
	v_readlane_b32 s65, v250, 15
	v_readlane_b32 s66, v250, 16
	v_readlane_b32 s67, v250, 17
	s_mov_b64 s[52:53], s[60:61]
	s_cselect_b32 s4, s4, s8
	s_mov_b64 s[56:57], s[64:65]
	s_mov_b64 s[58:59], s[66:67]
	s_sext_i32_i16 s8, s4
	s_cselect_b32 s10, s57, s59
	s_mulk_i32 s8, 0xba3
	s_cselect_b32 s11, s56, s58
	v_mov_b32_e32 v13, s10
	s_lshr_b32 s10, s8, 31
	s_ashr_i32 s8, s8, 18
	s_add_i32 s10, s8, s10
	s_mul_i32 s8, s10, 0x58
	s_sub_i32 s4, s4, s8
	s_sext_i32_i16 s8, s4
	s_lshl_b32 s4, s10, 6
	v_mov_b32_e32 v12, s11
	s_lshl_b32 s10, s8, 5
	v_add_u32_e32 v10, s4, v1
	s_movk_i32 s11, 0x2c00
	v_mad_i64_i32 v[12:13], s[52:53], v10, s11, v[12:13]
	s_ashr_i32 s11, s10, 31
	v_lshl_add_u64 v[12:13], s[10:11], 2, v[12:13]
	v_lshlrev_b32_e32 v146, 2, v0
	v_lshl_add_u64 v[12:13], v[12:13], 0, v[146:147]
	s_mov_b32 s11, 0xb00000
	v_add_co_u32_e32 v20, vcc, s11, v12
	s_mov_b32 s11, 0xb05000
	s_nop 0
	v_addc_co_u32_e32 v21, vcc, 0, v13, vcc
	global_load_dword v22, v[20:21], off nt
	v_add_co_u32_e32 v20, vcc, s11, v12
	s_mov_b32 s11, 0xb0b000
	s_nop 0
	v_addc_co_u32_e32 v21, vcc, 0, v13, vcc
	global_load_dword v23, v[20:21], off offset:2048 nt
	v_add_co_u32_e32 v20, vcc, s11, v12
	s_mov_b32 s11, 0xb10000
	s_nop 0
	v_addc_co_u32_e32 v21, vcc, 0, v13, vcc
	global_load_dword v24, v[20:21], off nt
	v_add_co_u32_e32 v20, vcc, s11, v12
	s_mov_b32 s11, 0xb16000
	s_nop 0
	v_addc_co_u32_e32 v21, vcc, 0, v13, vcc
	global_load_dword v25, v[20:21], off offset:2048 nt
	v_add_co_u32_e32 v20, vcc, s11, v12
	s_mov_b32 s11, 0xb1b000
	s_nop 0
	v_addc_co_u32_e32 v21, vcc, 0, v13, vcc
	global_load_dword v26, v[20:21], off nt
	v_add_co_u32_e32 v20, vcc, s11, v12
	s_mov_b32 s11, 0xb21000
	s_nop 0
	v_addc_co_u32_e32 v21, vcc, 0, v13, vcc
	global_load_dword v27, v[20:21], off offset:2048 nt
	v_add_co_u32_e32 v20, vcc, s11, v12
	s_mov_b32 s11, 0xb26000
	s_nop 0
	v_addc_co_u32_e32 v21, vcc, 0, v13, vcc
	global_load_dword v28, v[20:21], off nt
	v_add_co_u32_e32 v20, vcc, s11, v12
	s_mov_b32 s11, 0xb2c000
	s_nop 0
	v_addc_co_u32_e32 v21, vcc, 0, v13, vcc
	global_load_dword v29, v[20:21], off offset:2048 nt
	v_add_co_u32_e32 v20, vcc, s11, v12
	s_mov_b32 s11, 0xb31000
	s_nop 0
	v_addc_co_u32_e32 v21, vcc, 0, v13, vcc
	global_load_dword v30, v[20:21], off nt
	v_add_co_u32_e32 v20, vcc, s11, v12
	s_mov_b32 s11, 0xb37000
	s_nop 0
	v_addc_co_u32_e32 v21, vcc, 0, v13, vcc
	global_load_dword v31, v[20:21], off offset:2048 nt
	v_add_co_u32_e32 v20, vcc, s11, v12
	s_mov_b32 s11, 0xb3c000
	s_nop 0
	v_addc_co_u32_e32 v21, vcc, 0, v13, vcc
	global_load_dword v32, v[20:21], off nt
	v_add_co_u32_e32 v20, vcc, s11, v12
	s_mov_b32 s11, 0xb42000
	s_nop 0
	v_addc_co_u32_e32 v21, vcc, 0, v13, vcc
	global_load_dword v33, v[20:21], off offset:2048 nt
	v_add_co_u32_e32 v20, vcc, s11, v12
	s_mov_b32 s11, 0xb47000
	s_nop 0
	v_addc_co_u32_e32 v21, vcc, 0, v13, vcc
	global_load_dword v34, v[20:21], off nt
	v_add_co_u32_e32 v20, vcc, s11, v12
	s_mov_b32 s11, 0xb4d000
	s_nop 0
	v_addc_co_u32_e32 v21, vcc, 0, v13, vcc
	global_load_dword v35, v[20:21], off offset:2048 nt
	v_add_co_u32_e32 v20, vcc, s11, v12
	s_mov_b32 s11, 0xb52000
	s_nop 0
	v_addc_co_u32_e32 v21, vcc, 0, v13, vcc
	global_load_dword v36, v[20:21], off nt
	v_add_co_u32_e32 v20, vcc, s11, v12
	s_mov_b32 s11, 0xb58000
	s_nop 0
	v_addc_co_u32_e32 v21, vcc, 0, v13, vcc
	global_load_dword v37, v[20:21], off offset:2048 nt
	v_add_co_u32_e32 v20, vcc, s11, v12
	s_mov_b32 s11, 0xb5d000
	s_nop 0
	v_addc_co_u32_e32 v21, vcc, 0, v13, vcc
	global_load_dword v38, v[20:21], off nt
	v_add_co_u32_e32 v20, vcc, s11, v12
	s_mov_b32 s11, 0xb63000
	s_nop 0
	v_addc_co_u32_e32 v21, vcc, 0, v13, vcc
	global_load_dword v39, v[20:21], off offset:2048 nt
	v_add_co_u32_e32 v20, vcc, s11, v12
	s_mov_b32 s11, 0xb68000
	s_nop 0
	v_addc_co_u32_e32 v21, vcc, 0, v13, vcc
	global_load_dword v40, v[20:21], off nt
	v_add_co_u32_e32 v20, vcc, s11, v12
	s_mov_b32 s11, 0xb6e000
	s_nop 0
	v_addc_co_u32_e32 v21, vcc, 0, v13, vcc
	global_load_dword v41, v[20:21], off offset:2048 nt
	v_add_co_u32_e32 v20, vcc, s11, v12
	s_mov_b32 s11, 0xb73000
	s_nop 0
	v_addc_co_u32_e32 v21, vcc, 0, v13, vcc
	global_load_dword v42, v[20:21], off nt
	v_add_co_u32_e32 v20, vcc, s11, v12
	s_mov_b32 s11, 0xb79000
	s_nop 0
	v_addc_co_u32_e32 v21, vcc, 0, v13, vcc
	global_load_dword v43, v[20:21], off offset:2048 nt
	v_add_co_u32_e32 v20, vcc, s11, v12
	s_mov_b32 s11, 0xb7e000
	s_nop 0
	v_addc_co_u32_e32 v21, vcc, 0, v13, vcc
	global_load_dword v44, v[20:21], off nt
	v_add_co_u32_e32 v20, vcc, s11, v12
	s_mov_b32 s11, 0xb84000
	s_nop 0
	v_addc_co_u32_e32 v21, vcc, 0, v13, vcc
	global_load_dword v45, v[20:21], off offset:2048 nt
	v_add_co_u32_e32 v20, vcc, s11, v12
	s_mov_b32 s11, 0xb89000
	s_nop 0
	v_addc_co_u32_e32 v21, vcc, 0, v13, vcc
	global_load_dword v46, v[20:21], off nt
	v_add_co_u32_e32 v20, vcc, s11, v12
	s_mov_b32 s11, 0xb8f000
	s_nop 0
	v_addc_co_u32_e32 v21, vcc, 0, v13, vcc
; __device__ __forceinline__ void transpose_item(const float* W, int K, int N, bf16_t* WT, int mode, int rowoff, const float* g, LAS float* scr, int item, int lane) {
;     ...
;     for (int i = 0; i < 32; ++i) tv[i] = __builtin_nontemporal_load(wp + (size_t)(2 * i) * N);
;     if (g) {
; #pragma unroll
;         for (int i = 0; i < 32; ++i) tv[i] *= g[k0 + 2 * i + (lane >> 5)]; }
; #pragma unroll
;     for (int i = 0; i < 32; ++i) scr[(2 * i + (lane >> 5)) * 33 + (lane & 31)] = tv[i];
	global_load_dword v47, v[20:21], off offset:2048 nt
	v_add_co_u32_e32 v20, vcc, s11, v12
	s_mov_b32 s11, 0xb94000
	s_nop 0
	v_addc_co_u32_e32 v21, vcc, 0, v13, vcc
	global_load_dword v48, v[20:21], off nt
	v_add_co_u32_e32 v20, vcc, s11, v12
	s_mov_b32 s11, 0xb9a000
	s_nop 0
	v_addc_co_u32_e32 v21, vcc, 0, v13, vcc
	global_load_dword v49, v[20:21], off offset:2048 nt
	v_add_co_u32_e32 v20, vcc, s11, v12
	s_mov_b32 s11, 0xb9f000
	s_nop 0
	v_addc_co_u32_e32 v21, vcc, 0, v13, vcc
	global_load_dword v50, v[20:21], off nt
	v_add_co_u32_e32 v20, vcc, s11, v12
	s_mov_b32 s11, 0xba5000
	s_nop 0
	v_addc_co_u32_e32 v21, vcc, 0, v13, vcc
	global_load_dword v51, v[20:21], off offset:2048 nt
	v_add_co_u32_e32 v20, vcc, s11, v12
	s_mov_b32 s11, 0xbaa000
	s_nop 0
	v_addc_co_u32_e32 v21, vcc, 0, v13, vcc
	v_readlane_b32 s52, v250, 43
	v_ashrrev_i32_e32 v11, 31, v10
	v_add_co_u32_e32 v12, vcc, s11, v12
	v_readlane_b32 s53, v250, 44
	s_nop 0
	v_addc_co_u32_e32 v13, vcc, 0, v13, vcc
	v_lshl_add_u64 v[10:11], v[10:11], 2, s[52:53]
	global_load_dword v20, v[20:21], off nt
	s_lshl_b32 s8, s8, 6
	global_load_dword v12, v[12:13], off offset:2048 nt
	s_and_b32 s10, s10, 0x60
	global_load_dword v13, v[10:11], off
	global_load_dword v21, v[10:11], off offset:8
	s_and_b32 s8, s8, 0xffffff00
	s_or_b32 s5, s10, s5
	s_or_b32 s8, s5, s8
	s_ashr_i32 s5, s4, 31
	s_mov_b64 s[54:55], s[62:63]
	s_mov_b32 s60, 0x32000
	s_mov_b32 s61, 0x2c000
	s_mov_b32 s62, 0x22000
	s_mov_b32 s63, 0xe000
	s_movk_i32 s65, 0x4000
	s_mov_b32 s64, 0x16000
	s_mov_b32 s55, 0x14000
	s_mov_b32 s54, 0x12000
	s_movk_i32 s67, 0x2000
	s_mov_b32 s66, 0x20000
	s_mov_b32 s57, 0x36000
	s_mov_b32 s59, 0x28000
	s_mov_b32 s56, 0x34000
	s_mov_b32 s58, 0x2a000
	s_mov_b32 s53, 0x1c000
	s_mov_b32 s52, 0x10000
	s_waitcnt vmcnt(0)
	v_mul_f32_e32 v13, v22, v13
	global_load_dword v22, v[10:11], off offset:16
	v_mul_f32_e32 v21, v23, v21
	global_load_dword v23, v[10:11], off offset:24
	s_waitcnt vmcnt(1)
	v_mul_f32_e32 v22, v24, v22
	global_load_dword v24, v[10:11], off offset:32
	s_waitcnt vmcnt(1)
	v_mul_f32_e32 v23, v25, v23
	global_load_dword v25, v[10:11], off offset:40
	s_waitcnt vmcnt(1)
	v_mul_f32_e32 v24, v26, v24
	global_load_dword v26, v[10:11], off offset:48
	s_waitcnt vmcnt(1)
	v_mul_f32_e32 v25, v27, v25
	global_load_dword v27, v[10:11], off offset:56
	s_waitcnt vmcnt(1)
	v_mul_f32_e32 v26, v28, v26
	global_load_dword v28, v[10:11], off offset:64
	s_waitcnt vmcnt(1)
	v_mul_f32_e32 v27, v29, v27
	global_load_dword v29, v[10:11], off offset:72
	s_waitcnt vmcnt(1)
	v_mul_f32_e32 v28, v30, v28
	global_load_dword v30, v[10:11], off offset:80
	s_waitcnt vmcnt(1)
	v_mul_f32_e32 v29, v31, v29
	global_load_dword v31, v[10:11], off offset:88
	s_waitcnt vmcnt(1)
	v_mul_f32_e32 v30, v32, v30
	global_load_dword v32, v[10:11], off offset:96
	s_waitcnt vmcnt(1)
	v_mul_f32_e32 v31, v33, v31
	global_load_dword v33, v[10:11], off offset:104
	s_waitcnt vmcnt(1)
	v_mul_f32_e32 v32, v34, v32
	global_load_dword v34, v[10:11], off offset:112
	s_waitcnt vmcnt(1)
	v_mul_f32_e32 v33, v35, v33
	global_load_dword v35, v[10:11], off offset:120
	s_waitcnt vmcnt(1)
	v_mul_f32_e32 v34, v36, v34
	global_load_dword v36, v[10:11], off offset:128
	s_waitcnt vmcnt(1)
	v_mul_f32_e32 v35, v37, v35
	global_load_dword v37, v[10:11], off offset:136
	s_waitcnt vmcnt(1)
	v_mul_f32_e32 v36, v38, v36
	global_load_dword v38, v[10:11], off offset:144
	s_waitcnt vmcnt(1)
	v_mul_f32_e32 v37, v39, v37
	global_load_dword v39, v[10:11], off offset:152
	s_waitcnt vmcnt(1)
	v_mul_f32_e32 v38, v40, v38
	global_load_dword v40, v[10:11], off offset:160
	s_waitcnt vmcnt(1)
	v_mul_f32_e32 v39, v41, v39
	global_load_dword v41, v[10:11], off offset:168
	s_waitcnt vmcnt(1)
	v_mul_f32_e32 v40, v42, v40
	global_load_dword v42, v[10:11], off offset:176
	s_waitcnt vmcnt(1)
	v_mul_f32_e32 v41, v43, v41
	global_load_dword v43, v[10:11], off offset:184
	s_waitcnt vmcnt(1)
	v_mul_f32_e32 v42, v44, v42
	global_load_dword v44, v[10:11], off offset:192
	s_waitcnt vmcnt(1)
	v_mul_f32_e32 v43, v45, v43
	global_load_dword v45, v[10:11], off offset:200
	s_waitcnt vmcnt(1)
	v_mul_f32_e32 v44, v46, v44
	global_load_dword v46, v[10:11], off offset:208
	s_waitcnt vmcnt(1)
	v_mul_f32_e32 v45, v47, v45
	global_load_dword v47, v[10:11], off offset:216
	s_waitcnt vmcnt(1)
	v_mul_f32_e32 v46, v48, v46
	global_load_dword v48, v[10:11], off offset:224
	s_waitcnt vmcnt(1)
	v_mul_f32_e32 v47, v49, v47
	global_load_dword v49, v[10:11], off offset:232
	s_waitcnt vmcnt(1)
	v_mul_f32_e32 v48, v50, v48
	global_load_dword v50, v[10:11], off offset:240
	s_waitcnt vmcnt(1)
	v_mul_f32_e32 v49, v51, v49
	global_load_dword v10, v[10:11], off offset:248
	v_add_u32_e32 v11, 0x400, v14
	ds_write2_b32 v14, v13, v21 offset1:66
	ds_write2_b32 v14, v22, v23 offset0:132 offset1:198
	ds_write2_b32 v11, v24, v25 offset0:8 offset1:74
	ds_write2_b32 v11, v26, v27 offset0:140 offset1:206
	v_add_u32_e32 v11, 0x800, v14
	ds_write2_b32 v11, v28, v29 offset0:16 offset1:82
	ds_write2_b32 v11, v30, v31 offset0:148 offset1:214
	v_add_u32_e32 v11, 0xc00, v14
	ds_write2_b32 v11, v32, v33 offset0:24 offset1:90
	ds_write2_b32 v11, v34, v35 offset0:156 offset1:222
	v_add_u32_e32 v11, 0x1000, v14
	ds_write2_b32 v11, v36, v37 offset0:32 offset1:98
	ds_write2_b32 v11, v38, v39 offset0:164 offset1:230
	v_add_u32_e32 v11, 0x1400, v14
	ds_write2_b32 v11, v40, v41 offset0:40 offset1:106
	ds_write2_b32 v11, v42, v43 offset0:172 offset1:238
	v_add_u32_e32 v11, 0x1800, v14
	ds_write2_b32 v11, v44, v45 offset0:48 offset1:114
	ds_write2_b32 v11, v46, v47 offset0:180 offset1:246
	v_add_u32_e32 v11, 0x1c00, v14
	v_add_u32_e32 v38, s8, v15
	v_ashrrev_i32_e32 v39, 31, v38
	v_lshlrev_b64 v[38:39], 11, v[38:39]
	s_waitcnt vmcnt(1)
; #define LAS __attribute__((address_space(3)))
; __device__ __forceinline__ unsigned pk_bf16(float lo, float hi) { f32x2 v = {lo, hi}; return __builtin_bit_cast(unsigned, __builtin_convertvector(v, bf16v2)); }
; __device__ __forceinline__ void transpose_item(const float* W, int K, int N, bf16_t* WT, int mode, int rowoff, const float* g, LAS float* scr, int item, int lane) {
;     ...
;         for (int i = 0; i < 32; ++i) tv[i] *= g[k0 + 2 * i + (lane >> 5)]; }
; #pragma unroll
;     for (int i = 0; i < 32; ++i) scr[(2 * i + (lane >> 5)) * 33 + (lane & 31)] = tv[i];
;     asm volatile("s_waitcnt lgkmcnt(0)" ::: "memory");
;     const int c = lane & 7;
; #pragma unroll
;     for (int j = 0; j < 4; ++j) { const int n = (lane >> 3) + 8 * j; const LAS float* s = scr + (8 * c) * 33 + n;
;         u32x4 o; o.x = pk_bf16(s[0 * 33], s[1 * 33]); o.y = pk_bf16(s[2 * 33], s[3 * 33]); o.z = pk_bf16(s[4 * 33], s[5 * 33]); o.w = pk_bf16(s[6 * 33], s[7 * 33]);
;         *(u32x4*)(WT + (size_t)(drow0 + n) * K + k0 + 8 * c) = o; }
; template <int SET>
; __device__ __forceinline__ void convert_weights(const Params& p, LAS unsigned char* lds, int gw, int ngw, int wave, int lane) {
;     ...
;             if (r < I_DN) { transpose_item(p.in[16], DFF, DM, (bf16_t*)(ws + WS_WD0), 0, 0, nullptr, scr, r, lane); continue; } r -= I_DN;
;             if (r < I_QKV) { transpose_item(p.in[12], DM, 3072, (bf16_t*)(ws + WS_WQKV), 0, 0, p.in[1] + DM, scr, r, lane); continue; } r -= I_QKV;
;             if (r < I_SQ) { transpose_item(p.in[13], DM, DM, (bf16_t*)(ws + WS_WBO), 0, 0, nullptr, scr, r, lane); continue; } r -= I_SQ;
	v_mul_f32_e32 v20, v20, v50
	s_waitcnt vmcnt(0)
	v_mul_f32_e32 v10, v12, v10
	ds_write2_b32 v11, v48, v49 offset0:56 offset1:122
	ds_write2_b32 v11, v20, v10 offset0:188 offset1:254
	s_waitcnt lgkmcnt(0)
	ds_read2_b32 v[22:23], v16 offset0:33 offset1:41
	ds_read2_b32 v[24:25], v16 offset1:8
	ds_read2_b32 v[26:27], v16 offset0:66 offset1:74
	ds_read2_b32 v[28:29], v16 offset0:99 offset1:107
	ds_read2_b32 v[30:31], v16 offset0:132 offset1:140
	ds_read2_b32 v[32:33], v16 offset0:165 offset1:173
	ds_read2_b32 v[34:35], v16 offset0:198 offset1:206
	ds_read2_b32 v[36:37], v16 offset0:231 offset1:239
	v_lshl_add_u64 v[20:21], s[4:5], 1, v[2:3]
	s_waitcnt lgkmcnt(6)
	v_cvt_pk_bf16_f32 v10, v24, v22
	s_waitcnt lgkmcnt(4)
	v_cvt_pk_bf16_f32 v11, v26, v28
	s_waitcnt lgkmcnt(2)
	v_cvt_pk_bf16_f32 v12, v30, v32
	s_waitcnt lgkmcnt(0)
	v_cvt_pk_bf16_f32 v13, v34, v36
	v_lshl_add_u64 v[38:39], v[20:21], 0, v[38:39]
	v_add_u32_e32 v22, s8, v17
	global_store_dwordx4 v[38:39], v[10:13], off sc1
	v_add_u32_e32 v38, s8, v18
	v_ashrrev_i32_e32 v39, 31, v38
	v_cvt_pk_bf16_f32 v10, v25, v23
	v_ashrrev_i32_e32 v23, 31, v22
	v_lshlrev_b64 v[22:23], 11, v[22:23]
	v_cvt_pk_bf16_f32 v11, v27, v29
	v_cvt_pk_bf16_f32 v12, v31, v33
	v_cvt_pk_bf16_f32 v13, v35, v37
	v_lshl_add_u64 v[22:23], v[20:21], 0, v[22:23]
	global_store_dwordx4 v[22:23], v[10:13], off sc1
	ds_read2_b32 v[22:23], v16 offset0:49 offset1:57
	ds_read2_b32 v[24:25], v16 offset0:16 offset1:24
	ds_read2_b32 v[26:27], v16 offset0:82 offset1:90
	ds_read2_b32 v[28:29], v16 offset0:115 offset1:123
	ds_read2_b32 v[30:31], v16 offset0:148 offset1:156
	ds_read2_b32 v[32:33], v16 offset0:181 offset1:189
	ds_read2_b32 v[34:35], v16 offset0:214 offset1:222
	ds_read2_b32 v[36:37], v16 offset0:247 offset1:255
	v_lshlrev_b64 v[38:39], 11, v[38:39]
	s_waitcnt lgkmcnt(6)
	v_cvt_pk_bf16_f32 v10, v24, v22
	s_waitcnt lgkmcnt(4)
	v_cvt_pk_bf16_f32 v11, v26, v28
	s_waitcnt lgkmcnt(2)
	v_cvt_pk_bf16_f32 v12, v30, v32
	s_waitcnt lgkmcnt(0)
	v_cvt_pk_bf16_f32 v13, v34, v36
	v_lshl_add_u64 v[38:39], v[20:21], 0, v[38:39]
	v_add_u32_e32 v22, s8, v19
	global_store_dwordx4 v[38:39], v[10:13], off sc1
	s_mov_b64 s[4:5], 0
	s_nop 0
	v_cvt_pk_bf16_f32 v10, v25, v23
	v_ashrrev_i32_e32 v23, 31, v22
	v_lshlrev_b64 v[22:23], 11, v[22:23]
	v_cvt_pk_bf16_f32 v11, v27, v29
	v_cvt_pk_bf16_f32 v12, v31, v33
	v_cvt_pk_bf16_f32 v13, v35, v37
	v_lshl_add_u64 v[20:21], v[20:21], 0, v[22:23]
	global_store_dwordx4 v[20:21], v[10:13], off sc1
	s_waitcnt lgkmcnt(0)
.LBB0_510:
	s_andn2_b64 vcc, exec, s[4:5]
	s_cbranch_vccnz .LBB0_512
	s_and_b32 s5, s44, 0x1ffc0
	v_add_u32_e32 v10, s5, v1
	v_ashrrev_i32_e32 v11, 31, v10
	v_readlane_b32 s52, v250, 2
	s_and_b32 s4, s42, 0x3e0
	v_lshlrev_b64 v[10:11], 12, v[10:11]
	v_readlane_b32 s62, v250, 12
	v_readlane_b32 s63, v250, 13
	s_lshl_b32 s76, s4, 2
	v_lshlrev_b32_e32 v146, 2, v0
	v_lshl_add_u64 v[10:11], s[62:63], 0, v[10:11]
	v_lshl_add_u64 v[10:11], v[10:11], 0, s[76:77]
	v_lshl_add_u64 v[10:11], v[10:11], 0, v[146:147]
	v_add_co_u32_e32 v12, vcc, 0x2000, v10
	global_load_dword v20, v[10:11], off nt
	s_nop 0
	v_addc_co_u32_e32 v13, vcc, 0, v11, vcc
	global_load_dword v21, v[12:13], off nt
	v_add_co_u32_e32 v12, vcc, 0x4000, v10
	s_mov_b32 s52, 0x10000
	s_nop 0
	v_addc_co_u32_e32 v13, vcc, 0, v11, vcc
	global_load_dword v22, v[12:13], off nt
	v_add_co_u32_e32 v12, vcc, 0x6000, v10
	v_readlane_b32 s54, v250, 4
	s_nop 0
	v_addc_co_u32_e32 v13, vcc, 0, v11, vcc
	global_load_dword v23, v[12:13], off nt
	v_add_co_u32_e32 v12, vcc, 0x8000, v10
	s_mov_b32 s54, 0x12000
	s_nop 0
	v_addc_co_u32_e32 v13, vcc, 0, v11, vcc
	global_load_dword v24, v[12:13], off nt
	v_add_co_u32_e32 v12, vcc, 0xa000, v10
	v_readlane_b32 s55, v250, 5
	s_nop 0
	v_addc_co_u32_e32 v13, vcc, 0, v11, vcc
	global_load_dword v25, v[12:13], off nt
	v_add_co_u32_e32 v12, vcc, 0xc000, v10
	s_mov_b32 s55, 0x14000
	s_nop 0
	v_addc_co_u32_e32 v13, vcc, 0, v11, vcc
	global_load_dword v26, v[12:13], off nt
	v_add_co_u32_e32 v12, vcc, 0xe000, v10
	v_readlane_b32 s64, v250, 14
	s_nop 0
	v_addc_co_u32_e32 v13, vcc, 0, v11, vcc
	global_load_dword v27, v[12:13], off nt
	v_add_co_u32_e32 v12, vcc, s52, v10
	s_mov_b32 s64, 0x16000
	s_nop 0
	v_addc_co_u32_e32 v13, vcc, 0, v11, vcc
	global_load_dword v28, v[12:13], off nt
	v_add_co_u32_e32 v12, vcc, s54, v10
	v_readlane_b32 s53, v250, 3
	s_nop 0
	v_addc_co_u32_e32 v13, vcc, 0, v11, vcc
	global_load_dword v29, v[12:13], off nt
	v_add_co_u32_e32 v12, vcc, s55, v10
	s_mov_b32 s53, 0x1c000
	s_nop 0
	v_addc_co_u32_e32 v13, vcc, 0, v11, vcc
	global_load_dword v30, v[12:13], off nt
	v_add_co_u32_e32 v12, vcc, s64, v10
	v_readlane_b32 s66, v250, 16
	s_nop 0
	v_addc_co_u32_e32 v13, vcc, 0, v11, vcc
	global_load_dword v31, v[12:13], off nt
	v_add_co_u32_e32 v12, vcc, s73, v10
	s_mov_b32 s66, 0x20000
	s_nop 0
	v_addc_co_u32_e32 v13, vcc, 0, v11, vcc
	global_load_dword v32, v[12:13], off nt
	v_add_co_u32_e32 v12, vcc, s70, v10
	s_mov_b32 s62, 0x22000
	s_nop 0
	v_addc_co_u32_e32 v13, vcc, 0, v11, vcc
	global_load_dword v33, v[12:13], off nt
	v_add_co_u32_e32 v12, vcc, s53, v10
	v_readlane_b32 s59, v250, 9
	s_nop 0
	v_addc_co_u32_e32 v13, vcc, 0, v11, vcc
	global_load_dword v34, v[12:13], off nt
	v_add_co_u32_e32 v12, vcc, s74, v10
	s_mov_b32 s59, 0x28000
	s_nop 0
	v_addc_co_u32_e32 v13, vcc, 0, v11, vcc
	global_load_dword v35, v[12:13], off nt
	v_add_co_u32_e32 v12, vcc, s66, v10
	v_readlane_b32 s58, v250, 8
	s_nop 0
	v_addc_co_u32_e32 v13, vcc, 0, v11, vcc
	global_load_dword v36, v[12:13], off nt
	v_add_co_u32_e32 v12, vcc, s62, v10
	s_mov_b32 s58, 0x2a000
	s_nop 0
	v_addc_co_u32_e32 v13, vcc, 0, v11, vcc
; #define LAS __attribute__((address_space(3)))
; __device__ __forceinline__ unsigned pk_bf16(float lo, float hi) { f32x2 v = {lo, hi}; return __builtin_bit_cast(unsigned, __builtin_convertvector(v, bf16v2)); }
; __device__ __forceinline__ void transpose_item(const float* W, int K, int N, bf16_t* WT, int mode, int rowoff, const float* g, LAS float* scr, int item, int lane) {
;     ...
;     const float* wp = W + (size_t)(k0 + (lane >> 5)) * N + n0 + (lane & 31);
; #pragma unroll
;     for (int i = 0; i < 32; ++i) tv[i] = __builtin_nontemporal_load(wp + (size_t)(2 * i) * N);
;     if (g) {
; #pragma unroll
;         for (int i = 0; i < 32; ++i) tv[i] *= g[k0 + 2 * i + (lane >> 5)]; }
; #pragma unroll
;     for (int i = 0; i < 32; ++i) scr[(2 * i + (lane >> 5)) * 33 + (lane & 31)] = tv[i];
;     asm volatile("s_waitcnt lgkmcnt(0)" ::: "memory");
;     const int c = lane & 7;
; #pragma unroll
;     for (int j = 0; j < 4; ++j) { const int n = (lane >> 3) + 8 * j; const LAS float* s = scr + (8 * c) * 33 + n;
;         u32x4 o; o.x = pk_bf16(s[0 * 33], s[1 * 33]); o.y = pk_bf16(s[2 * 33], s[3 * 33]); o.z = pk_bf16(s[4 * 33], s[5 * 33]); o.w = pk_bf16(s[6 * 33], s[7 * 33]);
;         *(u32x4*)(WT + (size_t)(drow0 + n) * K + k0 + 8 * c) = o; }
; template <int SET>
; __device__ __forceinline__ void convert_weights(const Params& p, LAS unsigned char* lds, int gw, int ngw, int wave, int lane) {
;     ...
;             if (r < I_SQ) { transpose_item(p.in[13], DM, DM, (bf16_t*)(ws + WS_WBO), 0, 0, nullptr, scr, r, lane); continue; } r -= I_SQ;
	global_load_dword v37, v[12:13], off nt
	v_add_co_u32_e32 v12, vcc, s82, v10
	v_readlane_b32 s61, v250, 11
	s_nop 0
	v_addc_co_u32_e32 v13, vcc, 0, v11, vcc
	global_load_dword v38, v[12:13], off nt
	v_add_co_u32_e32 v12, vcc, s83, v10
	s_mov_b32 s61, 0x2c000
	s_nop 0
	v_addc_co_u32_e32 v13, vcc, 0, v11, vcc
	global_load_dword v39, v[12:13], off nt
	v_add_co_u32_e32 v12, vcc, s59, v10
	v_readlane_b32 s60, v250, 10
	s_nop 0
	v_addc_co_u32_e32 v13, vcc, 0, v11, vcc
	global_load_dword v40, v[12:13], off nt
	v_add_co_u32_e32 v12, vcc, s58, v10
	s_mov_b32 s60, 0x32000
	s_nop 0
	v_addc_co_u32_e32 v13, vcc, 0, v11, vcc
	global_load_dword v41, v[12:13], off nt
	v_add_co_u32_e32 v12, vcc, s61, v10
	v_readlane_b32 s56, v250, 6
	s_nop 0
	v_addc_co_u32_e32 v13, vcc, 0, v11, vcc
	global_load_dword v42, v[12:13], off nt
	v_add_co_u32_e32 v12, vcc, s26, v10
	s_mov_b32 s56, 0x34000
	s_nop 0
	v_addc_co_u32_e32 v13, vcc, 0, v11, vcc
	global_load_dword v43, v[12:13], off nt
	v_add_co_u32_e32 v12, vcc, s27, v10
	v_readlane_b32 s57, v250, 7
	s_nop 0
	v_addc_co_u32_e32 v13, vcc, 0, v11, vcc
	global_load_dword v44, v[12:13], off nt
	v_add_co_u32_e32 v12, vcc, s60, v10
	s_mov_b32 s57, 0x36000
	s_nop 0
	v_addc_co_u32_e32 v13, vcc, 0, v11, vcc
	global_load_dword v45, v[12:13], off nt
	v_add_co_u32_e32 v12, vcc, s56, v10
	s_mov_b32 s8, 0x38000
	s_nop 0
	v_addc_co_u32_e32 v13, vcc, 0, v11, vcc
	global_load_dword v46, v[12:13], off nt
	v_add_co_u32_e32 v12, vcc, s57, v10
	s_lshl_b32 s76, s5, 1
	s_nop 0
	v_addc_co_u32_e32 v13, vcc, 0, v11, vcc
	global_load_dword v47, v[12:13], off nt
	v_add_co_u32_e32 v12, vcc, s8, v10
	s_mov_b32 s8, 0x3a000
	s_nop 0
	v_addc_co_u32_e32 v13, vcc, 0, v11, vcc
	global_load_dword v48, v[12:13], off nt
	v_add_co_u32_e32 v12, vcc, s8, v10
	s_mov_b32 s8, 0x3c000
	s_nop 0
	v_addc_co_u32_e32 v13, vcc, 0, v11, vcc
	global_load_dword v49, v[12:13], off nt
	v_add_co_u32_e32 v12, vcc, s8, v10
	v_readlane_b32 s65, v250, 15
	s_nop 0
	v_addc_co_u32_e32 v13, vcc, 0, v11, vcc
	v_add_co_u32_e32 v10, vcc, s33, v10
	global_load_dword v12, v[12:13], off nt
	s_nop 0
	v_addc_co_u32_e32 v11, vcc, 0, v11, vcc
	global_load_dword v10, v[10:11], off nt
	v_add_u32_e32 v11, 0x400, v14
	s_waitcnt vmcnt(0)
	ds_write2_b32 v14, v20, v21 offset1:66
	ds_write2_b32 v14, v22, v23 offset0:132 offset1:198
	ds_write2_b32 v11, v24, v25 offset0:8 offset1:74
	ds_write2_b32 v11, v26, v27 offset0:140 offset1:206
	v_add_u32_e32 v11, 0x800, v14
	ds_write2_b32 v11, v28, v29 offset0:16 offset1:82
	ds_write2_b32 v11, v30, v31 offset0:148 offset1:214
	v_add_u32_e32 v11, 0xc00, v14
	ds_write2_b32 v11, v32, v33 offset0:24 offset1:90
	ds_write2_b32 v11, v34, v35 offset0:156 offset1:222
	v_add_u32_e32 v11, 0x1000, v14
	ds_write2_b32 v11, v36, v37 offset0:32 offset1:98
	ds_write2_b32 v11, v38, v39 offset0:164 offset1:230
	v_add_u32_e32 v11, 0x1400, v14
	ds_write2_b32 v11, v40, v41 offset0:40 offset1:106
	ds_write2_b32 v11, v42, v43 offset0:172 offset1:238
	v_add_u32_e32 v11, 0x1800, v14
	ds_write2_b32 v11, v44, v45 offset0:48 offset1:114
	ds_write2_b32 v11, v46, v47 offset0:180 offset1:246
	v_add_u32_e32 v11, 0x1c00, v14
	ds_write2_b32 v11, v48, v49 offset0:56 offset1:122
	ds_write2_b32 v11, v12, v10 offset0:188 offset1:254
	s_waitcnt lgkmcnt(0)
	ds_read2_b32 v[22:23], v16 offset0:33 offset1:41
	ds_read2_b32 v[24:25], v16 offset1:8
	ds_read2_b32 v[26:27], v16 offset0:66 offset1:74
	ds_read2_b32 v[28:29], v16 offset0:99 offset1:107
	ds_read2_b32 v[30:31], v16 offset0:132 offset1:140
	ds_read2_b32 v[32:33], v16 offset0:165 offset1:173
	ds_read2_b32 v[34:35], v16 offset0:198 offset1:206
	ds_read2_b32 v[36:37], v16 offset0:231 offset1:239
	v_add_u32_e32 v38, s4, v15
	v_ashrrev_i32_e32 v39, 31, v38
	v_lshl_add_u64 v[20:21], v[4:5], 0, s[76:77]
	v_lshlrev_b64 v[38:39], 11, v[38:39]
	s_waitcnt lgkmcnt(6)
	v_cvt_pk_bf16_f32 v10, v24, v22
	s_waitcnt lgkmcnt(4)
	v_cvt_pk_bf16_f32 v11, v26, v28
	s_waitcnt lgkmcnt(2)
	v_cvt_pk_bf16_f32 v12, v30, v32
	s_waitcnt lgkmcnt(0)
	v_cvt_pk_bf16_f32 v13, v34, v36
	v_lshl_add_u64 v[38:39], v[20:21], 0, v[38:39]
	v_add_u32_e32 v22, s4, v17
	global_store_dwordx4 v[38:39], v[10:13], off sc1
	v_add_u32_e32 v38, s4, v18
	v_ashrrev_i32_e32 v39, 31, v38
	v_cvt_pk_bf16_f32 v10, v25, v23
	v_ashrrev_i32_e32 v23, 31, v22
	v_lshlrev_b64 v[22:23], 11, v[22:23]
	v_cvt_pk_bf16_f32 v11, v27, v29
	v_cvt_pk_bf16_f32 v12, v31, v33
	v_cvt_pk_bf16_f32 v13, v35, v37
	v_lshl_add_u64 v[22:23], v[20:21], 0, v[22:23]
	global_store_dwordx4 v[22:23], v[10:13], off sc1
	ds_read2_b32 v[22:23], v16 offset0:49 offset1:57
	ds_read2_b32 v[24:25], v16 offset0:16 offset1:24
	ds_read2_b32 v[26:27], v16 offset0:82 offset1:90
	ds_read2_b32 v[28:29], v16 offset0:115 offset1:123
	ds_read2_b32 v[30:31], v16 offset0:148 offset1:156
	ds_read2_b32 v[32:33], v16 offset0:181 offset1:189
	ds_read2_b32 v[34:35], v16 offset0:214 offset1:222
	ds_read2_b32 v[36:37], v16 offset0:247 offset1:255
	v_lshlrev_b64 v[38:39], 11, v[38:39]
	s_waitcnt lgkmcnt(6)
	v_cvt_pk_bf16_f32 v10, v24, v22
	s_waitcnt lgkmcnt(4)
	v_cvt_pk_bf16_f32 v11, v26, v28
	s_waitcnt lgkmcnt(2)
	v_cvt_pk_bf16_f32 v12, v30, v32
	s_waitcnt lgkmcnt(0)
	v_cvt_pk_bf16_f32 v13, v34, v36
	v_lshl_add_u64 v[38:39], v[20:21], 0, v[38:39]
	v_add_u32_e32 v22, s4, v19
	global_store_dwordx4 v[38:39], v[10:13], off sc1
	v_readlane_b32 s67, v250, 17
	s_movk_i32 s65, 0x4000
	v_cvt_pk_bf16_f32 v10, v25, v23
	v_ashrrev_i32_e32 v23, 31, v22
	v_lshlrev_b64 v[22:23], 11, v[22:23]
	v_cvt_pk_bf16_f32 v11, v27, v29
	v_cvt_pk_bf16_f32 v12, v31, v33
	v_cvt_pk_bf16_f32 v13, v35, v37
	v_lshl_add_u64 v[20:21], v[20:21], 0, v[22:23]
	global_store_dwordx4 v[20:21], v[10:13], off sc1
	s_waitcnt lgkmcnt(0)
	s_movk_i32 s67, 0x2000
	s_mov_b32 s63, 0xe000
	s_mov_b32 s76, 0x38000

; __device__ __forceinline__ void transpose_item(const float* W, int K, int N, bf16_t* WT, int mode, int rowoff, const float* g, LAS float* scr, int item, int lane) {
;     const int nblk = N / 32, kb = item / nblk, nb = item % nblk, k0 = 64 * kb, n0 = 32 * nb;
;     const int drow0 = rowoff + (mode ? 256 * (n0 >> 7) + (n0 & 127) : n0);
;     float tv[32];
;     const float* wp = W + (size_t)(k0 + (lane >> 5)) * N + n0 + (lane & 31);
; #pragma unroll
;     for (int i = 0; i < 32; ++i) tv[i] = __builtin_nontemporal_load(wp + (size_t)(2 * i) * N);
;     if (g) {
; #pragma unroll
;         for (int i = 0; i < 32; ++i) tv[i] *= g[k0 + 2 * i + (lane >> 5)]; }
; template <int SET>
; __device__ __forceinline__ void convert_weights(const Params& p, LAS unsigned char* lds, int gw, int ngw, int wave, int lane) {
;     ...
;             if (r < I_QKV) { transpose_item(p.in[12], DM, 3072, (bf16_t*)(ws + WS_WQKV), 0, 0, p.in[1] + DM, scr, r, lane); continue; } r -= I_QKV;
.LBB0_513:
	s_andn2_b64 vcc, exec, s[4:5]
	s_cbranch_vccnz .LBB0_515
	s_add_i32 s4, s50, 0xfa80
	s_and_b32 s5, s4, 0xffff
	s_mul_i32 s5, s5, 0xaaab
	s_lshr_b32 s8, s5, 16
	s_lshr_b32 s5, s5, 22
	s_mulk_i32 s5, 0x60
	s_sub_i32 s4, s4, s5
	v_readlane_b32 s52, v250, 2
	s_and_b32 s5, s8, 0xffc0
	s_lshl_b32 s4, s4, 5
	v_readlane_b32 s60, v250, 10
	v_readlane_b32 s61, v250, 11
	s_and_b32 s4, s4, 0xffe0
	v_add_u32_e32 v10, s5, v1
	v_mov_b64_e32 v[12:13], s[60:61]
	s_movk_i32 s8, 0x3000
	v_mad_i64_i32 v[12:13], s[10:11], v10, s8, v[12:13]
	s_lshl_b32 s76, s4, 2
	v_lshl_add_u64 v[12:13], v[12:13], 0, s[76:77]
	v_lshlrev_b32_e32 v146, 2, v0
	v_lshl_add_u64 v[12:13], v[12:13], 0, v[146:147]
	v_add_co_u32_e32 v20, vcc, s51, v12
	v_readlane_b32 s54, v250, 4
	s_nop 0
	v_addc_co_u32_e32 v21, vcc, 0, v13, vcc
	global_load_dword v22, v[12:13], off nt
	global_load_dword v23, v[20:21], off nt
	v_add_co_u32_e32 v20, vcc, s75, v12
	s_mov_b32 s54, 0x12000
	s_nop 0
	v_addc_co_u32_e32 v21, vcc, 0, v13, vcc
	global_load_dword v24, v[20:21], off nt
	v_add_co_u32_e32 v20, vcc, s54, v12
	v_readlane_b32 s58, v250, 8
	s_nop 0
	v_addc_co_u32_e32 v21, vcc, 0, v13, vcc
	global_load_dword v25, v[20:21], off nt
	v_add_co_u32_e32 v20, vcc, s73, v12
	s_mov_b32 s58, 0x2a000
	s_nop 0
	v_addc_co_u32_e32 v21, vcc, 0, v13, vcc
	global_load_dword v26, v[20:21], off nt
	v_add_co_u32_e32 v20, vcc, s74, v12
	v_readlane_b32 s57, v250, 7
	s_nop 0
	v_addc_co_u32_e32 v21, vcc, 0, v13, vcc
	global_load_dword v27, v[20:21], off nt
	v_add_co_u32_e32 v20, vcc, s82, v12
	s_mov_b32 s57, 0x36000
	s_nop 0
	v_addc_co_u32_e32 v21, vcc, 0, v13, vcc
	global_load_dword v28, v[20:21], off nt
	v_add_co_u32_e32 v20, vcc, s58, v12
	s_mov_b32 s8, 0x3c000
	s_nop 0
	v_addc_co_u32_e32 v21, vcc, 0, v13, vcc
	global_load_dword v29, v[20:21], off nt
	v_add_co_u32_e32 v20, vcc, s27, v12
	v_ashrrev_i32_e32 v11, 31, v10
	s_nop 0
	v_addc_co_u32_e32 v21, vcc, 0, v13, vcc
	global_load_dword v30, v[20:21], off nt
	v_add_co_u32_e32 v20, vcc, s57, v12
	s_lshl_b32 s76, s5, 1
	s_nop 0
	v_addc_co_u32_e32 v21, vcc, 0, v13, vcc
	global_load_dword v31, v[20:21], off nt
	v_add_co_u32_e32 v20, vcc, s8, v12
	s_mov_b32 s8, 0x42000
	s_nop 0
	v_addc_co_u32_e32 v21, vcc, 0, v13, vcc
	global_load_dword v32, v[20:21], off nt
	v_add_co_u32_e32 v20, vcc, s8, v12
	s_mov_b32 s8, 0x48000
	s_nop 0
	v_addc_co_u32_e32 v21, vcc, 0, v13, vcc
	global_load_dword v33, v[20:21], off nt
	v_add_co_u32_e32 v20, vcc, s8, v12
	s_mov_b32 s8, 0x4e000
	s_nop 0
	v_addc_co_u32_e32 v21, vcc, 0, v13, vcc
	global_load_dword v34, v[20:21], off nt
	v_add_co_u32_e32 v20, vcc, s8, v12
	s_mov_b32 s8, 0x54000
	s_nop 0
	v_addc_co_u32_e32 v21, vcc, 0, v13, vcc
	global_load_dword v35, v[20:21], off nt
	v_add_co_u32_e32 v20, vcc, s8, v12
	s_mov_b32 s8, 0x5a000
	s_nop 0
	v_addc_co_u32_e32 v21, vcc, 0, v13, vcc
	global_load_dword v36, v[20:21], off nt
	v_add_co_u32_e32 v20, vcc, s8, v12
	s_mov_b32 s8, 0x60000
	s_nop 0
	v_addc_co_u32_e32 v21, vcc, 0, v13, vcc
	global_load_dword v37, v[20:21], off nt
	v_add_co_u32_e32 v20, vcc, s8, v12
	s_mov_b32 s8, 0x66000
	s_nop 0
	v_addc_co_u32_e32 v21, vcc, 0, v13, vcc
	global_load_dword v38, v[20:21], off nt
	v_add_co_u32_e32 v20, vcc, s8, v12
	s_mov_b32 s8, 0x6c000
	s_nop 0
	v_addc_co_u32_e32 v21, vcc, 0, v13, vcc
	global_load_dword v39, v[20:21], off nt
	v_add_co_u32_e32 v20, vcc, s8, v12
	s_mov_b32 s8, 0x72000
	s_nop 0
	v_addc_co_u32_e32 v21, vcc, 0, v13, vcc
	global_load_dword v40, v[20:21], off nt
	v_add_co_u32_e32 v20, vcc, s8, v12
	s_mov_b32 s8, 0x78000
	s_nop 0
	v_addc_co_u32_e32 v21, vcc, 0, v13, vcc
	global_load_dword v41, v[20:21], off nt
	v_add_co_u32_e32 v20, vcc, s8, v12
	s_mov_b32 s8, 0x7e000
	s_nop 0
	v_addc_co_u32_e32 v21, vcc, 0, v13, vcc
	global_load_dword v42, v[20:21], off nt
	v_add_co_u32_e32 v20, vcc, s8, v12
	s_mov_b32 s8, 0x84000
	s_nop 0
	v_addc_co_u32_e32 v21, vcc, 0, v13, vcc
	global_load_dword v43, v[20:21], off nt
	v_add_co_u32_e32 v20, vcc, s8, v12
	s_mov_b32 s8, 0x8a000
	s_nop 0
	v_addc_co_u32_e32 v21, vcc, 0, v13, vcc
	global_load_dword v44, v[20:21], off nt
	v_add_co_u32_e32 v20, vcc, s8, v12
	s_mov_b32 s8, 0x90000
	s_nop 0
	v_addc_co_u32_e32 v21, vcc, 0, v13, vcc
	global_load_dword v45, v[20:21], off nt
	v_add_co_u32_e32 v20, vcc, s8, v12
	s_mov_b32 s8, 0x96000
	s_nop 0
	v_addc_co_u32_e32 v21, vcc, 0, v13, vcc
	global_load_dword v46, v[20:21], off nt
	v_add_co_u32_e32 v20, vcc, s8, v12
	s_mov_b32 s8, 0x9c000
	s_nop 0
	v_addc_co_u32_e32 v21, vcc, 0, v13, vcc
	global_load_dword v47, v[20:21], off nt
	v_add_co_u32_e32 v20, vcc, s8, v12
	s_mov_b32 s8, 0xa2000
	s_nop 0
	v_addc_co_u32_e32 v21, vcc, 0, v13, vcc
	global_load_dword v48, v[20:21], off nt
	v_add_co_u32_e32 v20, vcc, s8, v12
	s_mov_b32 s8, 0xa8000
	s_nop 0
	v_addc_co_u32_e32 v21, vcc, 0, v13, vcc
	global_load_dword v49, v[20:21], off nt
	v_add_co_u32_e32 v20, vcc, s8, v12
	s_mov_b32 s8, 0xae000
	s_nop 0
	v_addc_co_u32_e32 v21, vcc, 0, v13, vcc
	global_load_dword v50, v[20:21], off nt
	v_add_co_u32_e32 v20, vcc, s8, v12
	s_mov_b32 s8, 0xb4000
	s_nop 0
	v_addc_co_u32_e32 v21, vcc, 0, v13, vcc
	global_load_dword v51, v[20:21], off nt
	v_add_co_u32_e32 v20, vcc, s8, v12
	s_mov_b32 s8, 0xba000
	s_nop 0
	v_addc_co_u32_e32 v21, vcc, 0, v13, vcc
	v_add_co_u32_e32 v12, vcc, s8, v12
	v_readlane_b32 s8, v250, 45
	v_readlane_b32 s9, v250, 46
	v_addc_co_u32_e32 v13, vcc, 0, v13, vcc
	s_nop 0
	v_lshl_add_u64 v[10:11], v[10:11], 2, s[8:9]
	global_load_dword v20, v[20:21], off nt
	v_readlane_b32 s53, v250, 3
	global_load_dword v12, v[12:13], off nt
	v_readlane_b32 s55, v250, 5
	global_load_dword v13, v[10:11], off
	global_load_dword v21, v[10:11], off offset:8
	v_readlane_b32 s56, v250, 6
	v_readlane_b32 s59, v250, 9
	v_readlane_b32 s62, v250, 12
	v_readlane_b32 s63, v250, 13
	v_readlane_b32 s64, v250, 14
	v_readlane_b32 s65, v250, 15
	v_readlane_b32 s66, v250, 16
	v_readlane_b32 s67, v250, 17
	s_mov_b32 s56, 0x34000
	s_mov_b32 s59, 0x28000
	s_mov_b32 s62, 0x22000
	s_mov_b32 s63, 0xe000
	s_mov_b32 s53, 0x1c000
	s_movk_i32 s65, 0x4000
	s_mov_b32 s64, 0x16000
	s_mov_b32 s55, 0x14000
	s_mov_b32 s52, 0x10000
	s_movk_i32 s67, 0x2000
	s_mov_b32 s66, 0x20000
	s_mov_b32 s60, 0x32000
	s_mov_b32 s61, 0x2c000
	s_waitcnt vmcnt(0)
; #define LAS __attribute__((address_space(3)))
; __device__ __forceinline__ unsigned pk_bf16(float lo, float hi) { f32x2 v = {lo, hi}; return __builtin_bit_cast(unsigned, __builtin_convertvector(v, bf16v2)); }
; __device__ __forceinline__ void transpose_item(const float* W, int K, int N, bf16_t* WT, int mode, int rowoff, const float* g, LAS float* scr, int item, int lane) {
;     ...
;         for (int i = 0; i < 32; ++i) tv[i] *= g[k0 + 2 * i + (lane >> 5)]; }
; #pragma unroll
;     for (int i = 0; i < 32; ++i) scr[(2 * i + (lane >> 5)) * 33 + (lane & 31)] = tv[i];
;     asm volatile("s_waitcnt lgkmcnt(0)" ::: "memory");
;     const int c = lane & 7;
; #pragma unroll
;     for (int j = 0; j < 4; ++j) { const int n = (lane >> 3) + 8 * j; const LAS float* s = scr + (8 * c) * 33 + n;
;         u32x4 o; o.x = pk_bf16(s[0 * 33], s[1 * 33]); o.y = pk_bf16(s[2 * 33], s[3 * 33]); o.z = pk_bf16(s[4 * 33], s[5 * 33]); o.w = pk_bf16(s[6 * 33], s[7 * 33]);
;         *(u32x4*)(WT + (size_t)(drow0 + n) * K + k0 + 8 * c) = o; }
	v_mul_f32_e32 v13, v22, v13
	global_load_dword v22, v[10:11], off offset:16
	v_mul_f32_e32 v21, v23, v21
	global_load_dword v23, v[10:11], off offset:24
	s_waitcnt vmcnt(1)
	v_mul_f32_e32 v22, v24, v22
	global_load_dword v24, v[10:11], off offset:32
	s_waitcnt vmcnt(1)
	v_mul_f32_e32 v23, v25, v23
	global_load_dword v25, v[10:11], off offset:40
	s_waitcnt vmcnt(1)
	v_mul_f32_e32 v24, v26, v24
	global_load_dword v26, v[10:11], off offset:48
	s_waitcnt vmcnt(1)
	v_mul_f32_e32 v25, v27, v25
	global_load_dword v27, v[10:11], off offset:56
	s_waitcnt vmcnt(1)
	v_mul_f32_e32 v26, v28, v26
	global_load_dword v28, v[10:11], off offset:64
	s_waitcnt vmcnt(1)
	v_mul_f32_e32 v27, v29, v27
	global_load_dword v29, v[10:11], off offset:72
	s_waitcnt vmcnt(1)
	v_mul_f32_e32 v28, v30, v28
	global_load_dword v30, v[10:11], off offset:80
	s_waitcnt vmcnt(1)
	v_mul_f32_e32 v29, v31, v29
	global_load_dword v31, v[10:11], off offset:88
	s_waitcnt vmcnt(1)
	v_mul_f32_e32 v30, v32, v30
	global_load_dword v32, v[10:11], off offset:96
	s_waitcnt vmcnt(1)
	v_mul_f32_e32 v31, v33, v31
	global_load_dword v33, v[10:11], off offset:104
	s_waitcnt vmcnt(1)
	v_mul_f32_e32 v32, v34, v32
	global_load_dword v34, v[10:11], off offset:112
	s_waitcnt vmcnt(1)
	v_mul_f32_e32 v33, v35, v33
	global_load_dword v35, v[10:11], off offset:120
	s_waitcnt vmcnt(1)
	v_mul_f32_e32 v34, v36, v34
	global_load_dword v36, v[10:11], off offset:128
	s_waitcnt vmcnt(1)
	v_mul_f32_e32 v35, v37, v35
	global_load_dword v37, v[10:11], off offset:136
	s_waitcnt vmcnt(1)
	v_mul_f32_e32 v36, v38, v36
	global_load_dword v38, v[10:11], off offset:144
	s_waitcnt vmcnt(1)
	v_mul_f32_e32 v37, v39, v37
	global_load_dword v39, v[10:11], off offset:152
	s_waitcnt vmcnt(1)
	v_mul_f32_e32 v38, v40, v38
	global_load_dword v40, v[10:11], off offset:160
	s_waitcnt vmcnt(1)
	v_mul_f32_e32 v39, v41, v39
	global_load_dword v41, v[10:11], off offset:168
	s_waitcnt vmcnt(1)
	v_mul_f32_e32 v40, v42, v40
	global_load_dword v42, v[10:11], off offset:176
	s_waitcnt vmcnt(1)
	v_mul_f32_e32 v41, v43, v41
	global_load_dword v43, v[10:11], off offset:184
	s_waitcnt vmcnt(1)
	v_mul_f32_e32 v42, v44, v42
	global_load_dword v44, v[10:11], off offset:192
	s_waitcnt vmcnt(1)
	v_mul_f32_e32 v43, v45, v43
	global_load_dword v45, v[10:11], off offset:200
	s_waitcnt vmcnt(1)
	v_mul_f32_e32 v44, v46, v44
	global_load_dword v46, v[10:11], off offset:208
	s_waitcnt vmcnt(1)
	v_mul_f32_e32 v45, v47, v45
	global_load_dword v47, v[10:11], off offset:216
	s_waitcnt vmcnt(1)
	v_mul_f32_e32 v46, v48, v46
	global_load_dword v48, v[10:11], off offset:224
	s_waitcnt vmcnt(1)
	v_mul_f32_e32 v47, v49, v47
	global_load_dword v49, v[10:11], off offset:232
	s_waitcnt vmcnt(1)
	v_mul_f32_e32 v48, v50, v48
	global_load_dword v50, v[10:11], off offset:240
	s_waitcnt vmcnt(1)
	v_mul_f32_e32 v49, v51, v49
	global_load_dword v10, v[10:11], off offset:248
	v_add_u32_e32 v11, 0x400, v14
	ds_write2_b32 v14, v13, v21 offset1:66
	ds_write2_b32 v14, v22, v23 offset0:132 offset1:198
	ds_write2_b32 v11, v24, v25 offset0:8 offset1:74
	ds_write2_b32 v11, v26, v27 offset0:140 offset1:206
	v_add_u32_e32 v11, 0x800, v14
	ds_write2_b32 v11, v28, v29 offset0:16 offset1:82
	ds_write2_b32 v11, v30, v31 offset0:148 offset1:214
	v_add_u32_e32 v11, 0xc00, v14
	ds_write2_b32 v11, v32, v33 offset0:24 offset1:90
	ds_write2_b32 v11, v34, v35 offset0:156 offset1:222
	v_add_u32_e32 v11, 0x1000, v14
	ds_write2_b32 v11, v36, v37 offset0:32 offset1:98
	ds_write2_b32 v11, v38, v39 offset0:164 offset1:230
	v_add_u32_e32 v11, 0x1400, v14
	ds_write2_b32 v11, v40, v41 offset0:40 offset1:106
	ds_write2_b32 v11, v42, v43 offset0:172 offset1:238
	v_add_u32_e32 v11, 0x1800, v14
	ds_write2_b32 v11, v44, v45 offset0:48 offset1:114
	ds_write2_b32 v11, v46, v47 offset0:180 offset1:246
	v_add_u32_e32 v11, 0x1c00, v14
	v_add_u32_e32 v38, s4, v15
	v_ashrrev_i32_e32 v39, 31, v38
	v_lshlrev_b64 v[38:39], 11, v[38:39]
	s_waitcnt vmcnt(1)
	v_mul_f32_e32 v20, v20, v50
	s_waitcnt vmcnt(0)
	v_mul_f32_e32 v10, v12, v10
	ds_write2_b32 v11, v48, v49 offset0:56 offset1:122
	ds_write2_b32 v11, v20, v10 offset0:188 offset1:254
	s_waitcnt lgkmcnt(0)
	ds_read2_b32 v[22:23], v16 offset0:33 offset1:41
	ds_read2_b32 v[24:25], v16 offset1:8
	ds_read2_b32 v[26:27], v16 offset0:66 offset1:74
	ds_read2_b32 v[28:29], v16 offset0:99 offset1:107
	ds_read2_b32 v[30:31], v16 offset0:132 offset1:140
	ds_read2_b32 v[32:33], v16 offset0:165 offset1:173
	ds_read2_b32 v[34:35], v16 offset0:198 offset1:206
	ds_read2_b32 v[36:37], v16 offset0:231 offset1:239
	v_lshl_add_u64 v[20:21], v[6:7], 0, s[76:77]
	s_waitcnt lgkmcnt(6)
	v_cvt_pk_bf16_f32 v10, v24, v22
	s_waitcnt lgkmcnt(4)
	v_cvt_pk_bf16_f32 v11, v26, v28
	s_waitcnt lgkmcnt(2)
	v_cvt_pk_bf16_f32 v12, v30, v32
	s_waitcnt lgkmcnt(0)
	v_cvt_pk_bf16_f32 v13, v34, v36
	v_lshl_add_u64 v[38:39], v[20:21], 0, v[38:39]
	v_add_u32_e32 v22, s4, v17
	global_store_dwordx4 v[38:39], v[10:13], off sc1
	v_add_u32_e32 v38, s4, v18
	v_ashrrev_i32_e32 v39, 31, v38
	v_cvt_pk_bf16_f32 v10, v25, v23
	v_ashrrev_i32_e32 v23, 31, v22
	v_lshlrev_b64 v[22:23], 11, v[22:23]
	v_cvt_pk_bf16_f32 v11, v27, v29
	v_cvt_pk_bf16_f32 v12, v31, v33
	v_cvt_pk_bf16_f32 v13, v35, v37
	v_lshl_add_u64 v[22:23], v[20:21], 0, v[22:23]
	global_store_dwordx4 v[22:23], v[10:13], off sc1
	ds_read2_b32 v[22:23], v16 offset0:49 offset1:57
	ds_read2_b32 v[24:25], v16 offset0:16 offset1:24
	ds_read2_b32 v[26:27], v16 offset0:82 offset1:90
	ds_read2_b32 v[28:29], v16 offset0:115 offset1:123
	ds_read2_b32 v[30:31], v16 offset0:148 offset1:156
	ds_read2_b32 v[32:33], v16 offset0:181 offset1:189
	ds_read2_b32 v[34:35], v16 offset0:214 offset1:222
	ds_read2_b32 v[36:37], v16 offset0:247 offset1:255
	v_lshlrev_b64 v[38:39], 11, v[38:39]
	s_waitcnt lgkmcnt(6)
	v_cvt_pk_bf16_f32 v10, v24, v22
	s_waitcnt lgkmcnt(4)
	v_cvt_pk_bf16_f32 v11, v26, v28
	s_waitcnt lgkmcnt(2)
	v_cvt_pk_bf16_f32 v12, v30, v32
	s_waitcnt lgkmcnt(0)
	v_cvt_pk_bf16_f32 v13, v34, v36
	v_lshl_add_u64 v[38:39], v[20:21], 0, v[38:39]
	v_add_u32_e32 v22, s4, v19
	global_store_dwordx4 v[38:39], v[10:13], off sc1
	s_mov_b32 s76, 0x38000
	s_nop 0
	v_cvt_pk_bf16_f32 v10, v25, v23
	v_ashrrev_i32_e32 v23, 31, v22
	v_lshlrev_b64 v[22:23], 11, v[22:23]
	v_cvt_pk_bf16_f32 v11, v27, v29
	v_cvt_pk_bf16_f32 v12, v31, v33
	v_cvt_pk_bf16_f32 v13, v35, v37
	v_lshl_add_u64 v[20:21], v[20:21], 0, v[22:23]
	global_store_dwordx4 v[20:21], v[10:13], off sc1
	s_waitcnt lgkmcnt(0)

; __device__ __forceinline__ void transpose_item(const float* W, int K, int N, bf16_t* WT, int mode, int rowoff, const float* g, LAS float* scr, int item, int lane) {
;     const int nblk = N / 32, kb = item / nblk, nb = item % nblk, k0 = 64 * kb, n0 = 32 * nb;
;     const int drow0 = rowoff + (mode ? 256 * (n0 >> 7) + (n0 & 127) : n0);
;     float tv[32];
;     const float* wp = W + (size_t)(k0 + (lane >> 5)) * N + n0 + (lane & 31);
; #pragma unroll
;     for (int i = 0; i < 32; ++i) tv[i] = __builtin_nontemporal_load(wp + (size_t)(2 * i) * N);
;     if (g) {
; #pragma unroll
;         for (int i = 0; i < 32; ++i) tv[i] *= g[k0 + 2 * i + (lane >> 5)]; }
; #pragma unroll
;     for (int i = 0; i < 32; ++i) scr[(2 * i + (lane >> 5)) * 33 + (lane & 31)] = tv[i];
; template <int SET>
; __device__ __forceinline__ void convert_weights(const Params& p, LAS unsigned char* lds, int gw, int ngw, int wave, int lane) {
;     ...
;             if (r < I_DN) { transpose_item(p.in[16], DFF, DM, (bf16_t*)(ws + WS_WD0), 0, 0, nullptr, scr, r, lane); continue; } r -= I_DN;
.LBB0_516:
	s_andn2_b64 vcc, exec, s[4:5]
	s_cbranch_vccnz .LBB0_505
	s_ashr_i32 s4, s50, 31
	s_lshr_b32 s4, s4, 27
	s_add_i32 s4, s50, s4
	s_ashr_i32 s4, s4, 5
	s_lshl_b32 s10, s4, 6
	v_add_u32_e32 v10, s10, v1
	s_lshl_b32 s4, s4, 10
	v_ashrrev_i32_e32 v11, 31, v10
	s_sub_i32 s4, s42, s4
	v_lshlrev_b64 v[10:11], 12, v[10:11]
	v_lshl_add_u64 v[10:11], s[84:85], 0, v[10:11]
	s_ashr_i32 s5, s4, 31
	v_lshl_add_u64 v[10:11], s[4:5], 2, v[10:11]
	v_lshlrev_b32_e32 v146, 2, v0
	v_lshl_add_u64 v[10:11], v[10:11], 0, v[146:147]
	v_add_co_u32_e32 v12, vcc, s67, v10
	global_load_dword v20, v[10:11], off nt
	s_nop 0
	v_addc_co_u32_e32 v13, vcc, 0, v11, vcc
	global_load_dword v21, v[12:13], off nt
	v_add_co_u32_e32 v12, vcc, s65, v10
	s_mov_b32 s5, 0x3a000
	s_nop 0
	v_addc_co_u32_e32 v13, vcc, 0, v11, vcc
	global_load_dword v22, v[12:13], off nt
	v_add_co_u32_e32 v12, vcc, s51, v10
	s_ashr_i32 s11, s10, 31
	s_nop 0
	v_addc_co_u32_e32 v13, vcc, 0, v11, vcc
	global_load_dword v23, v[12:13], off nt
	v_add_co_u32_e32 v12, vcc, s39, v10
	s_nop 1
	v_addc_co_u32_e32 v13, vcc, 0, v11, vcc
	global_load_dword v24, v[12:13], off nt
	v_add_co_u32_e32 v12, vcc, s71, v10
	s_nop 1
	v_addc_co_u32_e32 v13, vcc, 0, v11, vcc
	global_load_dword v25, v[12:13], off nt
	v_add_co_u32_e32 v12, vcc, s75, v10
	s_nop 1
	v_addc_co_u32_e32 v13, vcc, 0, v11, vcc
	global_load_dword v26, v[12:13], off nt
	v_add_co_u32_e32 v12, vcc, s63, v10
	s_nop 1
	v_addc_co_u32_e32 v13, vcc, 0, v11, vcc
	global_load_dword v27, v[12:13], off nt
	v_add_co_u32_e32 v12, vcc, s52, v10
	s_nop 1
	v_addc_co_u32_e32 v13, vcc, 0, v11, vcc
	global_load_dword v28, v[12:13], off nt
	v_add_co_u32_e32 v12, vcc, s54, v10
	s_nop 1
	v_addc_co_u32_e32 v13, vcc, 0, v11, vcc
	global_load_dword v29, v[12:13], off nt
	v_add_co_u32_e32 v12, vcc, s55, v10
	s_nop 1
	v_addc_co_u32_e32 v13, vcc, 0, v11, vcc
	global_load_dword v30, v[12:13], off nt
	v_add_co_u32_e32 v12, vcc, s64, v10
	s_nop 1
	v_addc_co_u32_e32 v13, vcc, 0, v11, vcc
	global_load_dword v31, v[12:13], off nt
	v_add_co_u32_e32 v12, vcc, s73, v10
	s_nop 1
	v_addc_co_u32_e32 v13, vcc, 0, v11, vcc
	global_load_dword v32, v[12:13], off nt
	v_add_co_u32_e32 v12, vcc, s70, v10
	s_nop 1
	v_addc_co_u32_e32 v13, vcc, 0, v11, vcc
	global_load_dword v33, v[12:13], off nt
	v_add_co_u32_e32 v12, vcc, s53, v10
	s_nop 1
	v_addc_co_u32_e32 v13, vcc, 0, v11, vcc
	global_load_dword v34, v[12:13], off nt
	v_add_co_u32_e32 v12, vcc, s74, v10
	s_nop 1
	v_addc_co_u32_e32 v13, vcc, 0, v11, vcc
	global_load_dword v35, v[12:13], off nt
	v_add_co_u32_e32 v12, vcc, s66, v10
	s_nop 1
	v_addc_co_u32_e32 v13, vcc, 0, v11, vcc
	global_load_dword v36, v[12:13], off nt
	v_add_co_u32_e32 v12, vcc, s62, v10
	s_nop 1
	v_addc_co_u32_e32 v13, vcc, 0, v11, vcc
	global_load_dword v37, v[12:13], off nt
	v_add_co_u32_e32 v12, vcc, s82, v10
	s_nop 1
	v_addc_co_u32_e32 v13, vcc, 0, v11, vcc
	global_load_dword v38, v[12:13], off nt
	v_add_co_u32_e32 v12, vcc, s83, v10
	s_nop 1
	v_addc_co_u32_e32 v13, vcc, 0, v11, vcc
	global_load_dword v39, v[12:13], off nt
	v_add_co_u32_e32 v12, vcc, s59, v10
	s_nop 1
	v_addc_co_u32_e32 v13, vcc, 0, v11, vcc
	global_load_dword v40, v[12:13], off nt
	v_add_co_u32_e32 v12, vcc, s58, v10
	s_nop 1
	v_addc_co_u32_e32 v13, vcc, 0, v11, vcc
	global_load_dword v41, v[12:13], off nt
	v_add_co_u32_e32 v12, vcc, s61, v10
	s_nop 1
	v_addc_co_u32_e32 v13, vcc, 0, v11, vcc
	global_load_dword v42, v[12:13], off nt
	v_add_co_u32_e32 v12, vcc, s26, v10
	s_nop 1
	v_addc_co_u32_e32 v13, vcc, 0, v11, vcc
	global_load_dword v43, v[12:13], off nt
	v_add_co_u32_e32 v12, vcc, s27, v10
	s_nop 1
	v_addc_co_u32_e32 v13, vcc, 0, v11, vcc
	global_load_dword v44, v[12:13], off nt
	v_add_co_u32_e32 v12, vcc, s60, v10
	s_nop 1
	v_addc_co_u32_e32 v13, vcc, 0, v11, vcc
	global_load_dword v45, v[12:13], off nt
	v_add_co_u32_e32 v12, vcc, s56, v10
	s_nop 1
	v_addc_co_u32_e32 v13, vcc, 0, v11, vcc
	global_load_dword v46, v[12:13], off nt
	v_add_co_u32_e32 v12, vcc, s57, v10
	s_nop 1
	v_addc_co_u32_e32 v13, vcc, 0, v11, vcc
	global_load_dword v47, v[12:13], off nt
	v_add_co_u32_e32 v12, vcc, s76, v10
	s_nop 1
	v_addc_co_u32_e32 v13, vcc, 0, v11, vcc
	global_load_dword v48, v[12:13], off nt
	v_add_co_u32_e32 v12, vcc, s5, v10
	s_mov_b32 s5, 0x3c000
	s_nop 0
	v_addc_co_u32_e32 v13, vcc, 0, v11, vcc
	global_load_dword v49, v[12:13], off nt
	v_add_co_u32_e32 v12, vcc, s5, v10
	s_nop 1
	v_addc_co_u32_e32 v13, vcc, 0, v11, vcc
	v_add_co_u32_e32 v10, vcc, s33, v10
	global_load_dword v12, v[12:13], off nt
	s_nop 0
	v_addc_co_u32_e32 v11, vcc, 0, v11, vcc
	global_load_dword v10, v[10:11], off nt
	v_add_u32_e32 v11, 0x400, v14
	s_waitcnt vmcnt(0)
; #define LAS __attribute__((address_space(3)))
; __device__ __forceinline__ unsigned pk_bf16(float lo, float hi) { f32x2 v = {lo, hi}; return __builtin_bit_cast(unsigned, __builtin_convertvector(v, bf16v2)); }
; __device__ __forceinline__ void transpose_item(const float* W, int K, int N, bf16_t* WT, int mode, int rowoff, const float* g, LAS float* scr, int item, int lane) {
;     ...
;     for (int i = 0; i < 32; ++i) scr[(2 * i + (lane >> 5)) * 33 + (lane & 31)] = tv[i];
;     asm volatile("s_waitcnt lgkmcnt(0)" ::: "memory");
;     const int c = lane & 7;
; #pragma unroll
;     for (int j = 0; j < 4; ++j) { const int n = (lane >> 3) + 8 * j; const LAS float* s = scr + (8 * c) * 33 + n;
;         u32x4 o; o.x = pk_bf16(s[0 * 33], s[1 * 33]); o.y = pk_bf16(s[2 * 33], s[3 * 33]); o.z = pk_bf16(s[4 * 33], s[5 * 33]); o.w = pk_bf16(s[6 * 33], s[7 * 33]);
;         *(u32x4*)(WT + (size_t)(drow0 + n) * K + k0 + 8 * c) = o; }
;     asm volatile("s_waitcnt lgkmcnt(0)" ::: "memory");
	ds_write2_b32 v14, v20, v21 offset1:66
	ds_write2_b32 v14, v22, v23 offset0:132 offset1:198
	ds_write2_b32 v11, v24, v25 offset0:8 offset1:74
	ds_write2_b32 v11, v26, v27 offset0:140 offset1:206
	v_add_u32_e32 v11, 0x800, v14
	ds_write2_b32 v11, v28, v29 offset0:16 offset1:82
	ds_write2_b32 v11, v30, v31 offset0:148 offset1:214
	v_add_u32_e32 v11, 0xc00, v14
	ds_write2_b32 v11, v32, v33 offset0:24 offset1:90
	ds_write2_b32 v11, v34, v35 offset0:156 offset1:222
	v_add_u32_e32 v11, 0x1000, v14
	ds_write2_b32 v11, v36, v37 offset0:32 offset1:98
	ds_write2_b32 v11, v38, v39 offset0:164 offset1:230
	v_add_u32_e32 v11, 0x1400, v14
	ds_write2_b32 v11, v40, v41 offset0:40 offset1:106
	ds_write2_b32 v11, v42, v43 offset0:172 offset1:238
	v_add_u32_e32 v11, 0x1800, v14
	ds_write2_b32 v11, v44, v45 offset0:48 offset1:114
	ds_write2_b32 v11, v46, v47 offset0:180 offset1:246
	v_add_u32_e32 v11, 0x1c00, v14
	ds_write2_b32 v11, v48, v49 offset0:56 offset1:122
	ds_write2_b32 v11, v12, v10 offset0:188 offset1:254
	s_waitcnt lgkmcnt(0)
	ds_read2_b32 v[22:23], v16 offset0:33 offset1:41
	ds_read2_b32 v[24:25], v16 offset1:8
	ds_read2_b32 v[26:27], v16 offset0:66 offset1:74
	ds_read2_b32 v[28:29], v16 offset0:99 offset1:107
	ds_read2_b32 v[30:31], v16 offset0:132 offset1:140
	ds_read2_b32 v[32:33], v16 offset0:165 offset1:173
	ds_read2_b32 v[34:35], v16 offset0:198 offset1:206
	ds_read2_b32 v[36:37], v16 offset0:231 offset1:239
	v_lshl_add_u64 v[20:21], s[10:11], 1, v[8:9]
	v_add_u32_e32 v40, s4, v15
	s_waitcnt lgkmcnt(6)
	v_cvt_pk_bf16_f32 v10, v24, v22
	s_waitcnt lgkmcnt(4)
	v_cvt_pk_bf16_f32 v11, v26, v28
	s_waitcnt lgkmcnt(2)
	v_cvt_pk_bf16_f32 v12, v30, v32
	s_waitcnt lgkmcnt(0)
	v_cvt_pk_bf16_f32 v13, v34, v36
	v_mad_i64_i32 v[38:39], s[4:5], v40, s38, v[20:21]
	v_add_u32_e32 v22, 8, v40
	global_store_dwordx4 v[38:39], v[10:13], off sc1
	s_nop 1
	v_cvt_pk_bf16_f32 v10, v25, v23
	v_cvt_pk_bf16_f32 v11, v27, v29
	v_cvt_pk_bf16_f32 v12, v31, v33
	v_cvt_pk_bf16_f32 v13, v35, v37
	v_mad_i64_i32 v[22:23], s[4:5], v22, s38, v[20:21]
	global_store_dwordx4 v[22:23], v[10:13], off sc1
	ds_read2_b32 v[22:23], v16 offset0:49 offset1:57
	ds_read2_b32 v[24:25], v16 offset0:16 offset1:24
	ds_read2_b32 v[26:27], v16 offset0:82 offset1:90
	ds_read2_b32 v[28:29], v16 offset0:115 offset1:123
	ds_read2_b32 v[30:31], v16 offset0:148 offset1:156
	ds_read2_b32 v[32:33], v16 offset0:181 offset1:189
	ds_read2_b32 v[34:35], v16 offset0:214 offset1:222
	ds_read2_b32 v[36:37], v16 offset0:247 offset1:255
	s_waitcnt lgkmcnt(6)
	v_cvt_pk_bf16_f32 v10, v24, v22
	v_add_u32_e32 v22, 16, v40
	s_waitcnt lgkmcnt(4)
	v_cvt_pk_bf16_f32 v11, v26, v28
	s_waitcnt lgkmcnt(2)
	v_cvt_pk_bf16_f32 v12, v30, v32
	s_waitcnt lgkmcnt(0)
	v_cvt_pk_bf16_f32 v13, v34, v36
	v_mad_i64_i32 v[38:39], s[4:5], v22, s38, v[20:21]
	v_add_u32_e32 v22, 24, v40
	global_store_dwordx4 v[38:39], v[10:13], off sc1
	v_mad_i64_i32 v[20:21], s[4:5], v22, s38, v[20:21]
	s_nop 0
	v_cvt_pk_bf16_f32 v10, v25, v23
	v_cvt_pk_bf16_f32 v11, v27, v29
	v_cvt_pk_bf16_f32 v12, v31, v33
	v_cvt_pk_bf16_f32 v13, v35, v37
	global_store_dwordx4 v[20:21], v[10:13], off sc1
	s_waitcnt lgkmcnt(0)
	s_branch .LBB0_505

; __device__ __forceinline__ unsigned pk_bf16(float lo, float hi) { f32x2 v = {lo, hi}; return __builtin_bit_cast(unsigned, __builtin_convertvector(v, bf16v2)); }
; __device__ __forceinline__ void tile_row_ss(const AccT& acc, PG8_LAS float* P, int wr, int wc, int fr, int fq) {
;     ...
;         for (int m = 0; m < 4; ++m) { float ss = 0.f;
; #pragma unroll
;             for (int bj = 0; bj < 2; ++bj) { const f32x4 v0 = acc[ai][bj][m][0], v1 = acc[ai][bj][m][1];
;                 ss += (v0[0] * v0[0] + v0[1] * v0[1]) + (v0[2] * v0[2] + v0[3] * v0[3]) + (v1[0] * v1[0] + v1[1] * v1[1]) + (v1[2] * v1[2] + v1[3] * v1[3]); }
;             ss += __shfl_xor(ss, 16); ss += __shfl_xor(ss, 32);
;             if (fq == 0) P[(ai * HALF + wr * 64 + m * 16 + fr) * 4 + wc] = ss; }
;     __device__ __forceinline__ void fused(AccT& acc, const Unit& u, int wr, int wc, int fr, int fq, PG8_LAS unsigned char* lds, int wid, int lane) const {
;     ...
;                 for (int bj = 0; bj < 2; ++bj) { const f32x4 v0 = acc[ai][bj][m][0], v1 = acc[ai][bj][m][1];
;                     u32x4 w; w.x = pk_bf16(v0[0], v0[1]); w.y = pk_bf16(v0[2], v0[3]); w.z = pk_bf16(v1[0], v1[1]); w.w = pk_bf16(v1[2], v1[3]);
;                     *(u32x4*)(xb + off0 + (unsigned)(ai * HALF + m * 16) * DM + bj * HALF) = w; }
;         tile_row_ss(acc, P, wr, wc, fr, fq);
.LBB0_635:
	s_lshl_b32 s5, s70, 8
	v_readlane_b32 s72, v250, 29
	s_add_i32 s8, s5, s72
	v_or_b32_e32 v128, s8, v140
	v_lshlrev_b32_e32 v128, 10, v128
	s_lshl_b32 s8, s4, 8
	v_add3_u32 v146, s8, v141, v128
	v_cvt_pk_bf16_f32 v128, v124, v125
	v_cvt_pk_bf16_f32 v129, v126, v127
	v_cvt_pk_bf16_f32 v130, v120, v121
	v_cvt_pk_bf16_f32 v131, v122, v123
	v_lshl_add_u64 v[132:133], v[146:147], 1, s[94:95]
	s_barrier
	global_store_dwordx4 v[132:133], v[128:131], off sc1
	v_add_co_u32_e32 v134, vcc, s39, v132
	s_nop 0
	v_cvt_pk_bf16_f32 v128, v116, v117
	v_cvt_pk_bf16_f32 v129, v118, v119
	v_cvt_pk_bf16_f32 v130, v112, v113
	v_cvt_pk_bf16_f32 v131, v114, v115
	global_store_dwordx4 v[132:133], v[128:131], off offset:256 sc1
	v_addc_co_u32_e32 v135, vcc, 0, v133, vcc
	s_nop 0
	v_cvt_pk_bf16_f32 v128, v108, v109
	v_cvt_pk_bf16_f32 v129, v110, v111
	v_cvt_pk_bf16_f32 v130, v104, v105
	v_cvt_pk_bf16_f32 v131, v106, v107
	global_store_dwordx4 v[134:135], v[128:131], off sc1
	s_mov_b32 s52, 0x10000
	s_mov_b32 s73, 0x18000
	v_cvt_pk_bf16_f32 v128, v96, v97
	v_cvt_pk_bf16_f32 v129, v98, v99
	v_cvt_pk_bf16_f32 v130, v88, v89
	v_cvt_pk_bf16_f32 v131, v90, v91
	global_store_dwordx4 v[134:135], v[128:131], off offset:256 sc1
	v_add_co_u32_e32 v134, vcc, s52, v132
	s_nop 0
	v_cvt_pk_bf16_f32 v128, v100, v101
	v_cvt_pk_bf16_f32 v129, v102, v103
	v_cvt_pk_bf16_f32 v130, v92, v93
	v_cvt_pk_bf16_f32 v131, v94, v95
	v_addc_co_u32_e32 v135, vcc, 0, v133, vcc
	global_store_dwordx4 v[134:135], v[128:131], off sc1
	s_mov_b32 s8, 0x40000
	v_mul_f32_e32 v125, v125, v125
	v_cvt_pk_bf16_f32 v128, v80, v81
	v_cvt_pk_bf16_f32 v129, v82, v83
	v_cvt_pk_bf16_f32 v130, v72, v73
	v_cvt_pk_bf16_f32 v131, v74, v75
	global_store_dwordx4 v[134:135], v[128:131], off offset:256 sc1
	v_add_co_u32_e32 v134, vcc, s73, v132
	s_nop 0
	v_cvt_pk_bf16_f32 v128, v84, v85
	v_cvt_pk_bf16_f32 v129, v86, v87
	v_cvt_pk_bf16_f32 v130, v76, v77
	v_cvt_pk_bf16_f32 v131, v78, v79
	v_addc_co_u32_e32 v135, vcc, 0, v133, vcc
	global_store_dwordx4 v[134:135], v[128:131], off sc1
	v_mul_f32_e32 v117, v117, v117
	v_fmac_f32_e32 v125, v124, v124
	v_cvt_pk_bf16_f32 v128, v68, v69
	v_cvt_pk_bf16_f32 v129, v70, v71
	v_cvt_pk_bf16_f32 v130, v60, v61
	v_cvt_pk_bf16_f32 v131, v62, v63
	global_store_dwordx4 v[134:135], v[128:131], off offset:256 sc1
	v_add_co_u32_e32 v134, vcc, s8, v132
	s_nop 0
	v_cvt_pk_bf16_f32 v128, v48, v49
	v_cvt_pk_bf16_f32 v129, v50, v51
	v_cvt_pk_bf16_f32 v130, v44, v45
	v_cvt_pk_bf16_f32 v131, v46, v47
	v_addc_co_u32_e32 v135, vcc, 0, v133, vcc
	global_store_dwordx4 v[134:135], v[128:131], off sc1
	s_mov_b32 s8, 0x48000
	v_mul_f32_e32 v124, v127, v127
	v_cvt_pk_bf16_f32 v128, v20, v21
	v_cvt_pk_bf16_f32 v129, v22, v23
	v_cvt_pk_bf16_f32 v130, v12, v13
	v_cvt_pk_bf16_f32 v131, v14, v15
	global_store_dwordx4 v[134:135], v[128:131], off offset:256 sc1
	v_add_co_u32_e32 v134, vcc, s8, v132
	s_nop 0
	v_cvt_pk_bf16_f32 v128, v24, v25
	v_cvt_pk_bf16_f32 v129, v26, v27
	v_cvt_pk_bf16_f32 v130, v16, v17
	v_cvt_pk_bf16_f32 v131, v18, v19
	v_addc_co_u32_e32 v135, vcc, 0, v133, vcc
	global_store_dwordx4 v[134:135], v[128:131], off sc1
	s_mov_b32 s8, 0x50000
	v_fmac_f32_e32 v117, v116, v116
	v_cvt_pk_bf16_f32 v128, v0, v1
	v_cvt_pk_bf16_f32 v129, v2, v3
	v_cvt_pk_bf16_f32 v130, v52, v53
	v_cvt_pk_bf16_f32 v131, v54, v55
	global_store_dwordx4 v[134:135], v[128:131], off offset:256 sc1
	v_add_co_u32_e32 v134, vcc, s8, v132
	s_nop 0
	v_cvt_pk_bf16_f32 v128, v64, v65
	v_cvt_pk_bf16_f32 v129, v66, v67
	v_cvt_pk_bf16_f32 v130, v56, v57
	v_cvt_pk_bf16_f32 v131, v58, v59
	v_addc_co_u32_e32 v135, vcc, 0, v133, vcc
	global_store_dwordx4 v[134:135], v[128:131], off sc1
	s_mov_b32 s8, 0x58000
	v_mul_f32_e32 v116, v119, v119
	v_cvt_pk_bf16_f32 v128, v36, v37
	v_cvt_pk_bf16_f32 v129, v38, v39
	v_cvt_pk_bf16_f32 v130, v28, v29
	v_cvt_pk_bf16_f32 v131, v30, v31
	global_store_dwordx4 v[134:135], v[128:131], off offset:256 sc1
	v_add_co_u32_e32 v134, vcc, s8, v132
	s_nop 0
	v_cvt_pk_bf16_f32 v128, v40, v41
	v_cvt_pk_bf16_f32 v129, v42, v43
	v_cvt_pk_bf16_f32 v130, v32, v33
	v_cvt_pk_bf16_f32 v131, v34, v35
	v_addc_co_u32_e32 v135, vcc, 0, v133, vcc
	v_fmac_f32_e32 v124, v126, v126
	v_mul_f32_e32 v121, v121, v121
	v_fmac_f32_e32 v116, v118, v118
	v_mul_f32_e32 v113, v113, v113
	global_store_dwordx4 v[134:135], v[128:131], off sc1
	v_add_f32_e32 v124, v125, v124
	v_fmac_f32_e32 v121, v120, v120
	v_and_b32_e32 v129, 64, v168
	v_add_f32_e32 v116, v117, v116
	v_fmac_f32_e32 v113, v112, v112
	v_xor_b32_e32 v128, 16, v168
	v_add_u32_e32 v129, 64, v129
	v_add_f32_e32 v120, v121, v124
	v_mul_f32_e32 v121, v123, v123
	v_add_f32_e32 v112, v113, v116
	v_mul_f32_e32 v113, v115, v115
	v_cmp_lt_i32_e32 vcc, v128, v129
	v_fmac_f32_e32 v121, v122, v122
	v_fmac_f32_e32 v113, v114, v114
	v_cndmask_b32_e32 v128, v168, v128, vcc
	v_add_f32_e32 v120, v121, v120
	v_add_f32_e32 v112, v113, v112
	v_lshlrev_b32_e32 v128, 2, v128
	v_add_f32_e32 v112, v112, v120
	ds_bpermute_b32 v114, v128, v112
	v_xor_b32_e32 v113, 32, v168
	v_cmp_lt_i32_e32 vcc, v113, v129
	v_readlane_b32 s8, v249, 19
	v_cvt_pk_bf16_f32 v130, v8, v9
	v_cndmask_b32_e32 v113, v168, v113, vcc
	v_lshlrev_b32_e32 v113, 2, v113
	s_waitcnt lgkmcnt(0)
	v_add_f32_e32 v114, v112, v114
	ds_bpermute_b32 v115, v113, v114
	v_cvt_pk_bf16_f32 v131, v10, v11
	v_cvt_pk_bf16_f32 v132, v4, v5
	v_cvt_pk_bf16_f32 v133, v6, v7
	v_cmp_gt_u32_e32 vcc, 16, v138
	v_add_u32_e32 v112, s8, v139
	global_store_dwordx4 v[134:135], v[130:133], off offset:256 sc1
	s_and_saveexec_b64 s[10:11], vcc
	v_readlane_b32 s68, v248, 18
	v_readlane_b32 s69, v248, 19
	s_mov_b32 s66, 0x20000
	s_movk_i32 s67, 0x2000
	s_movk_i32 s50, 0x6000
	s_mov_b32 s71, 0xa000
	s_mov_b32 s53, 0x1c000
	s_mov_b32 s74, 0x1e000
	s_mov_b32 s75, 0xc000
	s_mov_b32 s51, 0x2e000
	s_mov_b32 s76, 0x38000
	s_cbranch_execz .LBB0_637
	s_waitcnt lgkmcnt(0)
	v_add_f32_e32 v114, v114, v115
	ds_write_b32 v112, v114

; __device__ __forceinline__ unsigned pk_bf16(float lo, float hi) { f32x2 v = {lo, hi}; return __builtin_bit_cast(unsigned, __builtin_convertvector(v, bf16v2)); }
;     __device__ __forceinline__ void operator()(const AccT& acc, const Unit& u, int wr, int wc, int fr, int fq) const {
;     ...
;             for (int m = 0; m < 4; ++m) { const int row = row0 + ai * HALF + m * 16; const float rs = rst[row - row_base] * sc;
;                 const unsigned b = (unsigned)row >> 13, t = (unsigned)row & 8191u;
; #pragma unroll
;                 for (int bj = 0; bj < 2; ++bj) { const f32x4 v0 = acc[ai][bj][m][0] * rs, v1 = acc[ai][bj][m][1] * rs;
;                     const unsigned col = col0 + bj * HALF, hd = col >> 6, d0 = col & 63u;
;                     const unsigned off = ((((b * NHEAD + hd) * 256u + (t >> 5)) * 4u + (d0 >> 4)) * 64u + ((d0 >> 3) & 1u) * 32u + (t & 31u)) * 8u;
;                     u32x4 w; w.x = pk_bf16(v0[0], v0[1]); w.y = pk_bf16(v0[2], v0[3]); w.z = pk_bf16(v1[0], v1[1]); w.w = pk_bf16(v1[2], v1[3]);
;                     *(u32x4*)(base + off) = w; } }
.LBB0_722:
	s_cmp_lt_i32 s67, 4
	s_cselect_b64 vcc, -1, 0
	s_and_b64 s[52:53], vcc, exec
	s_cselect_b32 s53, s97, s93
	s_cselect_b32 s52, s96, s92
	s_lshl_b32 s8, s68, 8
	s_add_i32 s9, s8, s72
	s_lshl_b32 s8, s67, 8
	s_and_b32 s8, s8, 0x300
	v_readlane_b32 s11, v250, 21
	s_or_b32 s8, s8, s11
	v_or_b32_e32 v131, s9, v160
	v_add_u32_e32 v177, s8, v161
	s_lshr_b32 s8, s9, 9
	s_and_b32 s11, s8, 0x1ff0
	v_subrev_u32_e32 v130, s17, v131
	s_add_i32 s8, 0, 0x20000
	v_lshl_add_u32 v130, v130, 2, s8
	ds_read2_b32 v[182:183], v130 offset1:16
	s_lshr_b32 s9, s9, 3
	v_bfe_u32 v129, v177, 4, 2
	s_and_b32 s9, s9, 0x3f8
	v_cndmask_b32_e32 v128, 1.0, v169, vcc
	v_or_b32_e32 v146, s9, v129
	v_lshrrev_b32_e32 v188, 6, v177
	s_waitcnt lgkmcnt(0)
	v_mul_f32_e32 v130, v128, v182
	v_add_lshl_u32 v189, v188, s11, 16
	v_lshlrev_b32_e32 v182, 6, v146
	v_or_b32_e32 v190, v182, v189
	v_or_b32_e32 v146, v190, v163
	v_pk_mul_f32 v[180:181], v[126:127], v[130:131] op_sel_hi:[1,0]
	v_pk_mul_f32 v[178:179], v[124:125], v[130:131] op_sel_hi:[1,0]
	v_pk_mul_f32 v[184:185], v[122:123], v[130:131] op_sel_hi:[1,0]
	v_pk_mul_f32 v[186:187], v[120:121], v[130:131] op_sel_hi:[1,0]
	v_lshlrev_b32_e32 v146, 3, v146
	v_cvt_pk_bf16_f32 v178, v178, v179
	v_cvt_pk_bf16_f32 v179, v180, v181
	v_cvt_pk_bf16_f32 v180, v186, v187
	v_cvt_pk_bf16_f32 v181, v184, v185
	v_lshl_add_u64 v[184:185], v[146:147], 1, s[52:53]
	global_store_dwordx4 v[184:185], v[178:181], off sc1
	v_pk_mul_f32 v[184:185], v[114:115], v[130:131] op_sel_hi:[1,0]
	v_pk_mul_f32 v[186:187], v[112:113], v[130:131] op_sel_hi:[1,0]
	v_pk_mul_f32 v[180:181], v[118:119], v[130:131] op_sel_hi:[1,0]
	v_pk_mul_f32 v[178:179], v[116:117], v[130:131] op_sel_hi:[1,0]
	v_add_u32_e32 v130, 0x80, v177
	v_lshrrev_b32_e32 v191, 6, v130
	v_add_lshl_u32 v177, v191, s11, 16
	v_or_b32_e32 v192, v177, v182
	v_or_b32_e32 v130, v192, v163
	v_lshlrev_b32_e32 v146, 3, v130
	v_cvt_pk_bf16_f32 v178, v178, v179
	v_cvt_pk_bf16_f32 v179, v180, v181
	v_cvt_pk_bf16_f32 v180, v186, v187
	v_cvt_pk_bf16_f32 v181, v184, v185
	v_lshl_add_u64 v[184:185], v[146:147], 1, s[52:53]
	v_mul_f32_e32 v130, v128, v183
	v_or_b32_e32 v146, v190, v170
	global_store_dwordx4 v[184:185], v[178:181], off sc1
	v_pk_mul_f32 v[182:183], v[106:107], v[130:131] op_sel_hi:[1,0]
	v_pk_mul_f32 v[184:185], v[104:105], v[130:131] op_sel_hi:[1,0]
	v_pk_mul_f32 v[180:181], v[110:111], v[130:131] op_sel_hi:[1,0]
	v_pk_mul_f32 v[178:179], v[108:109], v[130:131] op_sel_hi:[1,0]
	v_lshlrev_b32_e32 v146, 3, v146
	v_cvt_pk_bf16_f32 v178, v178, v179
	v_cvt_pk_bf16_f32 v179, v180, v181
	v_cvt_pk_bf16_f32 v180, v184, v185
	v_cvt_pk_bf16_f32 v181, v182, v183
	v_lshl_add_u64 v[182:183], v[146:147], 1, s[52:53]
	global_store_dwordx4 v[182:183], v[178:181], off sc1
	v_pk_mul_f32 v[182:183], v[98:99], v[130:131] op_sel_hi:[1,0]
	v_pk_mul_f32 v[184:185], v[96:97], v[130:131] op_sel_hi:[1,0]
	v_pk_mul_f32 v[180:181], v[102:103], v[130:131] op_sel_hi:[1,0]
	v_pk_mul_f32 v[178:179], v[100:101], v[130:131] op_sel_hi:[1,0]
	v_or_b32_e32 v130, v192, v170
	v_lshlrev_b32_e32 v146, 3, v130
	v_cvt_pk_bf16_f32 v178, v178, v179
	v_cvt_pk_bf16_f32 v179, v180, v181
	v_cvt_pk_bf16_f32 v181, v182, v183
	v_lshl_add_u64 v[182:183], v[146:147], 1, s[52:53]
	v_or_b32_e32 v146, 32, v131
	v_subrev_u32_e32 v130, s17, v146
	v_lshl_add_u32 v130, v130, 2, s8
	ds_read_b32 v130, v130
	v_lshrrev_b32_e32 v146, 3, v146
	v_and_or_b32 v146, v146, s1, v129
	v_lshlrev_b32_e32 v186, 6, v146
	v_cvt_pk_bf16_f32 v180, v184, v185
	s_waitcnt lgkmcnt(0)
	v_mul_f32_e32 v130, v128, v130
	v_or3_b32 v146, v189, v186, v163
	global_store_dwordx4 v[182:183], v[178:181], off sc1
	v_pk_mul_f32 v[182:183], v[90:91], v[130:131] op_sel_hi:[1,0]
	v_pk_mul_f32 v[184:185], v[88:89], v[130:131] op_sel_hi:[1,0]
	v_pk_mul_f32 v[180:181], v[94:95], v[130:131] op_sel_hi:[1,0]
	v_pk_mul_f32 v[178:179], v[92:93], v[130:131] op_sel_hi:[1,0]
	v_lshlrev_b32_e32 v146, 3, v146
	v_cvt_pk_bf16_f32 v178, v178, v179
	v_cvt_pk_bf16_f32 v179, v180, v181
	v_cvt_pk_bf16_f32 v180, v184, v185
	v_cvt_pk_bf16_f32 v181, v182, v183
	v_lshl_add_u64 v[182:183], v[146:147], 1, s[52:53]
	global_store_dwordx4 v[182:183], v[178:181], off sc1
	v_pk_mul_f32 v[182:183], v[82:83], v[130:131] op_sel_hi:[1,0]
	v_pk_mul_f32 v[184:185], v[80:81], v[130:131] op_sel_hi:[1,0]
	v_pk_mul_f32 v[180:181], v[86:87], v[130:131] op_sel_hi:[1,0]
	v_pk_mul_f32 v[178:179], v[84:85], v[130:131] op_sel_hi:[1,0]
	v_or3_b32 v130, v177, v186, v163
	v_lshlrev_b32_e32 v146, 3, v130
	v_cvt_pk_bf16_f32 v178, v178, v179
	v_cvt_pk_bf16_f32 v179, v180, v181
	v_cvt_pk_bf16_f32 v181, v182, v183
	v_lshl_add_u64 v[182:183], v[146:147], 1, s[52:53]
	v_or_b32_e32 v146, 48, v131
	v_subrev_u32_e32 v130, s17, v146
	v_lshl_add_u32 v130, v130, 2, s8
	ds_read_b32 v130, v130
	v_lshrrev_b32_e32 v146, 3, v146
	v_and_or_b32 v146, v146, s1, v129
	v_lshlrev_b32_e32 v186, 6, v146
	v_cvt_pk_bf16_f32 v180, v184, v185
	s_waitcnt lgkmcnt(0)
; __device__ __forceinline__ unsigned pk_bf16(float lo, float hi) { f32x2 v = {lo, hi}; return __builtin_bit_cast(unsigned, __builtin_convertvector(v, bf16v2)); }
;     __device__ __forceinline__ void operator()(const AccT& acc, const Unit& u, int wr, int wc, int fr, int fq) const {
;     ...
;             for (int m = 0; m < 4; ++m) { const int row = row0 + ai * HALF + m * 16; const float rs = rst[row - row_base] * sc;
;                 const unsigned b = (unsigned)row >> 13, t = (unsigned)row & 8191u;
; #pragma unroll
;                 for (int bj = 0; bj < 2; ++bj) { const f32x4 v0 = acc[ai][bj][m][0] * rs, v1 = acc[ai][bj][m][1] * rs;
;                     const unsigned col = col0 + bj * HALF, hd = col >> 6, d0 = col & 63u;
;                     const unsigned off = ((((b * NHEAD + hd) * 256u + (t >> 5)) * 4u + (d0 >> 4)) * 64u + ((d0 >> 3) & 1u) * 32u + (t & 31u)) * 8u;
;                     u32x4 w; w.x = pk_bf16(v0[0], v0[1]); w.y = pk_bf16(v0[2], v0[3]); w.z = pk_bf16(v1[0], v1[1]); w.w = pk_bf16(v1[2], v1[3]);
;                     *(u32x4*)(base + off) = w; } }
	v_mul_f32_e32 v130, v128, v130
	v_or3_b32 v146, v189, v186, v170
	global_store_dwordx4 v[182:183], v[178:181], off sc1
	v_pk_mul_f32 v[182:183], v[74:75], v[130:131] op_sel_hi:[1,0]
	v_pk_mul_f32 v[184:185], v[72:73], v[130:131] op_sel_hi:[1,0]
	v_pk_mul_f32 v[180:181], v[78:79], v[130:131] op_sel_hi:[1,0]
	v_pk_mul_f32 v[178:179], v[76:77], v[130:131] op_sel_hi:[1,0]
	v_lshlrev_b32_e32 v146, 3, v146
	v_cvt_pk_bf16_f32 v178, v178, v179
	v_cvt_pk_bf16_f32 v179, v180, v181
	v_cvt_pk_bf16_f32 v180, v184, v185
	v_cvt_pk_bf16_f32 v181, v182, v183
	v_lshl_add_u64 v[182:183], v[146:147], 1, s[52:53]
	global_store_dwordx4 v[182:183], v[178:181], off sc1
	v_pk_mul_f32 v[182:183], v[66:67], v[130:131] op_sel_hi:[1,0]
	v_pk_mul_f32 v[184:185], v[64:65], v[130:131] op_sel_hi:[1,0]
	v_pk_mul_f32 v[180:181], v[70:71], v[130:131] op_sel_hi:[1,0]
	v_pk_mul_f32 v[178:179], v[68:69], v[130:131] op_sel_hi:[1,0]
	v_or3_b32 v130, v177, v186, v170
	v_lshlrev_b32_e32 v146, 3, v130
	v_cvt_pk_bf16_f32 v178, v178, v179
	v_cvt_pk_bf16_f32 v179, v180, v181
	v_cvt_pk_bf16_f32 v181, v182, v183
	v_lshl_add_u64 v[182:183], v[146:147], 1, s[52:53]
	v_add_u32_e32 v146, 0x80, v131
	v_lshrrev_b32_e32 v130, 9, v146
	v_and_b32_e32 v186, 0x1ff0, v130
	v_subrev_u32_e32 v130, s17, v146
	v_lshl_add_u32 v130, v130, 2, s8
	ds_read_b32 v130, v130
	v_lshrrev_b32_e32 v146, 3, v146
	s_movk_i32 s9, 0x3f8
	v_and_or_b32 v146, v146, s9, v129
	v_add_lshl_u32 v177, v186, v188, 16
	v_lshlrev_b32_e32 v187, 6, v146
	v_cvt_pk_bf16_f32 v180, v184, v185
	s_waitcnt lgkmcnt(0)
	v_mul_f32_e32 v130, v128, v130
	v_or3_b32 v146, v177, v187, v163
	global_store_dwordx4 v[182:183], v[178:181], off sc1
	v_pk_mul_f32 v[182:183], v[58:59], v[130:131] op_sel_hi:[1,0]
	v_pk_mul_f32 v[184:185], v[56:57], v[130:131] op_sel_hi:[1,0]
	v_pk_mul_f32 v[180:181], v[62:63], v[130:131] op_sel_hi:[1,0]
	v_pk_mul_f32 v[178:179], v[60:61], v[130:131] op_sel_hi:[1,0]
	v_lshlrev_b32_e32 v146, 3, v146
	v_cvt_pk_bf16_f32 v178, v178, v179
	v_cvt_pk_bf16_f32 v179, v180, v181
	v_cvt_pk_bf16_f32 v180, v184, v185
	v_cvt_pk_bf16_f32 v181, v182, v183
	v_lshl_add_u64 v[182:183], v[146:147], 1, s[52:53]
	global_store_dwordx4 v[182:183], v[178:181], off sc1
	v_pk_mul_f32 v[182:183], v[50:51], v[130:131] op_sel_hi:[1,0]
	v_pk_mul_f32 v[184:185], v[48:49], v[130:131] op_sel_hi:[1,0]
	v_pk_mul_f32 v[180:181], v[54:55], v[130:131] op_sel_hi:[1,0]
	v_pk_mul_f32 v[178:179], v[52:53], v[130:131] op_sel_hi:[1,0]
	v_add_lshl_u32 v130, v186, v191, 16
	v_or3_b32 v146, v130, v187, v163
	v_lshlrev_b32_e32 v146, 3, v146
	v_cvt_pk_bf16_f32 v178, v178, v179
	v_cvt_pk_bf16_f32 v179, v180, v181
	v_cvt_pk_bf16_f32 v180, v184, v185
	v_cvt_pk_bf16_f32 v181, v182, v183
	v_lshl_add_u64 v[182:183], v[146:147], 1, s[52:53]
	v_add_u32_e32 v146, 0x90, v131
	global_store_dwordx4 v[182:183], v[178:181], off sc1
	s_nop 1
	v_subrev_u32_e32 v178, s17, v146
	v_lshl_add_u32 v178, v178, 2, s8
	ds_read_b32 v178, v178
	v_lshrrev_b32_e32 v146, 3, v146
	v_and_or_b32 v146, v146, s9, v129
	v_lshlrev_b32_e32 v188, 6, v146
	v_or3_b32 v146, v177, v188, v170
	s_waitcnt lgkmcnt(0)
; __device__ __forceinline__ unsigned pk_bf16(float lo, float hi) { f32x2 v = {lo, hi}; return __builtin_bit_cast(unsigned, __builtin_convertvector(v, bf16v2)); }
;     __device__ __forceinline__ void operator()(const AccT& acc, const Unit& u, int wr, int wc, int fr, int fq) const {
;     ...
;             for (int m = 0; m < 4; ++m) { const int row = row0 + ai * HALF + m * 16; const float rs = rst[row - row_base] * sc;
;                 const unsigned b = (unsigned)row >> 13, t = (unsigned)row & 8191u;
; #pragma unroll
;                 for (int bj = 0; bj < 2; ++bj) { const f32x4 v0 = acc[ai][bj][m][0] * rs, v1 = acc[ai][bj][m][1] * rs;
;                     const unsigned col = col0 + bj * HALF, hd = col >> 6, d0 = col & 63u;
;                     const unsigned off = ((((b * NHEAD + hd) * 256u + (t >> 5)) * 4u + (d0 >> 4)) * 64u + ((d0 >> 3) & 1u) * 32u + (t & 31u)) * 8u;
;                     u32x4 w; w.x = pk_bf16(v0[0], v0[1]); w.y = pk_bf16(v0[2], v0[3]); w.z = pk_bf16(v1[0], v1[1]); w.w = pk_bf16(v1[2], v1[3]);
;                     *(u32x4*)(base + off) = w; } }
	v_mul_f32_e32 v182, v128, v178
	v_pk_mul_f32 v[180:181], v[46:47], v[182:183] op_sel_hi:[1,0]
	v_pk_mul_f32 v[178:179], v[44:45], v[182:183] op_sel_hi:[1,0]
	v_pk_mul_f32 v[184:185], v[42:43], v[182:183] op_sel_hi:[1,0]
	v_pk_mul_f32 v[186:187], v[40:41], v[182:183] op_sel_hi:[1,0]
	v_lshlrev_b32_e32 v146, 3, v146
	v_cvt_pk_bf16_f32 v178, v178, v179
	v_cvt_pk_bf16_f32 v179, v180, v181
	v_cvt_pk_bf16_f32 v180, v186, v187
	v_cvt_pk_bf16_f32 v181, v184, v185
	v_lshl_add_u64 v[184:185], v[146:147], 1, s[52:53]
	v_or3_b32 v146, v130, v188, v170
	global_store_dwordx4 v[184:185], v[178:181], off sc1
	v_pk_mul_f32 v[184:185], v[34:35], v[182:183] op_sel_hi:[1,0]
	v_lshlrev_b32_e32 v146, 3, v146
	v_pk_mul_f32 v[180:181], v[38:39], v[182:183] op_sel_hi:[1,0]
	v_pk_mul_f32 v[178:179], v[36:37], v[182:183] op_sel_hi:[1,0]
	v_pk_mul_f32 v[182:183], v[32:33], v[182:183] op_sel_hi:[1,0]
	v_cvt_pk_bf16_f32 v178, v178, v179
	v_cvt_pk_bf16_f32 v179, v180, v181
	v_cvt_pk_bf16_f32 v180, v182, v183
	v_cvt_pk_bf16_f32 v181, v184, v185
	v_lshl_add_u64 v[182:183], v[146:147], 1, s[52:53]
	v_add_u32_e32 v146, 0xa0, v131
	global_store_dwordx4 v[182:183], v[178:181], off sc1
	v_add_u32_e32 v131, 0xb0, v131
	s_nop 0
	v_subrev_u32_e32 v178, s17, v146
	v_lshl_add_u32 v178, v178, 2, s8
	ds_read_b32 v178, v178
	v_lshrrev_b32_e32 v146, 3, v146
	v_and_or_b32 v146, v146, s1, v129
	v_lshlrev_b32_e32 v188, 6, v146
	v_or3_b32 v146, v177, v188, v163
	s_waitcnt lgkmcnt(0)
	v_mul_f32_e32 v182, v128, v178
	v_pk_mul_f32 v[180:181], v[30:31], v[182:183] op_sel_hi:[1,0]
	v_pk_mul_f32 v[178:179], v[28:29], v[182:183] op_sel_hi:[1,0]
	v_pk_mul_f32 v[184:185], v[26:27], v[182:183] op_sel_hi:[1,0]
	v_pk_mul_f32 v[186:187], v[24:25], v[182:183] op_sel_hi:[1,0]
	v_lshlrev_b32_e32 v146, 3, v146
	v_cvt_pk_bf16_f32 v178, v178, v179
	v_cvt_pk_bf16_f32 v179, v180, v181
	v_cvt_pk_bf16_f32 v180, v186, v187
	v_cvt_pk_bf16_f32 v181, v184, v185
	v_lshl_add_u64 v[184:185], v[146:147], 1, s[52:53]
	v_or3_b32 v146, v130, v188, v163
	global_store_dwordx4 v[184:185], v[178:181], off sc1
	v_pk_mul_f32 v[184:185], v[18:19], v[182:183] op_sel_hi:[1,0]
	v_lshlrev_b32_e32 v146, 3, v146
	v_pk_mul_f32 v[180:181], v[22:23], v[182:183] op_sel_hi:[1,0]
	v_pk_mul_f32 v[178:179], v[20:21], v[182:183] op_sel_hi:[1,0]
	v_pk_mul_f32 v[182:183], v[16:17], v[182:183] op_sel_hi:[1,0]
	v_cvt_pk_bf16_f32 v178, v178, v179
	v_cvt_pk_bf16_f32 v179, v180, v181
	v_cvt_pk_bf16_f32 v180, v182, v183
	v_lshl_add_u64 v[182:183], v[146:147], 1, s[52:53]
	v_subrev_u32_e32 v146, s17, v131
	v_lshl_add_u32 v146, v146, 2, s8
	ds_read_b32 v146, v146
	v_lshrrev_b32_e32 v131, 3, v131
	v_cvt_pk_bf16_f32 v181, v184, v185
	v_and_or_b32 v129, v131, s1, v129
	global_store_dwordx4 v[182:183], v[178:181], off sc1
	s_waitcnt lgkmcnt(0)
	v_mul_f32_e32 v128, v128, v146
	v_pk_mul_f32 v[182:183], v[10:11], v[128:129] op_sel_hi:[1,0]
	v_pk_mul_f32 v[180:181], v[14:15], v[128:129] op_sel_hi:[1,0]
	v_pk_mul_f32 v[178:179], v[12:13], v[128:129] op_sel_hi:[1,0]
	v_pk_mul_f32 v[184:185], v[8:9], v[128:129] op_sel_hi:[1,0]
	v_lshlrev_b32_e32 v129, 6, v129
	v_or3_b32 v131, v177, v129, v170
	v_lshlrev_b32_e32 v146, 3, v131
	v_cvt_pk_bf16_f32 v178, v178, v179
	v_cvt_pk_bf16_f32 v179, v180, v181
	v_cvt_pk_bf16_f32 v180, v184, v185
	v_cvt_pk_bf16_f32 v181, v182, v183
	v_lshl_add_u64 v[182:183], v[146:147], 1, s[52:53]
	global_store_dwordx4 v[182:183], v[178:181], off sc1
	v_pk_mul_f32 v[182:183], v[2:3], v[128:129] op_sel_hi:[1,0]
	v_pk_mul_f32 v[184:185], v[0:1], v[128:129] op_sel_hi:[1,0]
	v_pk_mul_f32 v[178:179], v[6:7], v[128:129] op_sel_hi:[1,0]
	v_pk_mul_f32 v[180:181], v[4:5], v[128:129] op_sel_hi:[1,0]
	v_or3_b32 v128, v130, v129, v170
	v_lshlrev_b32_e32 v146, 3, v128
	v_cvt_pk_bf16_f32 v128, v180, v181
	v_cvt_pk_bf16_f32 v129, v178, v179
	v_cvt_pk_bf16_f32 v130, v184, v185
	v_cvt_pk_bf16_f32 v131, v182, v183
	v_lshl_add_u64 v[178:179], v[146:147], 1, s[52:53]
	global_store_dwordx4 v[178:179], v[128:131], off sc1
	s_cbranch_execnz .LBB0_721

; __device__ __forceinline__ unsigned pk_bf16(float lo, float hi) { f32x2 v = {lo, hi}; return __builtin_bit_cast(unsigned, __builtin_convertvector(v, bf16v2)); }
; __device__ __forceinline__ void tile_row_ss(const AccT& acc, PG8_LAS float* P, int wr, int wc, int fr, int fq) {
;     ...
;         for (int m = 0; m < 4; ++m) { float ss = 0.f;
; #pragma unroll
;             for (int bj = 0; bj < 2; ++bj) { const f32x4 v0 = acc[ai][bj][m][0], v1 = acc[ai][bj][m][1];
;                 ss += (v0[0] * v0[0] + v0[1] * v0[1]) + (v0[2] * v0[2] + v0[3] * v0[3]) + (v1[0] * v1[0] + v1[1] * v1[1]) + (v1[2] * v1[2] + v1[3] * v1[3]); }
;             ss += __shfl_xor(ss, 16); ss += __shfl_xor(ss, 32);
;             if (fq == 0) P[(ai * HALF + wr * 64 + m * 16 + fr) * 4 + wc] = ss; }
;     __device__ __forceinline__ void fused(AccT& acc, const Unit& u, int wr, int wc, int fr, int fq, PG8_LAS unsigned char* lds, int wid, int lane) const {
;     ...
;                 for (int bj = 0; bj < 2; ++bj) { const f32x4 v0 = acc[ai][bj][m][0], v1 = acc[ai][bj][m][1];
;                     u32x4 w; w.x = pk_bf16(v0[0], v0[1]); w.y = pk_bf16(v0[2], v0[3]); w.z = pk_bf16(v1[0], v1[1]); w.w = pk_bf16(v1[2], v1[3]);
;                     *(u32x4*)(xb + off0 + (unsigned)(ai * HALF + m * 16) * DM + bj * HALF) = w; }
;         tile_row_ss(acc, P, wr, wc, fr, fq);
.LBB0_836:
	s_lshl_b32 s5, s68, 8
	v_readlane_b32 s72, v250, 29
	s_add_i32 s8, s5, s72
	v_or_b32_e32 v128, s8, v140
	v_lshlrev_b32_e32 v128, 10, v128
	s_lshl_b32 s8, s4, 8
	v_add3_u32 v146, s8, v141, v128
	v_cvt_pk_bf16_f32 v128, v124, v125
	v_cvt_pk_bf16_f32 v129, v126, v127
	v_cvt_pk_bf16_f32 v130, v120, v121
	v_cvt_pk_bf16_f32 v131, v122, v123
	v_lshl_add_u64 v[132:133], v[146:147], 1, s[94:95]
	s_mov_b32 s8, 0x8000
	s_barrier
	global_store_dwordx4 v[132:133], v[128:131], off sc1
	v_add_co_u32_e32 v134, vcc, s8, v132
	s_nop 0
	v_cvt_pk_bf16_f32 v128, v116, v117
	v_cvt_pk_bf16_f32 v129, v118, v119
	v_cvt_pk_bf16_f32 v130, v112, v113
	v_cvt_pk_bf16_f32 v131, v114, v115
	global_store_dwordx4 v[132:133], v[128:131], off offset:256 sc1
	v_addc_co_u32_e32 v135, vcc, 0, v133, vcc
	s_nop 0
	v_cvt_pk_bf16_f32 v128, v108, v109
	v_cvt_pk_bf16_f32 v129, v110, v111
	v_cvt_pk_bf16_f32 v130, v104, v105
	v_cvt_pk_bf16_f32 v131, v106, v107
	global_store_dwordx4 v[134:135], v[128:131], off sc1
	s_mov_b32 s52, 0x10000
	s_mov_b32 s8, 0x40000
	v_cvt_pk_bf16_f32 v128, v96, v97
	v_cvt_pk_bf16_f32 v129, v98, v99
	v_cvt_pk_bf16_f32 v130, v88, v89
	v_cvt_pk_bf16_f32 v131, v90, v91
	global_store_dwordx4 v[134:135], v[128:131], off offset:256 sc1
	v_add_co_u32_e32 v134, vcc, s52, v132
	s_nop 0
	v_cvt_pk_bf16_f32 v128, v100, v101
	v_cvt_pk_bf16_f32 v129, v102, v103
	v_cvt_pk_bf16_f32 v130, v92, v93
	v_cvt_pk_bf16_f32 v131, v94, v95
	v_addc_co_u32_e32 v135, vcc, 0, v133, vcc
	global_store_dwordx4 v[134:135], v[128:131], off sc1
	v_mul_f32_e32 v125, v125, v125
	v_mul_f32_e32 v117, v117, v117
	v_cvt_pk_bf16_f32 v128, v80, v81
	v_cvt_pk_bf16_f32 v129, v82, v83
	v_cvt_pk_bf16_f32 v130, v72, v73
	v_cvt_pk_bf16_f32 v131, v74, v75
	global_store_dwordx4 v[134:135], v[128:131], off offset:256 sc1
	v_add_co_u32_e32 v134, vcc, s73, v132
	s_nop 0
	v_cvt_pk_bf16_f32 v128, v84, v85
	v_cvt_pk_bf16_f32 v129, v86, v87
	v_cvt_pk_bf16_f32 v130, v76, v77
	v_cvt_pk_bf16_f32 v131, v78, v79
	v_addc_co_u32_e32 v135, vcc, 0, v133, vcc
	global_store_dwordx4 v[134:135], v[128:131], off sc1
	v_fmac_f32_e32 v125, v124, v124
	v_mul_f32_e32 v124, v127, v127
	v_cvt_pk_bf16_f32 v128, v68, v69
	v_cvt_pk_bf16_f32 v129, v70, v71
	v_cvt_pk_bf16_f32 v130, v56, v57
	v_cvt_pk_bf16_f32 v131, v58, v59
	global_store_dwordx4 v[134:135], v[128:131], off offset:256 sc1
	v_add_co_u32_e32 v134, vcc, s8, v132
	s_nop 0
	v_cvt_pk_bf16_f32 v128, v44, v45
	v_cvt_pk_bf16_f32 v129, v46, v47
	v_cvt_pk_bf16_f32 v130, v40, v41
	v_cvt_pk_bf16_f32 v131, v42, v43
	v_addc_co_u32_e32 v135, vcc, 0, v133, vcc
	global_store_dwordx4 v[134:135], v[128:131], off sc1
	s_mov_b32 s8, 0x48000
	v_fmac_f32_e32 v117, v116, v116
	v_cvt_pk_bf16_f32 v128, v16, v17
	v_cvt_pk_bf16_f32 v129, v18, v19
	v_cvt_pk_bf16_f32 v130, v8, v9
	v_cvt_pk_bf16_f32 v131, v10, v11
	global_store_dwordx4 v[134:135], v[128:131], off offset:256 sc1
	v_add_co_u32_e32 v134, vcc, s8, v132
	s_nop 0
	v_cvt_pk_bf16_f32 v128, v20, v21
	v_cvt_pk_bf16_f32 v129, v22, v23
	v_cvt_pk_bf16_f32 v130, v12, v13
	v_cvt_pk_bf16_f32 v131, v14, v15
	v_addc_co_u32_e32 v135, vcc, 0, v133, vcc
	global_store_dwordx4 v[134:135], v[128:131], off sc1
	s_mov_b32 s8, 0x50000
	v_mul_f32_e32 v116, v119, v119
	v_cvt_pk_bf16_f32 v128, v60, v61
	v_cvt_pk_bf16_f32 v129, v62, v63
	v_cvt_pk_bf16_f32 v130, v48, v49
	v_cvt_pk_bf16_f32 v131, v50, v51
	global_store_dwordx4 v[134:135], v[128:131], off offset:256 sc1
	v_add_co_u32_e32 v134, vcc, s8, v132
	s_nop 0
	v_cvt_pk_bf16_f32 v128, v64, v65
	v_cvt_pk_bf16_f32 v129, v66, v67
	v_cvt_pk_bf16_f32 v130, v52, v53
	v_cvt_pk_bf16_f32 v131, v54, v55
	v_addc_co_u32_e32 v135, vcc, 0, v133, vcc
	global_store_dwordx4 v[134:135], v[128:131], off sc1
	s_mov_b32 s8, 0x58000
	v_fmac_f32_e32 v124, v126, v126
	v_cvt_pk_bf16_f32 v128, v32, v33
	v_cvt_pk_bf16_f32 v129, v34, v35
	v_cvt_pk_bf16_f32 v130, v24, v25
	v_cvt_pk_bf16_f32 v131, v26, v27
	global_store_dwordx4 v[134:135], v[128:131], off offset:256 sc1
	v_add_co_u32_e32 v134, vcc, s8, v132
	s_nop 0
	v_cvt_pk_bf16_f32 v128, v36, v37
	v_cvt_pk_bf16_f32 v129, v38, v39
	v_cvt_pk_bf16_f32 v130, v28, v29
	v_cvt_pk_bf16_f32 v131, v30, v31
	v_addc_co_u32_e32 v135, vcc, 0, v133, vcc
	v_mul_f32_e32 v121, v121, v121
	v_fmac_f32_e32 v116, v118, v118
	v_mul_f32_e32 v113, v113, v113
	global_store_dwordx4 v[134:135], v[128:131], off sc1
	v_add_f32_e32 v124, v125, v124
	v_fmac_f32_e32 v121, v120, v120
	v_and_b32_e32 v129, 64, v168
	v_add_f32_e32 v116, v117, v116
	v_fmac_f32_e32 v113, v112, v112
	v_xor_b32_e32 v128, 16, v168
	v_add_u32_e32 v129, 64, v129
	v_add_f32_e32 v120, v121, v124
	v_mul_f32_e32 v121, v123, v123
	v_add_f32_e32 v112, v113, v116
	v_mul_f32_e32 v113, v115, v115
	v_cmp_lt_i32_e32 vcc, v128, v129
	v_fmac_f32_e32 v121, v122, v122
	v_fmac_f32_e32 v113, v114, v114
	v_cndmask_b32_e32 v128, v168, v128, vcc
	v_add_f32_e32 v120, v121, v120
	v_add_f32_e32 v112, v113, v112
	v_lshlrev_b32_e32 v128, 2, v128
	v_add_f32_e32 v112, v112, v120
	ds_bpermute_b32 v114, v128, v112
	v_xor_b32_e32 v113, 32, v168
	v_cmp_lt_i32_e32 vcc, v113, v129
	v_readlane_b32 s8, v249, 19
	v_cvt_pk_bf16_f32 v130, v4, v5
	v_cndmask_b32_e32 v113, v168, v113, vcc
	v_lshlrev_b32_e32 v113, 2, v113
	s_waitcnt lgkmcnt(0)
	v_add_f32_e32 v114, v112, v114
	ds_bpermute_b32 v115, v113, v114
	v_cvt_pk_bf16_f32 v131, v6, v7
	v_cvt_pk_bf16_f32 v132, v0, v1
	v_cvt_pk_bf16_f32 v133, v2, v3
	v_cmp_gt_u32_e32 vcc, 16, v138
	v_add_u32_e32 v112, s8, v139
	global_store_dwordx4 v[134:135], v[130:133], off offset:256 sc1
	s_and_saveexec_b64 s[10:11], vcc
	s_mov_b32 s66, 0x20000
	s_movk_i32 s67, 0x2000
	s_mov_b32 s54, 0x12000
	s_mov_b32 s55, 0x14000
	s_mov_b32 s64, 0x16000
	s_movk_i32 s65, 0x4000
	s_movk_i32 s50, 0x6000
	s_mov_b32 s70, 0x1a000
	s_mov_b32 s71, 0xa000
	s_cbranch_execz .LBB0_838
	s_waitcnt lgkmcnt(0)
	v_add_f32_e32 v114, v114, v115
	ds_write_b32 v112, v114
